# on top of v8: short-conv and pooling mixers rewritten by hand: batched/prefetched loads (2 + ~1 exposed round trips instead of ~75), pooling weights staged in LDS by DMA
# speedup vs baseline: 1.0133x; 1.0089x over previous
; #define GAS __attribute__((address_space(1)))
; __device__ __forceinline__ int lane_opaque() { int l; asm volatile("v_mbcnt_lo_u32_b32 %0, -1, 0\n\tv_mbcnt_hi_u32_b32 %0, -1, %0" : "=v"(l)); return l; }
; __device__ __forceinline__ void unpack8(const v4u w, float (&f)[8]) { f[0] = bf_lo(w.x); f[1] = bf_hi(w.x); f[2] = bf_lo(w.y); f[3] = bf_hi(w.y); f[4] = bf_lo(w.z); f[5] = bf_hi(w.z); f[6] = bf_lo(w.w); f[7] = bf_hi(w.w); }
; __device__ __forceinline__ v4u pack8(const float (&f)[8]) { v4u w; w.x = cvt_pk_bf16(f[0], f[1]); w.y = cvt_pk_bf16(f[2], f[3]); w.z = cvt_pk_bf16(f[4], f[5]); w.w = cvt_pk_bf16(f[6], f[7]); return w; }
; __device__ __forceinline__ void mixer_shortconv(const Frame& F, const Args& A, int l, int chunk, const bf16* Z, bf16* MIX) {
;     const int lane = lane_opaque();
;     const int c8 = lane * 8, row0 = chunk * 128, pos0 = (chunk & 31) * 128, t0 = F.wave * 16;
;     const float* cw = A.in[8] + (size_t)l * 3 * GW;
;     float w0[8], w1[8], w2[8];
; #pragma unroll
;     for (int j = 0; j < 8; ++j) { w0[j] = cw[c8 + j]; w1[j] = cw[GW + c8 + j]; w2[j] = cw[2 * GW + c8 + j]; }
;     float xm2[8], xm1[8];
; #pragma unroll
;     for (int j = 0; j < 8; ++j) { xm2[j] = 0.f; xm1[j] = 0.f; }
; #pragma unroll
;     for (int dt = -2; dt < 16; ++dt) {
;         const int t = t0 + dt; const bool valid = (pos0 + t) >= 0;
;         const bf16* zr = Z + (size_t)(row0 + (valid ? t : 0)) * ZC;
;         float xv[8], x[8];
;         unpack8(*(const GAS v4u*)(zr + 1024 + c8), xv);
; #pragma unroll
;         for (int j = 0; j < 8; ++j) x[j] = valid ? xv[j] : 0.f;
;         if (dt >= 0) { float bg[8], o[8]; unpack8(*(const GAS v4u*)(zr + 1536 + c8), bg);
; #pragma unroll
;             for (int j = 0; j < 8; ++j) o[j] = bg[j] * (w0[j] * xm2[j] + w1[j] * xm1[j] + w2[j] * x[j]);
;             *(GAS v4u*)(MIX + (size_t)(row0 + t) * D + 512 + c8) = pack8(o); }
; __global__ void __launch_bounds__(NTHR, 2) trunk_fwd(Args args) {
;     ...
;             for (int chunk_ = bid; chunk_ < (M / 128) * (((PROBE_DUP >> 1) & 1) + 1); chunk_ += P.G) { const int cq = chunk_ & (M / 128 - 1), chunk = (P.G == 256) ? ((cq & 7) * 32 + (cq >> 3)) : cq;
;                 mixer_shortconv(P, args, l, chunk, Z, MIX);
.LBB0_302:
	s_lshl_b32 s4, s26, 5
	s_and_b32 s4, s4, 0xe0
	s_bfe_u32 s5, s26, 0x50003
	s_or_b32 s36, s4, s5
	v_readlane_b32 s4, v253, 24
	s_and_b32 s21, s26, 0xff
	v_readlane_b32 s5, v253, 25
	s_and_b64 s[4:5], s[4:5], exec
	s_cselect_b32 s5, s36, s21
	s_lshl_b32 s21, s5, 7
	s_and_b32 s4, s21, 0xf80
	v_mbcnt_lo_u32_b32 v1, -1, 0
	v_mbcnt_hi_u32_b32 v1, -1, v1
	v_lshlrev_b32_e32 v2, 4, v1
	v_lshlrev_b32_e32 v3, 5, v1
	v_and_b32_e32 v4, 15, v1
	v_lshrrev_b32_e32 v5, 4, v1
	v_readlane_b32 s42, v253, 44
	v_readlane_b32 s43, v253, 45
	v_or_b32_e32 v10, 0, v5
	v_xor_b32_e32 v10, v4, v10
	v_lshlrev_b32_e32 v10, 4, v10
	v_lshl_add_u32 v6, v5, 8, v10
	v_or_b32_e32 v10, 4, v5
	v_xor_b32_e32 v10, v4, v10
	v_lshlrev_b32_e32 v10, 4, v10
	v_lshl_add_u32 v7, v5, 8, v10
	v_or_b32_e32 v10, 8, v5
	v_xor_b32_e32 v10, v4, v10
	v_lshlrev_b32_e32 v10, 4, v10
	v_lshl_add_u32 v8, v5, 8, v10
	v_or_b32_e32 v10, 12, v5
	v_xor_b32_e32 v10, v4, v10
	v_lshlrev_b32_e32 v10, 4, v10
	v_lshl_add_u32 v9, v5, 8, v10
	s_lshl_b32 s36, s56, 10
	s_add_u32 s38, s54, s36
	s_addc_u32 s39, s55, 0
	s_add_i32 m0, s36, 0
	s_nop 0
	global_load_lds_dwordx4 v6, s[38:39]
	s_add_i32 m0, s36, 1024
	s_add_u32 s48, s38, 1024
	s_addc_u32 s49, s39, 0
	global_load_lds_dwordx4 v7, s[48:49]
	s_add_i32 m0, s36, 2048
	s_add_u32 s48, s38, 2048
	s_addc_u32 s49, s39, 0
	global_load_lds_dwordx4 v8, s[48:49]
	s_add_i32 m0, s36, 3072
	s_add_u32 s48, s38, 3072
	s_addc_u32 s49, s39, 0
	global_load_lds_dwordx4 v9, s[48:49]
	s_add_i32 m0, s36, 4096
	s_add_u32 s48, s38, 4096
	s_addc_u32 s49, s39, 0
	global_load_lds_dwordx4 v6, s[48:49]
	s_add_i32 m0, s36, 5120
	s_add_u32 s48, s38, 5120
	s_addc_u32 s49, s39, 0
	global_load_lds_dwordx4 v7, s[48:49]
	s_add_i32 m0, s36, 6144
	s_add_u32 s48, s38, 6144
	s_addc_u32 s49, s39, 0
	global_load_lds_dwordx4 v8, s[48:49]
	s_add_i32 m0, s36, 7168
	s_add_u32 s48, s38, 7168
	s_addc_u32 s49, s39, 0
	global_load_lds_dwordx4 v9, s[48:49]
	s_add_i32 m0, s36, 8192
	s_add_u32 s48, s38, 8192
	s_addc_u32 s49, s39, 0
	global_load_lds_dwordx4 v6, s[48:49]
	s_add_i32 m0, s36, 9216
	s_add_u32 s48, s38, 9216
	s_addc_u32 s49, s39, 0
	global_load_lds_dwordx4 v7, s[48:49]
	s_add_i32 m0, s36, 10240
	s_add_u32 s48, s38, 10240
	s_addc_u32 s49, s39, 0
	global_load_lds_dwordx4 v8, s[48:49]
	s_add_i32 m0, s36, 11264
	s_add_u32 s48, s38, 11264
	s_addc_u32 s49, s39, 0
	global_load_lds_dwordx4 v9, s[48:49]
	s_add_i32 m0, s36, 12288
	s_add_u32 s48, s38, 12288
	s_addc_u32 s49, s39, 0
	global_load_lds_dwordx4 v6, s[48:49]
	s_add_i32 m0, s36, 13312
	s_add_u32 s48, s38, 13312
	s_addc_u32 s49, s39, 0
	global_load_lds_dwordx4 v7, s[48:49]
	s_add_i32 m0, s36, 14336
	s_add_u32 s48, s38, 14336
	s_addc_u32 s49, s39, 0
	global_load_lds_dwordx4 v8, s[48:49]
	s_add_i32 m0, s36, 15360
	s_add_u32 s48, s38, 15360
	s_addc_u32 s49, s39, 0
	global_load_lds_dwordx4 v9, s[48:49]
	s_add_i32 s36, s21, s56
	s_lshl_b32 s84, s36, 12
	s_mov_b32 s85, 0
	s_add_u32 s46, s2, s84
	s_addc_u32 s47, s3, 0
	s_add_i32 s37, s4, s56
	s_cmp_lg_u32 s37, 0
	s_cselect_b64 s[40:41], -1, 0
	s_mul_i32 s37, s36, s33
	s_add_u32 s38, s82, s37
	s_addc_u32 s39, s83, 0
	global_load_dwordx4 v[100:103], v3, s[42:43]
	global_load_dwordx4 v[104:107], v3, s[42:43] offset:16
	global_load_dwordx4 v[108:111], v3, s[42:43] offset:2048
	global_load_dwordx4 v[112:115], v3, s[42:43] offset:2064
	s_add_u32 s48, s42, 0x1000
	s_addc_u32 s49, s43, 0
	global_load_dwordx4 v[116:119], v3, s[48:49]
	global_load_dwordx4 v[120:123], v3, s[48:49] offset:16
	s_sub_u32 s48, s38, 0x3000
	s_subb_u32 s49, s39, 0
	s_and_b64 vcc, s[40:41], exec
	s_cselect_b32 s48, s48, s38
	s_cselect_b32 s49, s49, s39
	global_load_dwordx4 v[12:15], v2, s[48:49] offset:2048
	s_sub_u32 s48, s38, 0x1800
	s_subb_u32 s49, s39, 0
	s_and_b64 vcc, s[40:41], exec
	s_cselect_b32 s48, s48, s38
	s_cselect_b32 s49, s49, s39
	global_load_dwordx4 v[16:19], v2, s[48:49] offset:2048
	s_mov_b64 s[48:49], s[38:39]
	global_load_dwordx4 v[20:23], v2, s[48:49] offset:2048
	global_load_dwordx4 v[52:55], v2, s[48:49] offset:3072
	s_add_u32 s48, s48, 0x1800
	s_addc_u32 s49, s49, 0
	global_load_dwordx4 v[24:27], v2, s[48:49] offset:2048
	global_load_dwordx4 v[56:59], v2, s[48:49] offset:3072
	s_add_u32 s48, s48, 0x1800
	s_addc_u32 s49, s49, 0
	global_load_dwordx4 v[28:31], v2, s[48:49] offset:2048
	global_load_dwordx4 v[60:63], v2, s[48:49] offset:3072
	s_add_u32 s48, s48, 0x1800
	s_addc_u32 s49, s49, 0
	global_load_dwordx4 v[32:35], v2, s[48:49] offset:2048
	global_load_dwordx4 v[64:67], v2, s[48:49] offset:3072
	s_add_u32 s48, s48, 0x1800
	s_addc_u32 s49, s49, 0
	global_load_dwordx4 v[36:39], v2, s[48:49] offset:2048
	global_load_dwordx4 v[68:71], v2, s[48:49] offset:3072
	s_add_u32 s48, s48, 0x1800
	s_addc_u32 s49, s49, 0
	global_load_dwordx4 v[40:43], v2, s[48:49] offset:2048
	global_load_dwordx4 v[72:75], v2, s[48:49] offset:3072
	s_add_u32 s48, s48, 0x1800
	s_addc_u32 s49, s49, 0
	global_load_dwordx4 v[44:47], v2, s[48:49] offset:2048
	global_load_dwordx4 v[76:79], v2, s[48:49] offset:3072
	s_add_u32 s48, s48, 0x1800
	s_addc_u32 s49, s49, 0
	global_load_dwordx4 v[48:51], v2, s[48:49] offset:2048
	global_load_dwordx4 v[80:83], v2, s[48:49] offset:3072
	s_add_u32 s48, s48, 0x1800
	s_addc_u32 s49, s49, 0
	s_waitcnt vmcnt(0)
; #define GAS __attribute__((address_space(1)))
; __device__ __forceinline__ void unpack8(const v4u w, float (&f)[8]) { f[0] = bf_lo(w.x); f[1] = bf_hi(w.x); f[2] = bf_lo(w.y); f[3] = bf_hi(w.y); f[4] = bf_lo(w.z); f[5] = bf_hi(w.z); f[6] = bf_lo(w.w); f[7] = bf_hi(w.w); }
; __device__ __forceinline__ v4u pack8(const float (&f)[8]) { v4u w; w.x = cvt_pk_bf16(f[0], f[1]); w.y = cvt_pk_bf16(f[2], f[3]); w.z = cvt_pk_bf16(f[4], f[5]); w.w = cvt_pk_bf16(f[6], f[7]); return w; }
; __device__ __forceinline__ void mixer_shortconv(const Frame& F, const Args& A, int l, int chunk, const bf16* Z, bf16* MIX) {
;     ...
;     for (int dt = -2; dt < 16; ++dt) {
;         const int t = t0 + dt; const bool valid = (pos0 + t) >= 0;
;         const bf16* zr = Z + (size_t)(row0 + (valid ? t : 0)) * ZC;
;         float xv[8], x[8];
;         unpack8(*(const GAS v4u*)(zr + 1024 + c8), xv);
; #pragma unroll
;         for (int j = 0; j < 8; ++j) x[j] = valid ? xv[j] : 0.f;
;         if (dt >= 0) { float bg[8], o[8]; unpack8(*(const GAS v4u*)(zr + 1536 + c8), bg);
; #pragma unroll
;             for (int j = 0; j < 8; ++j) o[j] = bg[j] * (w0[j] * xm2[j] + w1[j] * xm1[j] + w2[j] * x[j]);
;             *(GAS v4u*)(MIX + (size_t)(row0 + t) * D + 512 + c8) = pack8(o); }
; #pragma unroll
;         for (int j = 0; j < 8; ++j) { xm2[j] = xm1[j]; xm1[j] = x[j]; }
;     }
	v_lshlrev_b32_e32 v84, 16, v12
	v_and_b32_e32 v85, 0xffff0000, v12
	v_lshlrev_b32_e32 v86, 16, v13
	v_and_b32_e32 v87, 0xffff0000, v13
	v_lshlrev_b32_e32 v88, 16, v14
	v_and_b32_e32 v89, 0xffff0000, v14
	v_lshlrev_b32_e32 v90, 16, v15
	v_and_b32_e32 v91, 0xffff0000, v15
	v_cndmask_b32_e64 v84, 0, v84, s[40:41]
	v_cndmask_b32_e64 v85, 0, v85, s[40:41]
	v_cndmask_b32_e64 v86, 0, v86, s[40:41]
	v_cndmask_b32_e64 v87, 0, v87, s[40:41]
	v_cndmask_b32_e64 v88, 0, v88, s[40:41]
	v_cndmask_b32_e64 v89, 0, v89, s[40:41]
	v_cndmask_b32_e64 v90, 0, v90, s[40:41]
	v_cndmask_b32_e64 v91, 0, v91, s[40:41]
	v_lshlrev_b32_e32 v92, 16, v16
	v_and_b32_e32 v93, 0xffff0000, v16
	v_lshlrev_b32_e32 v94, 16, v17
	v_and_b32_e32 v95, 0xffff0000, v17
	v_lshlrev_b32_e32 v96, 16, v18
	v_and_b32_e32 v97, 0xffff0000, v18
	v_lshlrev_b32_e32 v98, 16, v19
	v_and_b32_e32 v99, 0xffff0000, v19
	v_cndmask_b32_e64 v92, 0, v92, s[40:41]
	v_cndmask_b32_e64 v93, 0, v93, s[40:41]
	v_cndmask_b32_e64 v94, 0, v94, s[40:41]
	v_cndmask_b32_e64 v95, 0, v95, s[40:41]
	v_cndmask_b32_e64 v96, 0, v96, s[40:41]
	v_cndmask_b32_e64 v97, 0, v97, s[40:41]
	v_cndmask_b32_e64 v98, 0, v98, s[40:41]
	v_cndmask_b32_e64 v99, 0, v99, s[40:41]
	v_lshlrev_b32_e32 v124, 16, v20
	v_and_b32_e32 v125, 0xffff0000, v20
	v_lshlrev_b32_e32 v126, 16, v21
	v_and_b32_e32 v127, 0xffff0000, v21
	v_lshlrev_b32_e32 v128, 16, v22
	v_and_b32_e32 v129, 0xffff0000, v22
	v_lshlrev_b32_e32 v130, 16, v23
	v_and_b32_e32 v131, 0xffff0000, v23
	v_lshlrev_b32_e32 v132, 16, v52
	v_and_b32_e32 v133, 0xffff0000, v52
	v_lshlrev_b32_e32 v134, 16, v53
	v_and_b32_e32 v135, 0xffff0000, v53
	v_lshlrev_b32_e32 v136, 16, v54
	v_and_b32_e32 v137, 0xffff0000, v54
	v_lshlrev_b32_e32 v138, 16, v55
	v_and_b32_e32 v139, 0xffff0000, v55
	v_mul_f32_e32 v140, v100, v84
	v_fmac_f32_e32 v140, v108, v92
	v_fmac_f32_e32 v140, v116, v124
	v_mul_f32_e32 v140, v132, v140
	v_mul_f32_e32 v141, v101, v85
	v_fmac_f32_e32 v141, v109, v93
	v_fmac_f32_e32 v141, v117, v125
	v_mul_f32_e32 v141, v133, v141
	v_mul_f32_e32 v142, v102, v86
	v_fmac_f32_e32 v142, v110, v94
	v_fmac_f32_e32 v142, v118, v126
	v_mul_f32_e32 v142, v134, v142
	v_mul_f32_e32 v143, v103, v87
	v_fmac_f32_e32 v143, v111, v95
	v_fmac_f32_e32 v143, v119, v127
	v_mul_f32_e32 v143, v135, v143
	v_mul_f32_e32 v144, v104, v88
	v_fmac_f32_e32 v144, v112, v96
	v_fmac_f32_e32 v144, v120, v128
	v_mul_f32_e32 v144, v136, v144
	v_mul_f32_e32 v145, v105, v89
	v_fmac_f32_e32 v145, v113, v97
	v_fmac_f32_e32 v145, v121, v129
	v_mul_f32_e32 v145, v137, v145
	v_mul_f32_e32 v146, v106, v90
	v_fmac_f32_e32 v146, v114, v98
	v_fmac_f32_e32 v146, v122, v130
	v_mul_f32_e32 v146, v138, v146
	v_mul_f32_e32 v147, v107, v91
	v_fmac_f32_e32 v147, v115, v99
	v_fmac_f32_e32 v147, v123, v131
	v_mul_f32_e32 v147, v139, v147
	v_cvt_pk_bf16_f32 v140, v140, v141
	v_cvt_pk_bf16_f32 v141, v142, v143
	v_cvt_pk_bf16_f32 v142, v144, v145
	v_cvt_pk_bf16_f32 v143, v146, v147
	global_store_dwordx4 v2, v[140:143], s[46:47] offset:1024
	s_add_u32 s46, s46, 0x1000
	s_addc_u32 s47, s47, 0
	global_load_dwordx4 v[20:23], v2, s[48:49] offset:2048
	global_load_dwordx4 v[52:55], v2, s[48:49] offset:3072
	s_add_u32 s48, s48, 0x1800
	s_addc_u32 s49, s49, 0
	v_lshlrev_b32_e32 v84, 16, v24
	v_and_b32_e32 v85, 0xffff0000, v24
	v_lshlrev_b32_e32 v86, 16, v25
	v_and_b32_e32 v87, 0xffff0000, v25
	v_lshlrev_b32_e32 v88, 16, v26
	v_and_b32_e32 v89, 0xffff0000, v26
	v_lshlrev_b32_e32 v90, 16, v27
	v_and_b32_e32 v91, 0xffff0000, v27
	v_lshlrev_b32_e32 v132, 16, v56
	v_and_b32_e32 v133, 0xffff0000, v56
	v_lshlrev_b32_e32 v134, 16, v57
	v_and_b32_e32 v135, 0xffff0000, v57
	v_lshlrev_b32_e32 v136, 16, v58
	v_and_b32_e32 v137, 0xffff0000, v58
	v_lshlrev_b32_e32 v138, 16, v59
	v_and_b32_e32 v139, 0xffff0000, v59
	v_mul_f32_e32 v140, v100, v92
	v_fmac_f32_e32 v140, v108, v124
	v_fmac_f32_e32 v140, v116, v84
	v_mul_f32_e32 v140, v132, v140
	v_mul_f32_e32 v141, v101, v93
	v_fmac_f32_e32 v141, v109, v125
	v_fmac_f32_e32 v141, v117, v85
	v_mul_f32_e32 v141, v133, v141
	v_mul_f32_e32 v142, v102, v94
	v_fmac_f32_e32 v142, v110, v126
	v_fmac_f32_e32 v142, v118, v86
	v_mul_f32_e32 v142, v134, v142
	v_mul_f32_e32 v143, v103, v95
	v_fmac_f32_e32 v143, v111, v127
	v_fmac_f32_e32 v143, v119, v87
	v_mul_f32_e32 v143, v135, v143
	v_mul_f32_e32 v144, v104, v96
	v_fmac_f32_e32 v144, v112, v128
	v_fmac_f32_e32 v144, v120, v88
	v_mul_f32_e32 v144, v136, v144
	v_mul_f32_e32 v145, v105, v97
	v_fmac_f32_e32 v145, v113, v129
	v_fmac_f32_e32 v145, v121, v89
	v_mul_f32_e32 v145, v137, v145
	v_mul_f32_e32 v146, v106, v98
	v_fmac_f32_e32 v146, v114, v130
	v_fmac_f32_e32 v146, v122, v90
	v_mul_f32_e32 v146, v138, v146
	v_mul_f32_e32 v147, v107, v99
	v_fmac_f32_e32 v147, v115, v131
	v_fmac_f32_e32 v147, v123, v91
	v_mul_f32_e32 v147, v139, v147
	v_cvt_pk_bf16_f32 v140, v140, v141
	v_cvt_pk_bf16_f32 v141, v142, v143
	v_cvt_pk_bf16_f32 v142, v144, v145
	v_cvt_pk_bf16_f32 v143, v146, v147
	global_store_dwordx4 v2, v[140:143], s[46:47] offset:1024
	s_add_u32 s46, s46, 0x1000
	s_addc_u32 s47, s47, 0
	global_load_dwordx4 v[24:27], v2, s[48:49] offset:2048
	global_load_dwordx4 v[56:59], v2, s[48:49] offset:3072
	s_add_u32 s48, s48, 0x1800
	s_addc_u32 s49, s49, 0
	v_lshlrev_b32_e32 v92, 16, v28
	v_and_b32_e32 v93, 0xffff0000, v28
	v_lshlrev_b32_e32 v94, 16, v29
	v_and_b32_e32 v95, 0xffff0000, v29
	v_lshlrev_b32_e32 v96, 16, v30
	v_and_b32_e32 v97, 0xffff0000, v30
	v_lshlrev_b32_e32 v98, 16, v31
	v_and_b32_e32 v99, 0xffff0000, v31
	v_lshlrev_b32_e32 v132, 16, v60
	v_and_b32_e32 v133, 0xffff0000, v60
	v_lshlrev_b32_e32 v134, 16, v61
	v_and_b32_e32 v135, 0xffff0000, v61
	v_lshlrev_b32_e32 v136, 16, v62
; #define GAS __attribute__((address_space(1)))
; __device__ __forceinline__ void unpack8(const v4u w, float (&f)[8]) { f[0] = bf_lo(w.x); f[1] = bf_hi(w.x); f[2] = bf_lo(w.y); f[3] = bf_hi(w.y); f[4] = bf_lo(w.z); f[5] = bf_hi(w.z); f[6] = bf_lo(w.w); f[7] = bf_hi(w.w); }
; __device__ __forceinline__ v4u pack8(const float (&f)[8]) { v4u w; w.x = cvt_pk_bf16(f[0], f[1]); w.y = cvt_pk_bf16(f[2], f[3]); w.z = cvt_pk_bf16(f[4], f[5]); w.w = cvt_pk_bf16(f[6], f[7]); return w; }
; __device__ __forceinline__ void mixer_shortconv(const Frame& F, const Args& A, int l, int chunk, const bf16* Z, bf16* MIX) {
;     ...
;     for (int dt = -2; dt < 16; ++dt) {
;         const int t = t0 + dt; const bool valid = (pos0 + t) >= 0;
;         const bf16* zr = Z + (size_t)(row0 + (valid ? t : 0)) * ZC;
;         float xv[8], x[8];
;         unpack8(*(const GAS v4u*)(zr + 1024 + c8), xv);
; #pragma unroll
;         for (int j = 0; j < 8; ++j) x[j] = valid ? xv[j] : 0.f;
;         if (dt >= 0) { float bg[8], o[8]; unpack8(*(const GAS v4u*)(zr + 1536 + c8), bg);
; #pragma unroll
;             for (int j = 0; j < 8; ++j) o[j] = bg[j] * (w0[j] * xm2[j] + w1[j] * xm1[j] + w2[j] * x[j]);
;             *(GAS v4u*)(MIX + (size_t)(row0 + t) * D + 512 + c8) = pack8(o); }
; #pragma unroll
;         for (int j = 0; j < 8; ++j) { xm2[j] = xm1[j]; xm1[j] = x[j]; }
;     }
	v_and_b32_e32 v137, 0xffff0000, v62
	v_lshlrev_b32_e32 v138, 16, v63
	v_and_b32_e32 v139, 0xffff0000, v63
	v_mul_f32_e32 v140, v100, v124
	v_fmac_f32_e32 v140, v108, v84
	v_fmac_f32_e32 v140, v116, v92
	v_mul_f32_e32 v140, v132, v140
	v_mul_f32_e32 v141, v101, v125
	v_fmac_f32_e32 v141, v109, v85
	v_fmac_f32_e32 v141, v117, v93
	v_mul_f32_e32 v141, v133, v141
	v_mul_f32_e32 v142, v102, v126
	v_fmac_f32_e32 v142, v110, v86
	v_fmac_f32_e32 v142, v118, v94
	v_mul_f32_e32 v142, v134, v142
	v_mul_f32_e32 v143, v103, v127
	v_fmac_f32_e32 v143, v111, v87
	v_fmac_f32_e32 v143, v119, v95
	v_mul_f32_e32 v143, v135, v143
	v_mul_f32_e32 v144, v104, v128
	v_fmac_f32_e32 v144, v112, v88
	v_fmac_f32_e32 v144, v120, v96
	v_mul_f32_e32 v144, v136, v144
	v_mul_f32_e32 v145, v105, v129
	v_fmac_f32_e32 v145, v113, v89
	v_fmac_f32_e32 v145, v121, v97
	v_mul_f32_e32 v145, v137, v145
	v_mul_f32_e32 v146, v106, v130
	v_fmac_f32_e32 v146, v114, v90
	v_fmac_f32_e32 v146, v122, v98
	v_mul_f32_e32 v146, v138, v146
	v_mul_f32_e32 v147, v107, v131
	v_fmac_f32_e32 v147, v115, v91
	v_fmac_f32_e32 v147, v123, v99
	v_mul_f32_e32 v147, v139, v147
	v_cvt_pk_bf16_f32 v140, v140, v141
	v_cvt_pk_bf16_f32 v141, v142, v143
	v_cvt_pk_bf16_f32 v142, v144, v145
	v_cvt_pk_bf16_f32 v143, v146, v147
	global_store_dwordx4 v2, v[140:143], s[46:47] offset:1024
	s_add_u32 s46, s46, 0x1000
	s_addc_u32 s47, s47, 0
	global_load_dwordx4 v[28:31], v2, s[48:49] offset:2048
	global_load_dwordx4 v[60:63], v2, s[48:49] offset:3072
	s_add_u32 s48, s48, 0x1800
	s_addc_u32 s49, s49, 0
	v_lshlrev_b32_e32 v124, 16, v32
	v_and_b32_e32 v125, 0xffff0000, v32
	v_lshlrev_b32_e32 v126, 16, v33
	v_and_b32_e32 v127, 0xffff0000, v33
	v_lshlrev_b32_e32 v128, 16, v34
	v_and_b32_e32 v129, 0xffff0000, v34
	v_lshlrev_b32_e32 v130, 16, v35
	v_and_b32_e32 v131, 0xffff0000, v35
	v_lshlrev_b32_e32 v132, 16, v64
	v_and_b32_e32 v133, 0xffff0000, v64
	v_lshlrev_b32_e32 v134, 16, v65
	v_and_b32_e32 v135, 0xffff0000, v65
	v_lshlrev_b32_e32 v136, 16, v66
	v_and_b32_e32 v137, 0xffff0000, v66
	v_lshlrev_b32_e32 v138, 16, v67
	v_and_b32_e32 v139, 0xffff0000, v67
	v_mul_f32_e32 v140, v100, v84
	v_fmac_f32_e32 v140, v108, v92
	v_fmac_f32_e32 v140, v116, v124
	v_mul_f32_e32 v140, v132, v140
	v_mul_f32_e32 v141, v101, v85
	v_fmac_f32_e32 v141, v109, v93
	v_fmac_f32_e32 v141, v117, v125
	v_mul_f32_e32 v141, v133, v141
	v_mul_f32_e32 v142, v102, v86
	v_fmac_f32_e32 v142, v110, v94
	v_fmac_f32_e32 v142, v118, v126
	v_mul_f32_e32 v142, v134, v142
	v_mul_f32_e32 v143, v103, v87
	v_fmac_f32_e32 v143, v111, v95
	v_fmac_f32_e32 v143, v119, v127
	v_mul_f32_e32 v143, v135, v143
	v_mul_f32_e32 v144, v104, v88
	v_fmac_f32_e32 v144, v112, v96
	v_fmac_f32_e32 v144, v120, v128
	v_mul_f32_e32 v144, v136, v144
	v_mul_f32_e32 v145, v105, v89
	v_fmac_f32_e32 v145, v113, v97
	v_fmac_f32_e32 v145, v121, v129
	v_mul_f32_e32 v145, v137, v145
	v_mul_f32_e32 v146, v106, v90
	v_fmac_f32_e32 v146, v114, v98
	v_fmac_f32_e32 v146, v122, v130
	v_mul_f32_e32 v146, v138, v146
	v_mul_f32_e32 v147, v107, v91
	v_fmac_f32_e32 v147, v115, v99
	v_fmac_f32_e32 v147, v123, v131
	v_mul_f32_e32 v147, v139, v147
	v_cvt_pk_bf16_f32 v140, v140, v141
	v_cvt_pk_bf16_f32 v141, v142, v143
	v_cvt_pk_bf16_f32 v142, v144, v145
	v_cvt_pk_bf16_f32 v143, v146, v147
	global_store_dwordx4 v2, v[140:143], s[46:47] offset:1024
	s_add_u32 s46, s46, 0x1000
	s_addc_u32 s47, s47, 0
	global_load_dwordx4 v[32:35], v2, s[48:49] offset:2048
	global_load_dwordx4 v[64:67], v2, s[48:49] offset:3072
	s_add_u32 s48, s48, 0x1800
	s_addc_u32 s49, s49, 0
	v_lshlrev_b32_e32 v84, 16, v36
	v_and_b32_e32 v85, 0xffff0000, v36
	v_lshlrev_b32_e32 v86, 16, v37
	v_and_b32_e32 v87, 0xffff0000, v37
	v_lshlrev_b32_e32 v88, 16, v38
	v_and_b32_e32 v89, 0xffff0000, v38
	v_lshlrev_b32_e32 v90, 16, v39
	v_and_b32_e32 v91, 0xffff0000, v39
	v_lshlrev_b32_e32 v132, 16, v68
	v_and_b32_e32 v133, 0xffff0000, v68
	v_lshlrev_b32_e32 v134, 16, v69
	v_and_b32_e32 v135, 0xffff0000, v69
	v_lshlrev_b32_e32 v136, 16, v70
	v_and_b32_e32 v137, 0xffff0000, v70
	v_lshlrev_b32_e32 v138, 16, v71
	v_and_b32_e32 v139, 0xffff0000, v71
	v_mul_f32_e32 v140, v100, v92
	v_fmac_f32_e32 v140, v108, v124
	v_fmac_f32_e32 v140, v116, v84
	v_mul_f32_e32 v140, v132, v140
	v_mul_f32_e32 v141, v101, v93
	v_fmac_f32_e32 v141, v109, v125
	v_fmac_f32_e32 v141, v117, v85
	v_mul_f32_e32 v141, v133, v141
	v_mul_f32_e32 v142, v102, v94
	v_fmac_f32_e32 v142, v110, v126
	v_fmac_f32_e32 v142, v118, v86
	v_mul_f32_e32 v142, v134, v142
	v_mul_f32_e32 v143, v103, v95
	v_fmac_f32_e32 v143, v111, v127
	v_fmac_f32_e32 v143, v119, v87
	v_mul_f32_e32 v143, v135, v143
	v_mul_f32_e32 v144, v104, v96
	v_fmac_f32_e32 v144, v112, v128
	v_fmac_f32_e32 v144, v120, v88
	v_mul_f32_e32 v144, v136, v144
	v_mul_f32_e32 v145, v105, v97
	v_fmac_f32_e32 v145, v113, v129
	v_fmac_f32_e32 v145, v121, v89
	v_mul_f32_e32 v145, v137, v145
	v_mul_f32_e32 v146, v106, v98
	v_fmac_f32_e32 v146, v114, v130
	v_fmac_f32_e32 v146, v122, v90
	v_mul_f32_e32 v146, v138, v146
	v_mul_f32_e32 v147, v107, v99
	v_fmac_f32_e32 v147, v115, v131
	v_fmac_f32_e32 v147, v123, v91
	v_mul_f32_e32 v147, v139, v147
	v_cvt_pk_bf16_f32 v140, v140, v141
	v_cvt_pk_bf16_f32 v141, v142, v143
	v_cvt_pk_bf16_f32 v142, v144, v145
	v_cvt_pk_bf16_f32 v143, v146, v147
	global_store_dwordx4 v2, v[140:143], s[46:47] offset:1024
	s_add_u32 s46, s46, 0x1000
	s_addc_u32 s47, s47, 0
	global_load_dwordx4 v[36:39], v2, s[48:49] offset:2048
	global_load_dwordx4 v[68:71], v2, s[48:49] offset:3072
	s_add_u32 s48, s48, 0x1800
	s_addc_u32 s49, s49, 0
	v_lshlrev_b32_e32 v92, 16, v40
	v_and_b32_e32 v93, 0xffff0000, v40
	v_lshlrev_b32_e32 v94, 16, v41
; #define GAS __attribute__((address_space(1)))
; __device__ __forceinline__ int lane_opaque() { int l; asm volatile("v_mbcnt_lo_u32_b32 %0, -1, 0\n\tv_mbcnt_hi_u32_b32 %0, -1, %0" : "=v"(l)); return l; }
; __device__ __forceinline__ void unpack8(const v4u w, float (&f)[8]) { f[0] = bf_lo(w.x); f[1] = bf_hi(w.x); f[2] = bf_lo(w.y); f[3] = bf_hi(w.y); f[4] = bf_lo(w.z); f[5] = bf_hi(w.z); f[6] = bf_lo(w.w); f[7] = bf_hi(w.w); }
; __device__ __forceinline__ v4u pack8(const float (&f)[8]) { v4u w; w.x = cvt_pk_bf16(f[0], f[1]); w.y = cvt_pk_bf16(f[2], f[3]); w.z = cvt_pk_bf16(f[4], f[5]); w.w = cvt_pk_bf16(f[6], f[7]); return w; }
; __device__ __forceinline__ void mixer_shortconv(const Frame& F, const Args& A, int l, int chunk, const bf16* Z, bf16* MIX) {
;     ...
;     for (int dt = -2; dt < 16; ++dt) {
;         const int t = t0 + dt; const bool valid = (pos0 + t) >= 0;
;         const bf16* zr = Z + (size_t)(row0 + (valid ? t : 0)) * ZC;
;         float xv[8], x[8];
;         unpack8(*(const GAS v4u*)(zr + 1024 + c8), xv);
; #pragma unroll
;         for (int j = 0; j < 8; ++j) x[j] = valid ? xv[j] : 0.f;
;         if (dt >= 0) { float bg[8], o[8]; unpack8(*(const GAS v4u*)(zr + 1536 + c8), bg);
; #pragma unroll
;             for (int j = 0; j < 8; ++j) o[j] = bg[j] * (w0[j] * xm2[j] + w1[j] * xm1[j] + w2[j] * x[j]);
;             *(GAS v4u*)(MIX + (size_t)(row0 + t) * D + 512 + c8) = pack8(o); }
; #pragma unroll
;         for (int j = 0; j < 8; ++j) { xm2[j] = xm1[j]; xm1[j] = x[j]; }
;     }
; __device__ __forceinline__ void mixer_pool(const Frame& F, int l, int chunk, const bf16* Z, bf16* MIX) {
;     const int lane = lane_opaque();
;     const int i = lane & 15, g4 = lane >> 4, t = F.wave * 16 + i, row = chunk * 128 + t, pos = (chunk & 31) * 128 + t;
;     const bool prev_ok = ((chunk & 31) * 128 + F.wave * 16) > 0;
;     const bf16* pwt = (const bf16*)(F.ws + WS_PWT) + (size_t)l * 4 * 128 * 128 + (size_t)i * 128 + 8 * g4;
;     const bf16* zrow = Z + (size_t)row * ZC + 2560 + 8 * g4; bf16* orow = MIX + (size_t)row * D + 1536 + 4 * g4;
	v_and_b32_e32 v95, 0xffff0000, v41
	v_lshlrev_b32_e32 v96, 16, v42
	v_and_b32_e32 v97, 0xffff0000, v42
	v_lshlrev_b32_e32 v98, 16, v43
	v_and_b32_e32 v99, 0xffff0000, v43
	v_lshlrev_b32_e32 v132, 16, v72
	v_and_b32_e32 v133, 0xffff0000, v72
	v_lshlrev_b32_e32 v134, 16, v73
	v_and_b32_e32 v135, 0xffff0000, v73
	v_lshlrev_b32_e32 v136, 16, v74
	v_and_b32_e32 v137, 0xffff0000, v74
	v_lshlrev_b32_e32 v138, 16, v75
	v_and_b32_e32 v139, 0xffff0000, v75
	v_mul_f32_e32 v140, v100, v124
	v_fmac_f32_e32 v140, v108, v84
	v_fmac_f32_e32 v140, v116, v92
	v_mul_f32_e32 v140, v132, v140
	v_mul_f32_e32 v141, v101, v125
	v_fmac_f32_e32 v141, v109, v85
	v_fmac_f32_e32 v141, v117, v93
	v_mul_f32_e32 v141, v133, v141
	v_mul_f32_e32 v142, v102, v126
	v_fmac_f32_e32 v142, v110, v86
	v_fmac_f32_e32 v142, v118, v94
	v_mul_f32_e32 v142, v134, v142
	v_mul_f32_e32 v143, v103, v127
	v_fmac_f32_e32 v143, v111, v87
	v_fmac_f32_e32 v143, v119, v95
	v_mul_f32_e32 v143, v135, v143
	v_mul_f32_e32 v144, v104, v128
	v_fmac_f32_e32 v144, v112, v88
	v_fmac_f32_e32 v144, v120, v96
	v_mul_f32_e32 v144, v136, v144
	v_mul_f32_e32 v145, v105, v129
	v_fmac_f32_e32 v145, v113, v89
	v_fmac_f32_e32 v145, v121, v97
	v_mul_f32_e32 v145, v137, v145
	v_mul_f32_e32 v146, v106, v130
	v_fmac_f32_e32 v146, v114, v90
	v_fmac_f32_e32 v146, v122, v98
	v_mul_f32_e32 v146, v138, v146
	v_mul_f32_e32 v147, v107, v131
	v_fmac_f32_e32 v147, v115, v91
	v_fmac_f32_e32 v147, v123, v99
	v_mul_f32_e32 v147, v139, v147
	v_cvt_pk_bf16_f32 v140, v140, v141
	v_cvt_pk_bf16_f32 v141, v142, v143
	v_cvt_pk_bf16_f32 v142, v144, v145
	v_cvt_pk_bf16_f32 v143, v146, v147
	global_store_dwordx4 v2, v[140:143], s[46:47] offset:1024
	s_add_u32 s46, s46, 0x1000
	s_addc_u32 s47, s47, 0
	global_load_dwordx4 v[40:43], v2, s[48:49] offset:2048
	global_load_dwordx4 v[72:75], v2, s[48:49] offset:3072
	s_add_u32 s48, s48, 0x1800
	s_addc_u32 s49, s49, 0
	v_lshlrev_b32_e32 v124, 16, v44
	v_and_b32_e32 v125, 0xffff0000, v44
	v_lshlrev_b32_e32 v126, 16, v45
	v_and_b32_e32 v127, 0xffff0000, v45
	v_lshlrev_b32_e32 v128, 16, v46
	v_and_b32_e32 v129, 0xffff0000, v46
	v_lshlrev_b32_e32 v130, 16, v47
	v_and_b32_e32 v131, 0xffff0000, v47
	v_lshlrev_b32_e32 v132, 16, v76
	v_and_b32_e32 v133, 0xffff0000, v76
	v_lshlrev_b32_e32 v134, 16, v77
	v_and_b32_e32 v135, 0xffff0000, v77
	v_lshlrev_b32_e32 v136, 16, v78
	v_and_b32_e32 v137, 0xffff0000, v78
	v_lshlrev_b32_e32 v138, 16, v79
	v_and_b32_e32 v139, 0xffff0000, v79
	v_mul_f32_e32 v140, v100, v84
	v_fmac_f32_e32 v140, v108, v92
	v_fmac_f32_e32 v140, v116, v124
	v_mul_f32_e32 v140, v132, v140
	v_mul_f32_e32 v141, v101, v85
	v_fmac_f32_e32 v141, v109, v93
	v_fmac_f32_e32 v141, v117, v125
	v_mul_f32_e32 v141, v133, v141
	v_mul_f32_e32 v142, v102, v86
	v_fmac_f32_e32 v142, v110, v94
	v_fmac_f32_e32 v142, v118, v126
	v_mul_f32_e32 v142, v134, v142
	v_mul_f32_e32 v143, v103, v87
	v_fmac_f32_e32 v143, v111, v95
	v_fmac_f32_e32 v143, v119, v127
	v_mul_f32_e32 v143, v135, v143
	v_mul_f32_e32 v144, v104, v88
	v_fmac_f32_e32 v144, v112, v96
	v_fmac_f32_e32 v144, v120, v128
	v_mul_f32_e32 v144, v136, v144
	v_mul_f32_e32 v145, v105, v89
	v_fmac_f32_e32 v145, v113, v97
	v_fmac_f32_e32 v145, v121, v129
	v_mul_f32_e32 v145, v137, v145
	v_mul_f32_e32 v146, v106, v90
	v_fmac_f32_e32 v146, v114, v98
	v_fmac_f32_e32 v146, v122, v130
	v_mul_f32_e32 v146, v138, v146
	v_mul_f32_e32 v147, v107, v91
	v_fmac_f32_e32 v147, v115, v99
	v_fmac_f32_e32 v147, v123, v131
	v_mul_f32_e32 v147, v139, v147
	v_cvt_pk_bf16_f32 v140, v140, v141
	v_cvt_pk_bf16_f32 v141, v142, v143
	v_cvt_pk_bf16_f32 v142, v144, v145
	v_cvt_pk_bf16_f32 v143, v146, v147
	global_store_dwordx4 v2, v[140:143], s[46:47] offset:1024
	s_add_u32 s46, s46, 0x1000
	s_addc_u32 s47, s47, 0
	global_load_dwordx4 v[44:47], v2, s[48:49] offset:2048
	global_load_dwordx4 v[76:79], v2, s[48:49] offset:3072
	s_add_u32 s48, s48, 0x1800
	s_addc_u32 s49, s49, 0
	v_lshlrev_b32_e32 v84, 16, v48
	v_and_b32_e32 v85, 0xffff0000, v48
	v_lshlrev_b32_e32 v86, 16, v49
	v_and_b32_e32 v87, 0xffff0000, v49
	v_lshlrev_b32_e32 v88, 16, v50
	v_and_b32_e32 v89, 0xffff0000, v50
	v_lshlrev_b32_e32 v90, 16, v51
	v_and_b32_e32 v91, 0xffff0000, v51
	v_lshlrev_b32_e32 v132, 16, v80
	v_and_b32_e32 v133, 0xffff0000, v80
	v_lshlrev_b32_e32 v134, 16, v81
	v_and_b32_e32 v135, 0xffff0000, v81
	v_lshlrev_b32_e32 v136, 16, v82
	v_and_b32_e32 v137, 0xffff0000, v82
	v_lshlrev_b32_e32 v138, 16, v83
	v_and_b32_e32 v139, 0xffff0000, v83
	v_mul_f32_e32 v140, v100, v92
	v_fmac_f32_e32 v140, v108, v124
	v_fmac_f32_e32 v140, v116, v84
	v_mul_f32_e32 v140, v132, v140
	v_mul_f32_e32 v141, v101, v93
	v_fmac_f32_e32 v141, v109, v125
	v_fmac_f32_e32 v141, v117, v85
	v_mul_f32_e32 v141, v133, v141
	v_mul_f32_e32 v142, v102, v94
	v_fmac_f32_e32 v142, v110, v126
	v_fmac_f32_e32 v142, v118, v86
	v_mul_f32_e32 v142, v134, v142
	v_mul_f32_e32 v143, v103, v95
	v_fmac_f32_e32 v143, v111, v127
	v_fmac_f32_e32 v143, v119, v87
	v_mul_f32_e32 v143, v135, v143
	v_mul_f32_e32 v144, v104, v96
	v_fmac_f32_e32 v144, v112, v128
	v_fmac_f32_e32 v144, v120, v88
	v_mul_f32_e32 v144, v136, v144
	v_mul_f32_e32 v145, v105, v97
	v_fmac_f32_e32 v145, v113, v129
	v_fmac_f32_e32 v145, v121, v89
	v_mul_f32_e32 v145, v137, v145
	v_mul_f32_e32 v146, v106, v98
	v_fmac_f32_e32 v146, v114, v130
	v_fmac_f32_e32 v146, v122, v90
	v_mul_f32_e32 v146, v138, v146
	v_mul_f32_e32 v147, v107, v99
	v_fmac_f32_e32 v147, v115, v131
	v_fmac_f32_e32 v147, v123, v91
	v_mul_f32_e32 v147, v139, v147
	v_cvt_pk_bf16_f32 v140, v140, v141
	v_cvt_pk_bf16_f32 v141, v142, v143
	v_cvt_pk_bf16_f32 v142, v144, v145
	v_cvt_pk_bf16_f32 v143, v146, v147
	global_store_dwordx4 v2, v[140:143], s[46:47] offset:1024
	s_add_u32 s46, s46, 0x1000
	s_addc_u32 s47, s47, 0
	global_load_dwordx4 v[48:51], v2, s[48:49] offset:2048
	global_load_dwordx4 v[80:83], v2, s[48:49] offset:3072
	s_add_u32 s48, s48, 0x1800
	s_addc_u32 s49, s49, 0
	v_mul_u32_u24_e32 v11, 0x1800, v4
	v_lshl_add_u32 v11, v5, 4, v11
	s_add_u32 s38, s38, 0x1400
	s_addc_u32 s39, s39, 0
	s_sub_u32 s48, s38, 0x18000
	s_subb_u32 s49, s39, 0
	s_and_b64 vcc, s[40:41], exec
	s_cselect_b32 s48, s48, s38
	s_cselect_b32 s49, s49, s39
	s_waitcnt vmcnt(21)
; #define GAS __attribute__((address_space(1)))
; __device__ __forceinline__ void unpack8(const v4u w, float (&f)[8]) { f[0] = bf_lo(w.x); f[1] = bf_hi(w.x); f[2] = bf_lo(w.y); f[3] = bf_hi(w.y); f[4] = bf_lo(w.z); f[5] = bf_hi(w.z); f[6] = bf_lo(w.w); f[7] = bf_hi(w.w); }
; __device__ __forceinline__ v4u pack8(const float (&f)[8]) { v4u w; w.x = cvt_pk_bf16(f[0], f[1]); w.y = cvt_pk_bf16(f[2], f[3]); w.z = cvt_pk_bf16(f[4], f[5]); w.w = cvt_pk_bf16(f[6], f[7]); return w; }
; __device__ __forceinline__ void mixer_shortconv(const Frame& F, const Args& A, int l, int chunk, const bf16* Z, bf16* MIX) {
;     ...
;     for (int dt = -2; dt < 16; ++dt) {
;         const int t = t0 + dt; const bool valid = (pos0 + t) >= 0;
;         const bf16* zr = Z + (size_t)(row0 + (valid ? t : 0)) * ZC;
;         float xv[8], x[8];
;         unpack8(*(const GAS v4u*)(zr + 1024 + c8), xv);
; #pragma unroll
;         for (int j = 0; j < 8; ++j) x[j] = valid ? xv[j] : 0.f;
;         if (dt >= 0) { float bg[8], o[8]; unpack8(*(const GAS v4u*)(zr + 1536 + c8), bg);
; #pragma unroll
;             for (int j = 0; j < 8; ++j) o[j] = bg[j] * (w0[j] * xm2[j] + w1[j] * xm1[j] + w2[j] * x[j]);
;             *(GAS v4u*)(MIX + (size_t)(row0 + t) * D + 512 + c8) = pack8(o); }
; #pragma unroll
;         for (int j = 0; j < 8; ++j) { xm2[j] = xm1[j]; xm1[j] = x[j]; }
;     }
; template <int W> __device__ __forceinline__ void pool_group(const bf16* zrow  , const bf16* pw  , bf16* orow  , int pos, bool prev_ok) {
;     const float inv = 1.0f / (float)((pos + 1) < W ? (pos + 1) : W);
;     f32x4 acc[8];
; #pragma unroll
;     for (int dt = 0; dt < 8; ++dt) acc[dt] = (f32x4){0.f, 0.f, 0.f, 0.f};
;     v4u cw[4], pv[4], aw[2][8];
; #pragma unroll
;     for (int kk = 0; kk < 4; ++kk) { cw[kk] = *(const GAS v4u*)(zrow + 32 * kk); pv[kk] = prev_ok ? *(const GAS v4u*)(zrow + 32 * kk - (ptrdiff_t)16 * ZC) : (v4u){0u, 0u, 0u, 0u}; }
	v_lshlrev_b32_e32 v92, 16, v20
	v_and_b32_e32 v93, 0xffff0000, v20
	v_lshlrev_b32_e32 v94, 16, v21
	v_and_b32_e32 v95, 0xffff0000, v21
	v_lshlrev_b32_e32 v96, 16, v22
	v_and_b32_e32 v97, 0xffff0000, v22
	v_lshlrev_b32_e32 v98, 16, v23
	v_and_b32_e32 v99, 0xffff0000, v23
	v_lshlrev_b32_e32 v132, 16, v52
	v_and_b32_e32 v133, 0xffff0000, v52
	v_lshlrev_b32_e32 v134, 16, v53
	v_and_b32_e32 v135, 0xffff0000, v53
	v_lshlrev_b32_e32 v136, 16, v54
	v_and_b32_e32 v137, 0xffff0000, v54
	v_lshlrev_b32_e32 v138, 16, v55
	v_and_b32_e32 v139, 0xffff0000, v55
	v_mul_f32_e32 v140, v100, v124
	v_fmac_f32_e32 v140, v108, v84
	v_fmac_f32_e32 v140, v116, v92
	v_mul_f32_e32 v140, v132, v140
	v_mul_f32_e32 v141, v101, v125
	v_fmac_f32_e32 v141, v109, v85
	v_fmac_f32_e32 v141, v117, v93
	v_mul_f32_e32 v141, v133, v141
	v_mul_f32_e32 v142, v102, v126
	v_fmac_f32_e32 v142, v110, v86
	v_fmac_f32_e32 v142, v118, v94
	v_mul_f32_e32 v142, v134, v142
	v_mul_f32_e32 v143, v103, v127
	v_fmac_f32_e32 v143, v111, v87
	v_fmac_f32_e32 v143, v119, v95
	v_mul_f32_e32 v143, v135, v143
	v_mul_f32_e32 v144, v104, v128
	v_fmac_f32_e32 v144, v112, v88
	v_fmac_f32_e32 v144, v120, v96
	v_mul_f32_e32 v144, v136, v144
	v_mul_f32_e32 v145, v105, v129
	v_fmac_f32_e32 v145, v113, v89
	v_fmac_f32_e32 v145, v121, v97
	v_mul_f32_e32 v145, v137, v145
	v_mul_f32_e32 v146, v106, v130
	v_fmac_f32_e32 v146, v114, v90
	v_fmac_f32_e32 v146, v122, v98
	v_mul_f32_e32 v146, v138, v146
	v_mul_f32_e32 v147, v107, v131
	v_fmac_f32_e32 v147, v115, v91
	v_fmac_f32_e32 v147, v123, v99
	v_mul_f32_e32 v147, v139, v147
	v_cvt_pk_bf16_f32 v140, v140, v141
	v_cvt_pk_bf16_f32 v141, v142, v143
	v_cvt_pk_bf16_f32 v142, v144, v145
	v_cvt_pk_bf16_f32 v143, v146, v147
	global_store_dwordx4 v2, v[140:143], s[46:47] offset:1024
	s_add_u32 s46, s46, 0x1000
	s_addc_u32 s47, s47, 0
	global_load_dwordx4 v[12:15], v11, s[38:39]
	global_load_dwordx4 v[16:19], v11, s[48:49]
	s_waitcnt vmcnt(21)
	v_lshlrev_b32_e32 v124, 16, v24
	v_and_b32_e32 v125, 0xffff0000, v24
	v_lshlrev_b32_e32 v126, 16, v25
	v_and_b32_e32 v127, 0xffff0000, v25
	v_lshlrev_b32_e32 v128, 16, v26
	v_and_b32_e32 v129, 0xffff0000, v26
	v_lshlrev_b32_e32 v130, 16, v27
	v_and_b32_e32 v131, 0xffff0000, v27
	v_lshlrev_b32_e32 v132, 16, v56
	v_and_b32_e32 v133, 0xffff0000, v56
	v_lshlrev_b32_e32 v134, 16, v57
	v_and_b32_e32 v135, 0xffff0000, v57
	v_lshlrev_b32_e32 v136, 16, v58
	v_and_b32_e32 v137, 0xffff0000, v58
	v_lshlrev_b32_e32 v138, 16, v59
	v_and_b32_e32 v139, 0xffff0000, v59
	v_mul_f32_e32 v140, v100, v84
	v_fmac_f32_e32 v140, v108, v92
	v_fmac_f32_e32 v140, v116, v124
	v_mul_f32_e32 v140, v132, v140
	v_mul_f32_e32 v141, v101, v85
	v_fmac_f32_e32 v141, v109, v93
	v_fmac_f32_e32 v141, v117, v125
	v_mul_f32_e32 v141, v133, v141
	v_mul_f32_e32 v142, v102, v86
	v_fmac_f32_e32 v142, v110, v94
	v_fmac_f32_e32 v142, v118, v126
	v_mul_f32_e32 v142, v134, v142
	v_mul_f32_e32 v143, v103, v87
	v_fmac_f32_e32 v143, v111, v95
	v_fmac_f32_e32 v143, v119, v127
	v_mul_f32_e32 v143, v135, v143
	v_mul_f32_e32 v144, v104, v88
	v_fmac_f32_e32 v144, v112, v96
	v_fmac_f32_e32 v144, v120, v128
	v_mul_f32_e32 v144, v136, v144
	v_mul_f32_e32 v145, v105, v89
	v_fmac_f32_e32 v145, v113, v97
	v_fmac_f32_e32 v145, v121, v129
	v_mul_f32_e32 v145, v137, v145
	v_mul_f32_e32 v146, v106, v90
	v_fmac_f32_e32 v146, v114, v98
	v_fmac_f32_e32 v146, v122, v130
	v_mul_f32_e32 v146, v138, v146
	v_mul_f32_e32 v147, v107, v91
	v_fmac_f32_e32 v147, v115, v99
	v_fmac_f32_e32 v147, v123, v131
	v_mul_f32_e32 v147, v139, v147
	v_cvt_pk_bf16_f32 v140, v140, v141
	v_cvt_pk_bf16_f32 v141, v142, v143
	v_cvt_pk_bf16_f32 v142, v144, v145
	v_cvt_pk_bf16_f32 v143, v146, v147
	global_store_dwordx4 v2, v[140:143], s[46:47] offset:1024
	s_add_u32 s46, s46, 0x1000
	s_addc_u32 s47, s47, 0
	global_load_dwordx4 v[20:23], v11, s[38:39] offset:64
	global_load_dwordx4 v[24:27], v11, s[48:49] offset:64
	s_waitcnt vmcnt(21)
	v_lshlrev_b32_e32 v84, 16, v28
	v_and_b32_e32 v85, 0xffff0000, v28
	v_lshlrev_b32_e32 v86, 16, v29
	v_and_b32_e32 v87, 0xffff0000, v29
	v_lshlrev_b32_e32 v88, 16, v30
	v_and_b32_e32 v89, 0xffff0000, v30
	v_lshlrev_b32_e32 v90, 16, v31
	v_and_b32_e32 v91, 0xffff0000, v31
	v_lshlrev_b32_e32 v132, 16, v60
	v_and_b32_e32 v133, 0xffff0000, v60
	v_lshlrev_b32_e32 v134, 16, v61
	v_and_b32_e32 v135, 0xffff0000, v61
	v_lshlrev_b32_e32 v136, 16, v62
	v_and_b32_e32 v137, 0xffff0000, v62
	v_lshlrev_b32_e32 v138, 16, v63
	v_and_b32_e32 v139, 0xffff0000, v63
	v_mul_f32_e32 v140, v100, v92
	v_fmac_f32_e32 v140, v108, v124
	v_fmac_f32_e32 v140, v116, v84
	v_mul_f32_e32 v140, v132, v140
	v_mul_f32_e32 v141, v101, v93
	v_fmac_f32_e32 v141, v109, v125
	v_fmac_f32_e32 v141, v117, v85
	v_mul_f32_e32 v141, v133, v141
	v_mul_f32_e32 v142, v102, v94
	v_fmac_f32_e32 v142, v110, v126
	v_fmac_f32_e32 v142, v118, v86
	v_mul_f32_e32 v142, v134, v142
	v_mul_f32_e32 v143, v103, v95
	v_fmac_f32_e32 v143, v111, v127
	v_fmac_f32_e32 v143, v119, v87
	v_mul_f32_e32 v143, v135, v143
	v_mul_f32_e32 v144, v104, v96
	v_fmac_f32_e32 v144, v112, v128
	v_fmac_f32_e32 v144, v120, v88
	v_mul_f32_e32 v144, v136, v144
	v_mul_f32_e32 v145, v105, v97
	v_fmac_f32_e32 v145, v113, v129
	v_fmac_f32_e32 v145, v121, v89
	v_mul_f32_e32 v145, v137, v145
	v_mul_f32_e32 v146, v106, v98
	v_fmac_f32_e32 v146, v114, v130
	v_fmac_f32_e32 v146, v122, v90
	v_mul_f32_e32 v146, v138, v146
	v_mul_f32_e32 v147, v107, v99
	v_fmac_f32_e32 v147, v115, v131
	v_fmac_f32_e32 v147, v123, v91
	v_mul_f32_e32 v147, v139, v147
	v_cvt_pk_bf16_f32 v140, v140, v141
	v_cvt_pk_bf16_f32 v141, v142, v143
	v_cvt_pk_bf16_f32 v142, v144, v145
	v_cvt_pk_bf16_f32 v143, v146, v147
	global_store_dwordx4 v2, v[140:143], s[46:47] offset:1024
	s_add_u32 s46, s46, 0x1000
	s_addc_u32 s47, s47, 0
	s_waitcnt vmcnt(19)
; #define GAS __attribute__((address_space(1)))
; __device__ __forceinline__ void unpack8(const v4u w, float (&f)[8]) { f[0] = bf_lo(w.x); f[1] = bf_hi(w.x); f[2] = bf_lo(w.y); f[3] = bf_hi(w.y); f[4] = bf_lo(w.z); f[5] = bf_hi(w.z); f[6] = bf_lo(w.w); f[7] = bf_hi(w.w); }
; __device__ __forceinline__ v4u pack8(const float (&f)[8]) { v4u w; w.x = cvt_pk_bf16(f[0], f[1]); w.y = cvt_pk_bf16(f[2], f[3]); w.z = cvt_pk_bf16(f[4], f[5]); w.w = cvt_pk_bf16(f[6], f[7]); return w; }
; __device__ __forceinline__ void mixer_shortconv(const Frame& F, const Args& A, int l, int chunk, const bf16* Z, bf16* MIX) {
;     ...
;     for (int dt = -2; dt < 16; ++dt) {
;         const int t = t0 + dt; const bool valid = (pos0 + t) >= 0;
;         const bf16* zr = Z + (size_t)(row0 + (valid ? t : 0)) * ZC;
;         float xv[8], x[8];
;         unpack8(*(const GAS v4u*)(zr + 1024 + c8), xv);
; #pragma unroll
;         for (int j = 0; j < 8; ++j) x[j] = valid ? xv[j] : 0.f;
;         if (dt >= 0) { float bg[8], o[8]; unpack8(*(const GAS v4u*)(zr + 1536 + c8), bg);
; #pragma unroll
;             for (int j = 0; j < 8; ++j) o[j] = bg[j] * (w0[j] * xm2[j] + w1[j] * xm1[j] + w2[j] * x[j]);
;             *(GAS v4u*)(MIX + (size_t)(row0 + t) * D + 512 + c8) = pack8(o); }
; #pragma unroll
;         for (int j = 0; j < 8; ++j) { xm2[j] = xm1[j]; xm1[j] = x[j]; }
;     }
; template <int W> __device__ __forceinline__ void pool_group(const bf16* zrow  , const bf16* pw  , bf16* orow  , int pos, bool prev_ok) {
;     const float inv = 1.0f / (float)((pos + 1) < W ? (pos + 1) : W);
;     f32x4 acc[8];
; #pragma unroll
;     for (int dt = 0; dt < 8; ++dt) acc[dt] = (f32x4){0.f, 0.f, 0.f, 0.f};
;     v4u cw[4], pv[4], aw[2][8];
; #pragma unroll
;     for (int kk = 0; kk < 4; ++kk) { cw[kk] = *(const GAS v4u*)(zrow + 32 * kk); pv[kk] = prev_ok ? *(const GAS v4u*)(zrow + 32 * kk - (ptrdiff_t)16 * ZC) : (v4u){0u, 0u, 0u, 0u}; }
	v_lshlrev_b32_e32 v92, 16, v32
	v_and_b32_e32 v93, 0xffff0000, v32
	v_lshlrev_b32_e32 v94, 16, v33
	v_and_b32_e32 v95, 0xffff0000, v33
	v_lshlrev_b32_e32 v96, 16, v34
	v_and_b32_e32 v97, 0xffff0000, v34
	v_lshlrev_b32_e32 v98, 16, v35
	v_and_b32_e32 v99, 0xffff0000, v35
	v_lshlrev_b32_e32 v132, 16, v64
	v_and_b32_e32 v133, 0xffff0000, v64
	v_lshlrev_b32_e32 v134, 16, v65
	v_and_b32_e32 v135, 0xffff0000, v65
	v_lshlrev_b32_e32 v136, 16, v66
	v_and_b32_e32 v137, 0xffff0000, v66
	v_lshlrev_b32_e32 v138, 16, v67
	v_and_b32_e32 v139, 0xffff0000, v67
	v_mul_f32_e32 v140, v100, v124
	v_fmac_f32_e32 v140, v108, v84
	v_fmac_f32_e32 v140, v116, v92
	v_mul_f32_e32 v140, v132, v140
	v_mul_f32_e32 v141, v101, v125
	v_fmac_f32_e32 v141, v109, v85
	v_fmac_f32_e32 v141, v117, v93
	v_mul_f32_e32 v141, v133, v141
	v_mul_f32_e32 v142, v102, v126
	v_fmac_f32_e32 v142, v110, v86
	v_fmac_f32_e32 v142, v118, v94
	v_mul_f32_e32 v142, v134, v142
	v_mul_f32_e32 v143, v103, v127
	v_fmac_f32_e32 v143, v111, v87
	v_fmac_f32_e32 v143, v119, v95
	v_mul_f32_e32 v143, v135, v143
	v_mul_f32_e32 v144, v104, v128
	v_fmac_f32_e32 v144, v112, v88
	v_fmac_f32_e32 v144, v120, v96
	v_mul_f32_e32 v144, v136, v144
	v_mul_f32_e32 v145, v105, v129
	v_fmac_f32_e32 v145, v113, v89
	v_fmac_f32_e32 v145, v121, v97
	v_mul_f32_e32 v145, v137, v145
	v_mul_f32_e32 v146, v106, v130
	v_fmac_f32_e32 v146, v114, v90
	v_fmac_f32_e32 v146, v122, v98
	v_mul_f32_e32 v146, v138, v146
	v_mul_f32_e32 v147, v107, v131
	v_fmac_f32_e32 v147, v115, v91
	v_fmac_f32_e32 v147, v123, v99
	v_mul_f32_e32 v147, v139, v147
	v_cvt_pk_bf16_f32 v140, v140, v141
	v_cvt_pk_bf16_f32 v141, v142, v143
	v_cvt_pk_bf16_f32 v142, v144, v145
	v_cvt_pk_bf16_f32 v143, v146, v147
	global_store_dwordx4 v2, v[140:143], s[46:47] offset:1024
	s_add_u32 s46, s46, 0x1000
	s_addc_u32 s47, s47, 0
	global_load_dwordx4 v[28:31], v11, s[38:39] offset:128
	global_load_dwordx4 v[32:35], v11, s[48:49] offset:128
	s_waitcnt vmcnt(19)
	v_lshlrev_b32_e32 v124, 16, v36
	v_and_b32_e32 v125, 0xffff0000, v36
	v_lshlrev_b32_e32 v126, 16, v37
	v_and_b32_e32 v127, 0xffff0000, v37
	v_lshlrev_b32_e32 v128, 16, v38
	v_and_b32_e32 v129, 0xffff0000, v38
	v_lshlrev_b32_e32 v130, 16, v39
	v_and_b32_e32 v131, 0xffff0000, v39
	v_lshlrev_b32_e32 v132, 16, v68
	v_and_b32_e32 v133, 0xffff0000, v68
	v_lshlrev_b32_e32 v134, 16, v69
	v_and_b32_e32 v135, 0xffff0000, v69
	v_lshlrev_b32_e32 v136, 16, v70
	v_and_b32_e32 v137, 0xffff0000, v70
	v_lshlrev_b32_e32 v138, 16, v71
	v_and_b32_e32 v139, 0xffff0000, v71
	v_mul_f32_e32 v140, v100, v84
	v_fmac_f32_e32 v140, v108, v92
	v_fmac_f32_e32 v140, v116, v124
	v_mul_f32_e32 v140, v132, v140
	v_mul_f32_e32 v141, v101, v85
	v_fmac_f32_e32 v141, v109, v93
	v_fmac_f32_e32 v141, v117, v125
	v_mul_f32_e32 v141, v133, v141
	v_mul_f32_e32 v142, v102, v86
	v_fmac_f32_e32 v142, v110, v94
	v_fmac_f32_e32 v142, v118, v126
	v_mul_f32_e32 v142, v134, v142
	v_mul_f32_e32 v143, v103, v87
	v_fmac_f32_e32 v143, v111, v95
	v_fmac_f32_e32 v143, v119, v127
	v_mul_f32_e32 v143, v135, v143
	v_mul_f32_e32 v144, v104, v88
	v_fmac_f32_e32 v144, v112, v96
	v_fmac_f32_e32 v144, v120, v128
	v_mul_f32_e32 v144, v136, v144
	v_mul_f32_e32 v145, v105, v89
	v_fmac_f32_e32 v145, v113, v97
	v_fmac_f32_e32 v145, v121, v129
	v_mul_f32_e32 v145, v137, v145
	v_mul_f32_e32 v146, v106, v90
	v_fmac_f32_e32 v146, v114, v98
	v_fmac_f32_e32 v146, v122, v130
	v_mul_f32_e32 v146, v138, v146
	v_mul_f32_e32 v147, v107, v91
	v_fmac_f32_e32 v147, v115, v99
	v_fmac_f32_e32 v147, v123, v131
	v_mul_f32_e32 v147, v139, v147
	v_cvt_pk_bf16_f32 v140, v140, v141
	v_cvt_pk_bf16_f32 v141, v142, v143
	v_cvt_pk_bf16_f32 v142, v144, v145
	v_cvt_pk_bf16_f32 v143, v146, v147
	global_store_dwordx4 v2, v[140:143], s[46:47] offset:1024
	s_add_u32 s46, s46, 0x1000
	s_addc_u32 s47, s47, 0
	s_waitcnt vmcnt(17)
	v_lshlrev_b32_e32 v84, 16, v40
	v_and_b32_e32 v85, 0xffff0000, v40
	v_lshlrev_b32_e32 v86, 16, v41
	v_and_b32_e32 v87, 0xffff0000, v41
	v_lshlrev_b32_e32 v88, 16, v42
	v_and_b32_e32 v89, 0xffff0000, v42
	v_lshlrev_b32_e32 v90, 16, v43
	v_and_b32_e32 v91, 0xffff0000, v43
	v_lshlrev_b32_e32 v132, 16, v72
	v_and_b32_e32 v133, 0xffff0000, v72
	v_lshlrev_b32_e32 v134, 16, v73
	v_and_b32_e32 v135, 0xffff0000, v73
	v_lshlrev_b32_e32 v136, 16, v74
	v_and_b32_e32 v137, 0xffff0000, v74
	v_lshlrev_b32_e32 v138, 16, v75
	v_and_b32_e32 v139, 0xffff0000, v75
	v_mul_f32_e32 v140, v100, v92
	v_fmac_f32_e32 v140, v108, v124
	v_fmac_f32_e32 v140, v116, v84
	v_mul_f32_e32 v140, v132, v140
	v_mul_f32_e32 v141, v101, v93
	v_fmac_f32_e32 v141, v109, v125
	v_fmac_f32_e32 v141, v117, v85
	v_mul_f32_e32 v141, v133, v141
	v_mul_f32_e32 v142, v102, v94
	v_fmac_f32_e32 v142, v110, v126
	v_fmac_f32_e32 v142, v118, v86
	v_mul_f32_e32 v142, v134, v142
	v_mul_f32_e32 v143, v103, v95
	v_fmac_f32_e32 v143, v111, v127
	v_fmac_f32_e32 v143, v119, v87
	v_mul_f32_e32 v143, v135, v143
	v_mul_f32_e32 v144, v104, v96
	v_fmac_f32_e32 v144, v112, v128
	v_fmac_f32_e32 v144, v120, v88
	v_mul_f32_e32 v144, v136, v144
	v_mul_f32_e32 v145, v105, v97
	v_fmac_f32_e32 v145, v113, v129
	v_fmac_f32_e32 v145, v121, v89
	v_mul_f32_e32 v145, v137, v145
	v_mul_f32_e32 v146, v106, v98
	v_fmac_f32_e32 v146, v114, v130
	v_fmac_f32_e32 v146, v122, v90
	v_mul_f32_e32 v146, v138, v146
	v_mul_f32_e32 v147, v107, v99
	v_fmac_f32_e32 v147, v115, v131
	v_fmac_f32_e32 v147, v123, v91
	v_mul_f32_e32 v147, v139, v147
	v_cvt_pk_bf16_f32 v140, v140, v141
	v_cvt_pk_bf16_f32 v141, v142, v143
	v_cvt_pk_bf16_f32 v142, v144, v145
	v_cvt_pk_bf16_f32 v143, v146, v147
	global_store_dwordx4 v2, v[140:143], s[46:47] offset:1024
	s_add_u32 s46, s46, 0x1000
	s_addc_u32 s47, s47, 0
	global_load_dwordx4 v[36:39], v11, s[38:39] offset:192
	global_load_dwordx4 v[40:43], v11, s[48:49] offset:192
	s_waitcnt vmcnt(17)
; #define GAS __attribute__((address_space(1)))
; __device__ __forceinline__ void unpack8(const v4u w, float (&f)[8]) { f[0] = bf_lo(w.x); f[1] = bf_hi(w.x); f[2] = bf_lo(w.y); f[3] = bf_hi(w.y); f[4] = bf_lo(w.z); f[5] = bf_hi(w.z); f[6] = bf_lo(w.w); f[7] = bf_hi(w.w); }
; __device__ __forceinline__ v4u pack8(const float (&f)[8]) { v4u w; w.x = cvt_pk_bf16(f[0], f[1]); w.y = cvt_pk_bf16(f[2], f[3]); w.z = cvt_pk_bf16(f[4], f[5]); w.w = cvt_pk_bf16(f[6], f[7]); return w; }
; __device__ __forceinline__ void mixer_shortconv(const Frame& F, const Args& A, int l, int chunk, const bf16* Z, bf16* MIX) {
;     ...
;     for (int dt = -2; dt < 16; ++dt) {
;         const int t = t0 + dt; const bool valid = (pos0 + t) >= 0;
;         const bf16* zr = Z + (size_t)(row0 + (valid ? t : 0)) * ZC;
;         float xv[8], x[8];
;         unpack8(*(const GAS v4u*)(zr + 1024 + c8), xv);
; #pragma unroll
;         for (int j = 0; j < 8; ++j) x[j] = valid ? xv[j] : 0.f;
;         if (dt >= 0) { float bg[8], o[8]; unpack8(*(const GAS v4u*)(zr + 1536 + c8), bg);
; #pragma unroll
;             for (int j = 0; j < 8; ++j) o[j] = bg[j] * (w0[j] * xm2[j] + w1[j] * xm1[j] + w2[j] * x[j]);
;             *(GAS v4u*)(MIX + (size_t)(row0 + t) * D + 512 + c8) = pack8(o); }
; #pragma unroll
;         for (int j = 0; j < 8; ++j) { xm2[j] = xm1[j]; xm1[j] = x[j]; }
;     }
; template <int W> __device__ __forceinline__ void pool_group(const bf16* zrow  , const bf16* pw  , bf16* orow  , int pos, bool prev_ok) {
;     const float inv = 1.0f / (float)((pos + 1) < W ? (pos + 1) : W);
;     f32x4 acc[8];
; #pragma unroll
;     for (int dt = 0; dt < 8; ++dt) acc[dt] = (f32x4){0.f, 0.f, 0.f, 0.f};
;     v4u cw[4], pv[4], aw[2][8];
; #pragma unroll
;     for (int kk = 0; kk < 4; ++kk) { cw[kk] = *(const GAS v4u*)(zrow + 32 * kk); pv[kk] = prev_ok ? *(const GAS v4u*)(zrow + 32 * kk - (ptrdiff_t)16 * ZC) : (v4u){0u, 0u, 0u, 0u}; }
; #pragma unroll
;     for (int dt = 0; dt < 8; ++dt) aw[0][dt] = *(const GAS v4u*)(pw + (size_t)16 * dt * 128);
	v_lshlrev_b32_e32 v92, 16, v44
	v_and_b32_e32 v93, 0xffff0000, v44
	v_lshlrev_b32_e32 v94, 16, v45
	v_and_b32_e32 v95, 0xffff0000, v45
	v_lshlrev_b32_e32 v96, 16, v46
	v_and_b32_e32 v97, 0xffff0000, v46
	v_lshlrev_b32_e32 v98, 16, v47
	v_and_b32_e32 v99, 0xffff0000, v47
	v_lshlrev_b32_e32 v132, 16, v76
	v_and_b32_e32 v133, 0xffff0000, v76
	v_lshlrev_b32_e32 v134, 16, v77
	v_and_b32_e32 v135, 0xffff0000, v77
	v_lshlrev_b32_e32 v136, 16, v78
	v_and_b32_e32 v137, 0xffff0000, v78
	v_lshlrev_b32_e32 v138, 16, v79
	v_and_b32_e32 v139, 0xffff0000, v79
	v_mul_f32_e32 v140, v100, v124
	v_fmac_f32_e32 v140, v108, v84
	v_fmac_f32_e32 v140, v116, v92
	v_mul_f32_e32 v140, v132, v140
	v_mul_f32_e32 v141, v101, v125
	v_fmac_f32_e32 v141, v109, v85
	v_fmac_f32_e32 v141, v117, v93
	v_mul_f32_e32 v141, v133, v141
	v_mul_f32_e32 v142, v102, v126
	v_fmac_f32_e32 v142, v110, v86
	v_fmac_f32_e32 v142, v118, v94
	v_mul_f32_e32 v142, v134, v142
	v_mul_f32_e32 v143, v103, v127
	v_fmac_f32_e32 v143, v111, v87
	v_fmac_f32_e32 v143, v119, v95
	v_mul_f32_e32 v143, v135, v143
	v_mul_f32_e32 v144, v104, v128
	v_fmac_f32_e32 v144, v112, v88
	v_fmac_f32_e32 v144, v120, v96
	v_mul_f32_e32 v144, v136, v144
	v_mul_f32_e32 v145, v105, v129
	v_fmac_f32_e32 v145, v113, v89
	v_fmac_f32_e32 v145, v121, v97
	v_mul_f32_e32 v145, v137, v145
	v_mul_f32_e32 v146, v106, v130
	v_fmac_f32_e32 v146, v114, v90
	v_fmac_f32_e32 v146, v122, v98
	v_mul_f32_e32 v146, v138, v146
	v_mul_f32_e32 v147, v107, v131
	v_fmac_f32_e32 v147, v115, v91
	v_fmac_f32_e32 v147, v123, v99
	v_mul_f32_e32 v147, v139, v147
	v_cvt_pk_bf16_f32 v140, v140, v141
	v_cvt_pk_bf16_f32 v141, v142, v143
	v_cvt_pk_bf16_f32 v142, v144, v145
	v_cvt_pk_bf16_f32 v143, v146, v147
	global_store_dwordx4 v2, v[140:143], s[46:47] offset:1024
	s_add_u32 s46, s46, 0x1000
	s_addc_u32 s47, s47, 0
	s_waitcnt vmcnt(15)
	v_lshlrev_b32_e32 v124, 16, v48
	v_and_b32_e32 v125, 0xffff0000, v48
	v_lshlrev_b32_e32 v126, 16, v49
	v_and_b32_e32 v127, 0xffff0000, v49
	v_lshlrev_b32_e32 v128, 16, v50
	v_and_b32_e32 v129, 0xffff0000, v50
	v_lshlrev_b32_e32 v130, 16, v51
	v_and_b32_e32 v131, 0xffff0000, v51
	v_lshlrev_b32_e32 v132, 16, v80
	v_and_b32_e32 v133, 0xffff0000, v80
	v_lshlrev_b32_e32 v134, 16, v81
	v_and_b32_e32 v135, 0xffff0000, v81
	v_lshlrev_b32_e32 v136, 16, v82
	v_and_b32_e32 v137, 0xffff0000, v82
	v_lshlrev_b32_e32 v138, 16, v83
	v_and_b32_e32 v139, 0xffff0000, v83
	v_mul_f32_e32 v140, v100, v84
	v_fmac_f32_e32 v140, v108, v92
	v_fmac_f32_e32 v140, v116, v124
	v_mul_f32_e32 v140, v132, v140
	v_mul_f32_e32 v141, v101, v85
	v_fmac_f32_e32 v141, v109, v93
	v_fmac_f32_e32 v141, v117, v125
	v_mul_f32_e32 v141, v133, v141
	v_mul_f32_e32 v142, v102, v86
	v_fmac_f32_e32 v142, v110, v94
	v_fmac_f32_e32 v142, v118, v126
	v_mul_f32_e32 v142, v134, v142
	v_mul_f32_e32 v143, v103, v87
	v_fmac_f32_e32 v143, v111, v95
	v_fmac_f32_e32 v143, v119, v127
	v_mul_f32_e32 v143, v135, v143
	v_mul_f32_e32 v144, v104, v88
	v_fmac_f32_e32 v144, v112, v96
	v_fmac_f32_e32 v144, v120, v128
	v_mul_f32_e32 v144, v136, v144
	v_mul_f32_e32 v145, v105, v89
	v_fmac_f32_e32 v145, v113, v97
	v_fmac_f32_e32 v145, v121, v129
	v_mul_f32_e32 v145, v137, v145
	v_mul_f32_e32 v146, v106, v90
	v_fmac_f32_e32 v146, v114, v98
	v_fmac_f32_e32 v146, v122, v130
	v_mul_f32_e32 v146, v138, v146
	v_mul_f32_e32 v147, v107, v91
	v_fmac_f32_e32 v147, v115, v99
	v_fmac_f32_e32 v147, v123, v131
	v_mul_f32_e32 v147, v139, v147
	v_cvt_pk_bf16_f32 v140, v140, v141
	v_cvt_pk_bf16_f32 v141, v142, v143
	v_cvt_pk_bf16_f32 v142, v144, v145
	v_cvt_pk_bf16_f32 v143, v146, v147
	global_store_dwordx4 v2, v[140:143], s[46:47] offset:1024
	s_add_u32 s46, s46, 0x1000
	s_addc_u32 s47, s47, 0
	s_barrier
	v_lshlrev_b32_e32 v142, 12, v4
	v_lshl_add_u32 v142, v5, 3, v142
	v_or_b32_e32 v10, 0, v5
	v_xor_b32_e32 v10, v4, v10
	v_lshlrev_b32_e32 v10, 4, v10
	v_lshl_add_u32 v143, v4, 8, v10
	v_or_b32_e32 v10, 4, v5
	v_xor_b32_e32 v10, v4, v10
	v_lshlrev_b32_e32 v10, 4, v10
	v_lshl_add_u32 v144, v4, 8, v10
	v_or_b32_e32 v10, 8, v5
	v_xor_b32_e32 v10, v4, v10
	v_lshlrev_b32_e32 v10, 4, v10
	v_lshl_add_u32 v145, v4, 8, v10
	v_or_b32_e32 v10, 12, v5
	v_xor_b32_e32 v10, v4, v10
	v_lshlrev_b32_e32 v10, 4, v10
	v_lshl_add_u32 v146, v4, 8, v10
	s_add_i32 s37, s4, s56
	v_add_u32_e32 v140, s37, v4
	v_add_u32_e32 v140, 1, v140
	s_add_u32 s46, s2, s84
	s_addc_u32 s47, s3, 0
	s_add_u32 s46, s46, 0xc00
	s_addc_u32 s47, s47, 0
	v_min_i32_e32 v139, 2, v140
	v_cvt_f32_i32_e32 v139, v139
	v_div_scale_f32 v1, s[42:43], v139, v139, 1.0
	v_rcp_f32_e32 v2, v1
	s_nop 0
	v_fma_f32 v7, -v1, v2, 1.0
	v_fmac_f32_e32 v2, v7, v2
	v_div_scale_f32 v3, vcc, 1.0, v139, 1.0
	v_mul_f32_e32 v6, v3, v2
	v_fma_f32 v7, -v1, v6, v3
	v_fmac_f32_e32 v6, v7, v2
	v_fma_f32 v1, -v1, v6, v3
	s_nop 1
	v_div_fmas_f32 v1, v1, v2, v6
	v_div_fixup_f32 v138, v1, v139, 1.0
	v_add_u32_e32 v147, 0, v143
	ds_read_b128 v[44:47], v147
	ds_read_b128 v[48:51], v147 offset:4096
	ds_read_b128 v[52:55], v147 offset:8192
	ds_read_b128 v[56:59], v147 offset:12288
	ds_read_b128 v[60:63], v147 offset:16384
	ds_read_b128 v[64:67], v147 offset:20480
	ds_read_b128 v[68:71], v147 offset:24576
	ds_read_b128 v[72:75], v147 offset:28672
	s_waitcnt vmcnt(13)
; #define GAS __attribute__((address_space(1)))
; __device__ __forceinline__ void unpack8(const v4u w, float (&f)[8]) { f[0] = bf_lo(w.x); f[1] = bf_hi(w.x); f[2] = bf_lo(w.y); f[3] = bf_hi(w.y); f[4] = bf_lo(w.z); f[5] = bf_hi(w.z); f[6] = bf_lo(w.w); f[7] = bf_hi(w.w); }
; __device__ __forceinline__ v4u pack8(const float (&f)[8]) { v4u w; w.x = cvt_pk_bf16(f[0], f[1]); w.y = cvt_pk_bf16(f[2], f[3]); w.z = cvt_pk_bf16(f[4], f[5]); w.w = cvt_pk_bf16(f[6], f[7]); return w; }
; template <int W> __device__ __forceinline__ void pool_group(const bf16* zrow  , const bf16* pw  , bf16* orow  , int pos, bool prev_ok) {
;     ...
;     for (int kk = 0; kk < 4; ++kk) {
;         if (kk < 3) {
; #pragma unroll
;             for (int dt = 0; dt < 8; ++dt) aw[(kk + 1) & 1][dt] = *(const GAS v4u*)(pw + (size_t)16 * dt * 128 + 32 * (kk + 1)); }
;         float own[8], c[8], p[8];
;         unpack8(cw[kk], own); unpack8(pv[kk], p);
; #pragma unroll
;         for (int j = 0; j < 8; ++j) c[j] = own[j];
;         win_step<1>(c, p);
;         if (W >= 4) win_step<2>(c, p);
;         if (W >= 8) win_step<4>(c, p);
;         if (W >= 16) win_step<8>(c, p);
;         float pl[8];
; #pragma unroll
;         for (int j = 0; j < 8; ++j) pl[j] = c[j] * inv - own[j];
;         const v4u pwk = pack8(pl); const bf16x8 pf = __builtin_bit_cast(bf16x8, pwk);
; #pragma unroll
;         for (int dt = 0; dt < 8; ++dt) acc[dt] = __builtin_amdgcn_mfma_f32_16x16x32_bf16(__builtin_bit_cast(bf16x8, aw[kk & 1][dt]), pf, acc[dt], 0, 0, 0);
	v_lshlrev_b32_e32 v108, 16, v12
	v_and_b32_e32 v109, 0xffff0000, v12
	v_lshlrev_b32_e32 v110, 16, v13
	v_and_b32_e32 v111, 0xffff0000, v13
	v_lshlrev_b32_e32 v112, 16, v14
	v_and_b32_e32 v113, 0xffff0000, v14
	v_lshlrev_b32_e32 v114, 16, v15
	v_and_b32_e32 v115, 0xffff0000, v15
	v_lshlrev_b32_e32 v124, 16, v16
	v_and_b32_e32 v125, 0xffff0000, v16
	v_lshlrev_b32_e32 v126, 16, v17
	v_and_b32_e32 v127, 0xffff0000, v17
	v_lshlrev_b32_e32 v128, 16, v18
	v_and_b32_e32 v129, 0xffff0000, v18
	v_lshlrev_b32_e32 v130, 16, v19
	v_and_b32_e32 v131, 0xffff0000, v19
	v_cndmask_b32_e64 v124, 0, v124, s[40:41]
	v_cndmask_b32_e64 v125, 0, v125, s[40:41]
	v_cndmask_b32_e64 v126, 0, v126, s[40:41]
	v_cndmask_b32_e64 v127, 0, v127, s[40:41]
	v_cndmask_b32_e64 v128, 0, v128, s[40:41]
	v_cndmask_b32_e64 v129, 0, v129, s[40:41]
	v_cndmask_b32_e64 v130, 0, v130, s[40:41]
	v_cndmask_b32_e64 v131, 0, v131, s[40:41]
	global_load_dwordx4 v[12:15], v11, s[38:39] offset:256
	global_load_dwordx4 v[16:19], v11, s[48:49] offset:256
	v_mov_b32_e32 v116, v108
	v_mov_b32_e32 v117, v109
	v_mov_b32_e32 v118, v110
	v_mov_b32_e32 v119, v111
	v_mov_b32_e32 v120, v112
	v_mov_b32_e32 v121, v113
	v_mov_b32_e32 v122, v114
	v_mov_b32_e32 v123, v115
	v_add_f32_dpp v132, v116, v116 row_shr:1 row_mask:0xf bank_mask:0xf bound_ctrl:1
	v_add_f32_dpp v116, v124, v132 row_shl:15 row_mask:0xf bank_mask:0xf bound_ctrl:1
	v_add_f32_dpp v124, v124, v124 row_shr:1 row_mask:0xf bank_mask:0xf bound_ctrl:1
	v_add_f32_dpp v132, v117, v117 row_shr:1 row_mask:0xf bank_mask:0xf bound_ctrl:1
	v_add_f32_dpp v117, v125, v132 row_shl:15 row_mask:0xf bank_mask:0xf bound_ctrl:1
	v_add_f32_dpp v125, v125, v125 row_shr:1 row_mask:0xf bank_mask:0xf bound_ctrl:1
	v_add_f32_dpp v132, v118, v118 row_shr:1 row_mask:0xf bank_mask:0xf bound_ctrl:1
	v_add_f32_dpp v118, v126, v132 row_shl:15 row_mask:0xf bank_mask:0xf bound_ctrl:1
	v_add_f32_dpp v126, v126, v126 row_shr:1 row_mask:0xf bank_mask:0xf bound_ctrl:1
	v_add_f32_dpp v132, v119, v119 row_shr:1 row_mask:0xf bank_mask:0xf bound_ctrl:1
	v_add_f32_dpp v119, v127, v132 row_shl:15 row_mask:0xf bank_mask:0xf bound_ctrl:1
	v_add_f32_dpp v127, v127, v127 row_shr:1 row_mask:0xf bank_mask:0xf bound_ctrl:1
	v_add_f32_dpp v132, v120, v120 row_shr:1 row_mask:0xf bank_mask:0xf bound_ctrl:1
	v_add_f32_dpp v120, v128, v132 row_shl:15 row_mask:0xf bank_mask:0xf bound_ctrl:1
	v_add_f32_dpp v128, v128, v128 row_shr:1 row_mask:0xf bank_mask:0xf bound_ctrl:1
	v_add_f32_dpp v132, v121, v121 row_shr:1 row_mask:0xf bank_mask:0xf bound_ctrl:1
	v_add_f32_dpp v121, v129, v132 row_shl:15 row_mask:0xf bank_mask:0xf bound_ctrl:1
	v_add_f32_dpp v129, v129, v129 row_shr:1 row_mask:0xf bank_mask:0xf bound_ctrl:1
	v_add_f32_dpp v132, v122, v122 row_shr:1 row_mask:0xf bank_mask:0xf bound_ctrl:1
	v_add_f32_dpp v122, v130, v132 row_shl:15 row_mask:0xf bank_mask:0xf bound_ctrl:1
	v_add_f32_dpp v130, v130, v130 row_shr:1 row_mask:0xf bank_mask:0xf bound_ctrl:1
	v_add_f32_dpp v132, v123, v123 row_shr:1 row_mask:0xf bank_mask:0xf bound_ctrl:1
	v_add_f32_dpp v123, v131, v132 row_shl:15 row_mask:0xf bank_mask:0xf bound_ctrl:1
	v_add_f32_dpp v131, v131, v131 row_shr:1 row_mask:0xf bank_mask:0xf bound_ctrl:1
	v_fma_f32 v116, v116, v138, -v108
	v_fma_f32 v117, v117, v138, -v109
	v_fma_f32 v118, v118, v138, -v110
	v_fma_f32 v119, v119, v138, -v111
	v_fma_f32 v120, v120, v138, -v112
	v_fma_f32 v121, v121, v138, -v113
	v_fma_f32 v122, v122, v138, -v114
	v_fma_f32 v123, v123, v138, -v115
	v_cvt_pk_bf16_f32 v134, v116, v117
	v_cvt_pk_bf16_f32 v135, v118, v119
	v_cvt_pk_bf16_f32 v136, v120, v121
	v_cvt_pk_bf16_f32 v137, v122, v123
	s_waitcnt lgkmcnt(0)
	s_nop 0
	v_mfma_f32_16x16x32_bf16 v[76:79], v[44:47], v[134:137], 0
	v_mfma_f32_16x16x32_bf16 v[80:83], v[48:51], v[134:137], 0
	v_mfma_f32_16x16x32_bf16 v[84:87], v[52:55], v[134:137], 0
	v_mfma_f32_16x16x32_bf16 v[88:91], v[56:59], v[134:137], 0
	v_mfma_f32_16x16x32_bf16 v[92:95], v[60:63], v[134:137], 0
	v_mfma_f32_16x16x32_bf16 v[96:99], v[64:67], v[134:137], 0
	v_mfma_f32_16x16x32_bf16 v[100:103], v[68:71], v[134:137], 0
	v_mfma_f32_16x16x32_bf16 v[104:107], v[72:75], v[134:137], 0
	v_add_u32_e32 v147, 0, v144
	ds_read_b128 v[44:47], v147
	ds_read_b128 v[48:51], v147 offset:4096
	ds_read_b128 v[52:55], v147 offset:8192
	ds_read_b128 v[56:59], v147 offset:12288
	ds_read_b128 v[60:63], v147 offset:16384
	ds_read_b128 v[64:67], v147 offset:20480
	ds_read_b128 v[68:71], v147 offset:24576
	ds_read_b128 v[72:75], v147 offset:28672
	s_waitcnt vmcnt(12)
; #define GAS __attribute__((address_space(1)))
; __device__ __forceinline__ void unpack8(const v4u w, float (&f)[8]) { f[0] = bf_lo(w.x); f[1] = bf_hi(w.x); f[2] = bf_lo(w.y); f[3] = bf_hi(w.y); f[4] = bf_lo(w.z); f[5] = bf_hi(w.z); f[6] = bf_lo(w.w); f[7] = bf_hi(w.w); }
; __device__ __forceinline__ v4u pack8(const float (&f)[8]) { v4u w; w.x = cvt_pk_bf16(f[0], f[1]); w.y = cvt_pk_bf16(f[2], f[3]); w.z = cvt_pk_bf16(f[4], f[5]); w.w = cvt_pk_bf16(f[6], f[7]); return w; }
; template <int W> __device__ __forceinline__ void pool_group(const bf16* zrow  , const bf16* pw  , bf16* orow  , int pos, bool prev_ok) {
;     ...
;     for (int kk = 0; kk < 4; ++kk) {
;         if (kk < 3) {
; #pragma unroll
;             for (int dt = 0; dt < 8; ++dt) aw[(kk + 1) & 1][dt] = *(const GAS v4u*)(pw + (size_t)16 * dt * 128 + 32 * (kk + 1)); }
;         float own[8], c[8], p[8];
;         unpack8(cw[kk], own); unpack8(pv[kk], p);
; #pragma unroll
;         for (int j = 0; j < 8; ++j) c[j] = own[j];
;         win_step<1>(c, p);
;         if (W >= 4) win_step<2>(c, p);
;         if (W >= 8) win_step<4>(c, p);
;         if (W >= 16) win_step<8>(c, p);
;         float pl[8];
; #pragma unroll
;         for (int j = 0; j < 8; ++j) pl[j] = c[j] * inv - own[j];
;         const v4u pwk = pack8(pl); const bf16x8 pf = __builtin_bit_cast(bf16x8, pwk);
; #pragma unroll
;         for (int dt = 0; dt < 8; ++dt) acc[dt] = __builtin_amdgcn_mfma_f32_16x16x32_bf16(__builtin_bit_cast(bf16x8, aw[kk & 1][dt]), pf, acc[dt], 0, 0, 0);
	v_lshlrev_b32_e32 v108, 16, v20
	v_and_b32_e32 v109, 0xffff0000, v20
	v_lshlrev_b32_e32 v110, 16, v21
	v_and_b32_e32 v111, 0xffff0000, v21
	v_lshlrev_b32_e32 v112, 16, v22
	v_and_b32_e32 v113, 0xffff0000, v22
	v_lshlrev_b32_e32 v114, 16, v23
	v_and_b32_e32 v115, 0xffff0000, v23
	v_lshlrev_b32_e32 v124, 16, v24
	v_and_b32_e32 v125, 0xffff0000, v24
	v_lshlrev_b32_e32 v126, 16, v25
	v_and_b32_e32 v127, 0xffff0000, v25
	v_lshlrev_b32_e32 v128, 16, v26
	v_and_b32_e32 v129, 0xffff0000, v26
	v_lshlrev_b32_e32 v130, 16, v27
	v_and_b32_e32 v131, 0xffff0000, v27
	v_cndmask_b32_e64 v124, 0, v124, s[40:41]
	v_cndmask_b32_e64 v125, 0, v125, s[40:41]
	v_cndmask_b32_e64 v126, 0, v126, s[40:41]
	v_cndmask_b32_e64 v127, 0, v127, s[40:41]
	v_cndmask_b32_e64 v128, 0, v128, s[40:41]
	v_cndmask_b32_e64 v129, 0, v129, s[40:41]
	v_cndmask_b32_e64 v130, 0, v130, s[40:41]
	v_cndmask_b32_e64 v131, 0, v131, s[40:41]
	global_load_dwordx4 v[20:23], v11, s[38:39] offset:320
	global_load_dwordx4 v[24:27], v11, s[48:49] offset:320
	v_mov_b32_e32 v116, v108
	v_mov_b32_e32 v117, v109
	v_mov_b32_e32 v118, v110
	v_mov_b32_e32 v119, v111
	v_mov_b32_e32 v120, v112
	v_mov_b32_e32 v121, v113
	v_mov_b32_e32 v122, v114
	v_mov_b32_e32 v123, v115
	v_add_f32_dpp v132, v116, v116 row_shr:1 row_mask:0xf bank_mask:0xf bound_ctrl:1
	v_add_f32_dpp v116, v124, v132 row_shl:15 row_mask:0xf bank_mask:0xf bound_ctrl:1
	v_add_f32_dpp v124, v124, v124 row_shr:1 row_mask:0xf bank_mask:0xf bound_ctrl:1
	v_add_f32_dpp v132, v117, v117 row_shr:1 row_mask:0xf bank_mask:0xf bound_ctrl:1
	v_add_f32_dpp v117, v125, v132 row_shl:15 row_mask:0xf bank_mask:0xf bound_ctrl:1
	v_add_f32_dpp v125, v125, v125 row_shr:1 row_mask:0xf bank_mask:0xf bound_ctrl:1
	v_add_f32_dpp v132, v118, v118 row_shr:1 row_mask:0xf bank_mask:0xf bound_ctrl:1
	v_add_f32_dpp v118, v126, v132 row_shl:15 row_mask:0xf bank_mask:0xf bound_ctrl:1
	v_add_f32_dpp v126, v126, v126 row_shr:1 row_mask:0xf bank_mask:0xf bound_ctrl:1
	v_add_f32_dpp v132, v119, v119 row_shr:1 row_mask:0xf bank_mask:0xf bound_ctrl:1
	v_add_f32_dpp v119, v127, v132 row_shl:15 row_mask:0xf bank_mask:0xf bound_ctrl:1
	v_add_f32_dpp v127, v127, v127 row_shr:1 row_mask:0xf bank_mask:0xf bound_ctrl:1
	v_add_f32_dpp v132, v120, v120 row_shr:1 row_mask:0xf bank_mask:0xf bound_ctrl:1
	v_add_f32_dpp v120, v128, v132 row_shl:15 row_mask:0xf bank_mask:0xf bound_ctrl:1
	v_add_f32_dpp v128, v128, v128 row_shr:1 row_mask:0xf bank_mask:0xf bound_ctrl:1
	v_add_f32_dpp v132, v121, v121 row_shr:1 row_mask:0xf bank_mask:0xf bound_ctrl:1
	v_add_f32_dpp v121, v129, v132 row_shl:15 row_mask:0xf bank_mask:0xf bound_ctrl:1
	v_add_f32_dpp v129, v129, v129 row_shr:1 row_mask:0xf bank_mask:0xf bound_ctrl:1
	v_add_f32_dpp v132, v122, v122 row_shr:1 row_mask:0xf bank_mask:0xf bound_ctrl:1
	v_add_f32_dpp v122, v130, v132 row_shl:15 row_mask:0xf bank_mask:0xf bound_ctrl:1
	v_add_f32_dpp v130, v130, v130 row_shr:1 row_mask:0xf bank_mask:0xf bound_ctrl:1
	v_add_f32_dpp v132, v123, v123 row_shr:1 row_mask:0xf bank_mask:0xf bound_ctrl:1
	v_add_f32_dpp v123, v131, v132 row_shl:15 row_mask:0xf bank_mask:0xf bound_ctrl:1
	v_add_f32_dpp v131, v131, v131 row_shr:1 row_mask:0xf bank_mask:0xf bound_ctrl:1
	v_fma_f32 v116, v116, v138, -v108
	v_fma_f32 v117, v117, v138, -v109
	v_fma_f32 v118, v118, v138, -v110
	v_fma_f32 v119, v119, v138, -v111
	v_fma_f32 v120, v120, v138, -v112
	v_fma_f32 v121, v121, v138, -v113
	v_fma_f32 v122, v122, v138, -v114
	v_fma_f32 v123, v123, v138, -v115
	v_cvt_pk_bf16_f32 v134, v116, v117
	v_cvt_pk_bf16_f32 v135, v118, v119
	v_cvt_pk_bf16_f32 v136, v120, v121
	v_cvt_pk_bf16_f32 v137, v122, v123
	s_waitcnt lgkmcnt(0)
	s_nop 0
	v_mfma_f32_16x16x32_bf16 v[76:79], v[44:47], v[134:137], v[76:79]
	v_mfma_f32_16x16x32_bf16 v[80:83], v[48:51], v[134:137], v[80:83]
	v_mfma_f32_16x16x32_bf16 v[84:87], v[52:55], v[134:137], v[84:87]
	v_mfma_f32_16x16x32_bf16 v[88:91], v[56:59], v[134:137], v[88:91]
	v_mfma_f32_16x16x32_bf16 v[92:95], v[60:63], v[134:137], v[92:95]
	v_mfma_f32_16x16x32_bf16 v[96:99], v[64:67], v[134:137], v[96:99]
	v_mfma_f32_16x16x32_bf16 v[100:103], v[68:71], v[134:137], v[100:103]
	v_mfma_f32_16x16x32_bf16 v[104:107], v[72:75], v[134:137], v[104:107]
	v_add_u32_e32 v147, 0, v145
	ds_read_b128 v[44:47], v147
	ds_read_b128 v[48:51], v147 offset:4096
	ds_read_b128 v[52:55], v147 offset:8192
	ds_read_b128 v[56:59], v147 offset:12288
	ds_read_b128 v[60:63], v147 offset:16384
	ds_read_b128 v[64:67], v147 offset:20480
	ds_read_b128 v[68:71], v147 offset:24576
	ds_read_b128 v[72:75], v147 offset:28672
	s_waitcnt vmcnt(10)
; #define GAS __attribute__((address_space(1)))
; __device__ __forceinline__ void unpack8(const v4u w, float (&f)[8]) { f[0] = bf_lo(w.x); f[1] = bf_hi(w.x); f[2] = bf_lo(w.y); f[3] = bf_hi(w.y); f[4] = bf_lo(w.z); f[5] = bf_hi(w.z); f[6] = bf_lo(w.w); f[7] = bf_hi(w.w); }
; __device__ __forceinline__ v4u pack8(const float (&f)[8]) { v4u w; w.x = cvt_pk_bf16(f[0], f[1]); w.y = cvt_pk_bf16(f[2], f[3]); w.z = cvt_pk_bf16(f[4], f[5]); w.w = cvt_pk_bf16(f[6], f[7]); return w; }
; template <int W> __device__ __forceinline__ void pool_group(const bf16* zrow  , const bf16* pw  , bf16* orow  , int pos, bool prev_ok) {
;     ...
;     for (int kk = 0; kk < 4; ++kk) {
;         if (kk < 3) {
; #pragma unroll
;             for (int dt = 0; dt < 8; ++dt) aw[(kk + 1) & 1][dt] = *(const GAS v4u*)(pw + (size_t)16 * dt * 128 + 32 * (kk + 1)); }
;         float own[8], c[8], p[8];
;         unpack8(cw[kk], own); unpack8(pv[kk], p);
; #pragma unroll
;         for (int j = 0; j < 8; ++j) c[j] = own[j];
;         win_step<1>(c, p);
;         if (W >= 4) win_step<2>(c, p);
;         if (W >= 8) win_step<4>(c, p);
;         if (W >= 16) win_step<8>(c, p);
;         float pl[8];
; #pragma unroll
;         for (int j = 0; j < 8; ++j) pl[j] = c[j] * inv - own[j];
;         const v4u pwk = pack8(pl); const bf16x8 pf = __builtin_bit_cast(bf16x8, pwk);
; #pragma unroll
;         for (int dt = 0; dt < 8; ++dt) acc[dt] = __builtin_amdgcn_mfma_f32_16x16x32_bf16(__builtin_bit_cast(bf16x8, aw[kk & 1][dt]), pf, acc[dt], 0, 0, 0);
	v_lshlrev_b32_e32 v108, 16, v28
	v_and_b32_e32 v109, 0xffff0000, v28
	v_lshlrev_b32_e32 v110, 16, v29
	v_and_b32_e32 v111, 0xffff0000, v29
	v_lshlrev_b32_e32 v112, 16, v30
	v_and_b32_e32 v113, 0xffff0000, v30
	v_lshlrev_b32_e32 v114, 16, v31
	v_and_b32_e32 v115, 0xffff0000, v31
	v_lshlrev_b32_e32 v124, 16, v32
	v_and_b32_e32 v125, 0xffff0000, v32
	v_lshlrev_b32_e32 v126, 16, v33
	v_and_b32_e32 v127, 0xffff0000, v33
	v_lshlrev_b32_e32 v128, 16, v34
	v_and_b32_e32 v129, 0xffff0000, v34
	v_lshlrev_b32_e32 v130, 16, v35
	v_and_b32_e32 v131, 0xffff0000, v35
	v_cndmask_b32_e64 v124, 0, v124, s[40:41]
	v_cndmask_b32_e64 v125, 0, v125, s[40:41]
	v_cndmask_b32_e64 v126, 0, v126, s[40:41]
	v_cndmask_b32_e64 v127, 0, v127, s[40:41]
	v_cndmask_b32_e64 v128, 0, v128, s[40:41]
	v_cndmask_b32_e64 v129, 0, v129, s[40:41]
	v_cndmask_b32_e64 v130, 0, v130, s[40:41]
	v_cndmask_b32_e64 v131, 0, v131, s[40:41]
	global_load_dwordx4 v[28:31], v11, s[38:39] offset:384
	global_load_dwordx4 v[32:35], v11, s[48:49] offset:384
	v_mov_b32_e32 v116, v108
	v_mov_b32_e32 v117, v109
	v_mov_b32_e32 v118, v110
	v_mov_b32_e32 v119, v111
	v_mov_b32_e32 v120, v112
	v_mov_b32_e32 v121, v113
	v_mov_b32_e32 v122, v114
	v_mov_b32_e32 v123, v115
	v_add_f32_dpp v132, v116, v116 row_shr:1 row_mask:0xf bank_mask:0xf bound_ctrl:1
	v_add_f32_dpp v116, v124, v132 row_shl:15 row_mask:0xf bank_mask:0xf bound_ctrl:1
	v_add_f32_dpp v124, v124, v124 row_shr:1 row_mask:0xf bank_mask:0xf bound_ctrl:1
	v_add_f32_dpp v132, v117, v117 row_shr:1 row_mask:0xf bank_mask:0xf bound_ctrl:1
	v_add_f32_dpp v117, v125, v132 row_shl:15 row_mask:0xf bank_mask:0xf bound_ctrl:1
	v_add_f32_dpp v125, v125, v125 row_shr:1 row_mask:0xf bank_mask:0xf bound_ctrl:1
	v_add_f32_dpp v132, v118, v118 row_shr:1 row_mask:0xf bank_mask:0xf bound_ctrl:1
	v_add_f32_dpp v118, v126, v132 row_shl:15 row_mask:0xf bank_mask:0xf bound_ctrl:1
	v_add_f32_dpp v126, v126, v126 row_shr:1 row_mask:0xf bank_mask:0xf bound_ctrl:1
	v_add_f32_dpp v132, v119, v119 row_shr:1 row_mask:0xf bank_mask:0xf bound_ctrl:1
	v_add_f32_dpp v119, v127, v132 row_shl:15 row_mask:0xf bank_mask:0xf bound_ctrl:1
	v_add_f32_dpp v127, v127, v127 row_shr:1 row_mask:0xf bank_mask:0xf bound_ctrl:1
	v_add_f32_dpp v132, v120, v120 row_shr:1 row_mask:0xf bank_mask:0xf bound_ctrl:1
	v_add_f32_dpp v120, v128, v132 row_shl:15 row_mask:0xf bank_mask:0xf bound_ctrl:1
	v_add_f32_dpp v128, v128, v128 row_shr:1 row_mask:0xf bank_mask:0xf bound_ctrl:1
	v_add_f32_dpp v132, v121, v121 row_shr:1 row_mask:0xf bank_mask:0xf bound_ctrl:1
	v_add_f32_dpp v121, v129, v132 row_shl:15 row_mask:0xf bank_mask:0xf bound_ctrl:1
	v_add_f32_dpp v129, v129, v129 row_shr:1 row_mask:0xf bank_mask:0xf bound_ctrl:1
	v_add_f32_dpp v132, v122, v122 row_shr:1 row_mask:0xf bank_mask:0xf bound_ctrl:1
	v_add_f32_dpp v122, v130, v132 row_shl:15 row_mask:0xf bank_mask:0xf bound_ctrl:1
	v_add_f32_dpp v130, v130, v130 row_shr:1 row_mask:0xf bank_mask:0xf bound_ctrl:1
	v_add_f32_dpp v132, v123, v123 row_shr:1 row_mask:0xf bank_mask:0xf bound_ctrl:1
	v_add_f32_dpp v123, v131, v132 row_shl:15 row_mask:0xf bank_mask:0xf bound_ctrl:1
	v_add_f32_dpp v131, v131, v131 row_shr:1 row_mask:0xf bank_mask:0xf bound_ctrl:1
	v_fma_f32 v116, v116, v138, -v108
	v_fma_f32 v117, v117, v138, -v109
	v_fma_f32 v118, v118, v138, -v110
	v_fma_f32 v119, v119, v138, -v111
	v_fma_f32 v120, v120, v138, -v112
	v_fma_f32 v121, v121, v138, -v113
	v_fma_f32 v122, v122, v138, -v114
	v_fma_f32 v123, v123, v138, -v115
	v_cvt_pk_bf16_f32 v134, v116, v117
	v_cvt_pk_bf16_f32 v135, v118, v119
	v_cvt_pk_bf16_f32 v136, v120, v121
	v_cvt_pk_bf16_f32 v137, v122, v123
	s_waitcnt lgkmcnt(0)
	s_nop 0
	v_mfma_f32_16x16x32_bf16 v[76:79], v[44:47], v[134:137], v[76:79]
	v_mfma_f32_16x16x32_bf16 v[80:83], v[48:51], v[134:137], v[80:83]
	v_mfma_f32_16x16x32_bf16 v[84:87], v[52:55], v[134:137], v[84:87]
	v_mfma_f32_16x16x32_bf16 v[88:91], v[56:59], v[134:137], v[88:91]
	v_mfma_f32_16x16x32_bf16 v[92:95], v[60:63], v[134:137], v[92:95]
	v_mfma_f32_16x16x32_bf16 v[96:99], v[64:67], v[134:137], v[96:99]
	v_mfma_f32_16x16x32_bf16 v[100:103], v[68:71], v[134:137], v[100:103]
	v_mfma_f32_16x16x32_bf16 v[104:107], v[72:75], v[134:137], v[104:107]
	v_add_u32_e32 v147, 0, v146
	ds_read_b128 v[44:47], v147
	ds_read_b128 v[48:51], v147 offset:4096
	ds_read_b128 v[52:55], v147 offset:8192
	ds_read_b128 v[56:59], v147 offset:12288
	ds_read_b128 v[60:63], v147 offset:16384
	ds_read_b128 v[64:67], v147 offset:20480
	ds_read_b128 v[68:71], v147 offset:24576
	ds_read_b128 v[72:75], v147 offset:28672
	s_waitcnt vmcnt(8)
; __device__ __forceinline__ unsigned cvt_pk_bf16(float lo, float hi) { return __builtin_bit_cast(unsigned, __builtin_convertvector((f32x2_t){lo, hi}, bf16x2_t)); }
; #define GAS __attribute__((address_space(1)))
; __device__ __forceinline__ void unpack8(const v4u w, float (&f)[8]) { f[0] = bf_lo(w.x); f[1] = bf_hi(w.x); f[2] = bf_lo(w.y); f[3] = bf_hi(w.y); f[4] = bf_lo(w.z); f[5] = bf_hi(w.z); f[6] = bf_lo(w.w); f[7] = bf_hi(w.w); }
; __device__ __forceinline__ v4u pack8(const float (&f)[8]) { v4u w; w.x = cvt_pk_bf16(f[0], f[1]); w.y = cvt_pk_bf16(f[2], f[3]); w.z = cvt_pk_bf16(f[4], f[5]); w.w = cvt_pk_bf16(f[6], f[7]); return w; }
; template <int W> __device__ __forceinline__ void pool_group(const bf16* zrow  , const bf16* pw  , bf16* orow  , int pos, bool prev_ok) {
;     ...
;     for (int kk = 0; kk < 4; ++kk) {
;         if (kk < 3) {
; #pragma unroll
;             for (int dt = 0; dt < 8; ++dt) aw[(kk + 1) & 1][dt] = *(const GAS v4u*)(pw + (size_t)16 * dt * 128 + 32 * (kk + 1)); }
;         float own[8], c[8], p[8];
;         unpack8(cw[kk], own); unpack8(pv[kk], p);
; #pragma unroll
;         for (int j = 0; j < 8; ++j) c[j] = own[j];
;         win_step<1>(c, p);
;         if (W >= 4) win_step<2>(c, p);
;         if (W >= 8) win_step<4>(c, p);
;         if (W >= 16) win_step<8>(c, p);
;         float pl[8];
; #pragma unroll
;         for (int j = 0; j < 8; ++j) pl[j] = c[j] * inv - own[j];
;         const v4u pwk = pack8(pl); const bf16x8 pf = __builtin_bit_cast(bf16x8, pwk);
; #pragma unroll
;         for (int dt = 0; dt < 8; ++dt) acc[dt] = __builtin_amdgcn_mfma_f32_16x16x32_bf16(__builtin_bit_cast(bf16x8, aw[kk & 1][dt]), pf, acc[dt], 0, 0, 0);
;     }
; #pragma unroll
;     for (int dt = 0; dt < 8; ++dt) { v2u w; w.x = cvt_pk_bf16(acc[dt][0], acc[dt][1]); w.y = cvt_pk_bf16(acc[dt][2], acc[dt][3]); *(GAS v2u*)(orow + 16 * dt) = w; }
; }
; __device__ __forceinline__ void mixer_pool(const Frame& F, int l, int chunk, const bf16* Z, bf16* MIX) {
;     ...
;     pool_group<2>(zrow, pwt, orow, pos, prev_ok);
;     pool_group<4>(zrow + 128, pwt + 128 * 128, orow + 128, pos, prev_ok);
	v_lshlrev_b32_e32 v108, 16, v36
	v_and_b32_e32 v109, 0xffff0000, v36
	v_lshlrev_b32_e32 v110, 16, v37
	v_and_b32_e32 v111, 0xffff0000, v37
	v_lshlrev_b32_e32 v112, 16, v38
	v_and_b32_e32 v113, 0xffff0000, v38
	v_lshlrev_b32_e32 v114, 16, v39
	v_and_b32_e32 v115, 0xffff0000, v39
	v_lshlrev_b32_e32 v124, 16, v40
	v_and_b32_e32 v125, 0xffff0000, v40
	v_lshlrev_b32_e32 v126, 16, v41
	v_and_b32_e32 v127, 0xffff0000, v41
	v_lshlrev_b32_e32 v128, 16, v42
	v_and_b32_e32 v129, 0xffff0000, v42
	v_lshlrev_b32_e32 v130, 16, v43
	v_and_b32_e32 v131, 0xffff0000, v43
	v_cndmask_b32_e64 v124, 0, v124, s[40:41]
	v_cndmask_b32_e64 v125, 0, v125, s[40:41]
	v_cndmask_b32_e64 v126, 0, v126, s[40:41]
	v_cndmask_b32_e64 v127, 0, v127, s[40:41]
	v_cndmask_b32_e64 v128, 0, v128, s[40:41]
	v_cndmask_b32_e64 v129, 0, v129, s[40:41]
	v_cndmask_b32_e64 v130, 0, v130, s[40:41]
	v_cndmask_b32_e64 v131, 0, v131, s[40:41]
	global_load_dwordx4 v[36:39], v11, s[38:39] offset:448
	global_load_dwordx4 v[40:43], v11, s[48:49] offset:448
	v_mov_b32_e32 v116, v108
	v_mov_b32_e32 v117, v109
	v_mov_b32_e32 v118, v110
	v_mov_b32_e32 v119, v111
	v_mov_b32_e32 v120, v112
	v_mov_b32_e32 v121, v113
	v_mov_b32_e32 v122, v114
	v_mov_b32_e32 v123, v115
	v_add_f32_dpp v132, v116, v116 row_shr:1 row_mask:0xf bank_mask:0xf bound_ctrl:1
	v_add_f32_dpp v116, v124, v132 row_shl:15 row_mask:0xf bank_mask:0xf bound_ctrl:1
	v_add_f32_dpp v124, v124, v124 row_shr:1 row_mask:0xf bank_mask:0xf bound_ctrl:1
	v_add_f32_dpp v132, v117, v117 row_shr:1 row_mask:0xf bank_mask:0xf bound_ctrl:1
	v_add_f32_dpp v117, v125, v132 row_shl:15 row_mask:0xf bank_mask:0xf bound_ctrl:1
	v_add_f32_dpp v125, v125, v125 row_shr:1 row_mask:0xf bank_mask:0xf bound_ctrl:1
	v_add_f32_dpp v132, v118, v118 row_shr:1 row_mask:0xf bank_mask:0xf bound_ctrl:1
	v_add_f32_dpp v118, v126, v132 row_shl:15 row_mask:0xf bank_mask:0xf bound_ctrl:1
	v_add_f32_dpp v126, v126, v126 row_shr:1 row_mask:0xf bank_mask:0xf bound_ctrl:1
	v_add_f32_dpp v132, v119, v119 row_shr:1 row_mask:0xf bank_mask:0xf bound_ctrl:1
	v_add_f32_dpp v119, v127, v132 row_shl:15 row_mask:0xf bank_mask:0xf bound_ctrl:1
	v_add_f32_dpp v127, v127, v127 row_shr:1 row_mask:0xf bank_mask:0xf bound_ctrl:1
	v_add_f32_dpp v132, v120, v120 row_shr:1 row_mask:0xf bank_mask:0xf bound_ctrl:1
	v_add_f32_dpp v120, v128, v132 row_shl:15 row_mask:0xf bank_mask:0xf bound_ctrl:1
	v_add_f32_dpp v128, v128, v128 row_shr:1 row_mask:0xf bank_mask:0xf bound_ctrl:1
	v_add_f32_dpp v132, v121, v121 row_shr:1 row_mask:0xf bank_mask:0xf bound_ctrl:1
	v_add_f32_dpp v121, v129, v132 row_shl:15 row_mask:0xf bank_mask:0xf bound_ctrl:1
	v_add_f32_dpp v129, v129, v129 row_shr:1 row_mask:0xf bank_mask:0xf bound_ctrl:1
	v_add_f32_dpp v132, v122, v122 row_shr:1 row_mask:0xf bank_mask:0xf bound_ctrl:1
	v_add_f32_dpp v122, v130, v132 row_shl:15 row_mask:0xf bank_mask:0xf bound_ctrl:1
	v_add_f32_dpp v130, v130, v130 row_shr:1 row_mask:0xf bank_mask:0xf bound_ctrl:1
	v_add_f32_dpp v132, v123, v123 row_shr:1 row_mask:0xf bank_mask:0xf bound_ctrl:1
	v_add_f32_dpp v123, v131, v132 row_shl:15 row_mask:0xf bank_mask:0xf bound_ctrl:1
	v_add_f32_dpp v131, v131, v131 row_shr:1 row_mask:0xf bank_mask:0xf bound_ctrl:1
	v_fma_f32 v116, v116, v138, -v108
	v_fma_f32 v117, v117, v138, -v109
	v_fma_f32 v118, v118, v138, -v110
	v_fma_f32 v119, v119, v138, -v111
	v_fma_f32 v120, v120, v138, -v112
	v_fma_f32 v121, v121, v138, -v113
	v_fma_f32 v122, v122, v138, -v114
	v_fma_f32 v123, v123, v138, -v115
	v_cvt_pk_bf16_f32 v134, v116, v117
	v_cvt_pk_bf16_f32 v135, v118, v119
	v_cvt_pk_bf16_f32 v136, v120, v121
	v_cvt_pk_bf16_f32 v137, v122, v123
	s_waitcnt lgkmcnt(0)
	s_nop 0
	v_mfma_f32_16x16x32_bf16 v[76:79], v[44:47], v[134:137], v[76:79]
	v_mfma_f32_16x16x32_bf16 v[80:83], v[48:51], v[134:137], v[80:83]
	v_mfma_f32_16x16x32_bf16 v[84:87], v[52:55], v[134:137], v[84:87]
	v_mfma_f32_16x16x32_bf16 v[88:91], v[56:59], v[134:137], v[88:91]
	v_mfma_f32_16x16x32_bf16 v[92:95], v[60:63], v[134:137], v[92:95]
	v_mfma_f32_16x16x32_bf16 v[96:99], v[64:67], v[134:137], v[96:99]
	v_mfma_f32_16x16x32_bf16 v[100:103], v[68:71], v[134:137], v[100:103]
	v_mfma_f32_16x16x32_bf16 v[104:107], v[72:75], v[134:137], v[104:107]
	s_nop 7
	s_nop 1
	v_cvt_pk_bf16_f32 v132, v76, v77
	v_cvt_pk_bf16_f32 v133, v78, v79
	global_store_dwordx2 v142, v[132:133], s[46:47] offset:0
	s_nop 0
	v_cvt_pk_bf16_f32 v132, v80, v81
	v_cvt_pk_bf16_f32 v133, v82, v83
	global_store_dwordx2 v142, v[132:133], s[46:47] offset:32
	s_nop 0
	v_cvt_pk_bf16_f32 v132, v84, v85
	v_cvt_pk_bf16_f32 v133, v86, v87
	global_store_dwordx2 v142, v[132:133], s[46:47] offset:64
	s_nop 0
	v_cvt_pk_bf16_f32 v132, v88, v89
	v_cvt_pk_bf16_f32 v133, v90, v91
	global_store_dwordx2 v142, v[132:133], s[46:47] offset:96
	s_nop 0
	v_cvt_pk_bf16_f32 v132, v92, v93
	v_cvt_pk_bf16_f32 v133, v94, v95
	global_store_dwordx2 v142, v[132:133], s[46:47] offset:128
	s_nop 0
	v_cvt_pk_bf16_f32 v132, v96, v97
	v_cvt_pk_bf16_f32 v133, v98, v99
	global_store_dwordx2 v142, v[132:133], s[46:47] offset:160
	s_nop 0
	v_cvt_pk_bf16_f32 v132, v100, v101
	v_cvt_pk_bf16_f32 v133, v102, v103
	global_store_dwordx2 v142, v[132:133], s[46:47] offset:192
	s_nop 0
	v_cvt_pk_bf16_f32 v132, v104, v105
	v_cvt_pk_bf16_f32 v133, v106, v107
	global_store_dwordx2 v142, v[132:133], s[46:47] offset:224
	s_nop 0
	v_min_i32_e32 v139, 4, v140
	v_cvt_f32_i32_e32 v139, v139
	v_div_scale_f32 v1, s[42:43], v139, v139, 1.0
	v_rcp_f32_e32 v2, v1
	s_nop 0
	v_fma_f32 v7, -v1, v2, 1.0
	v_fmac_f32_e32 v2, v7, v2
	v_div_scale_f32 v3, vcc, 1.0, v139, 1.0
	v_mul_f32_e32 v6, v3, v2
	v_fma_f32 v7, -v1, v6, v3
	v_fmac_f32_e32 v6, v7, v2
	v_fma_f32 v1, -v1, v6, v3
	s_nop 1
	v_div_fmas_f32 v1, v1, v2, v6
	v_div_fixup_f32 v138, v1, v139, 1.0
	v_add_u32_e32 v147, 32768, v143
	ds_read_b128 v[44:47], v147
	ds_read_b128 v[48:51], v147 offset:4096
	ds_read_b128 v[52:55], v147 offset:8192
	ds_read_b128 v[56:59], v147 offset:12288
	ds_read_b128 v[60:63], v147 offset:16384
	ds_read_b128 v[64:67], v147 offset:20480
	ds_read_b128 v[68:71], v147 offset:24576
	ds_read_b128 v[72:75], v147 offset:28672
	s_waitcnt vmcnt(14)
; #define GAS __attribute__((address_space(1)))
; __device__ __forceinline__ void unpack8(const v4u w, float (&f)[8]) { f[0] = bf_lo(w.x); f[1] = bf_hi(w.x); f[2] = bf_lo(w.y); f[3] = bf_hi(w.y); f[4] = bf_lo(w.z); f[5] = bf_hi(w.z); f[6] = bf_lo(w.w); f[7] = bf_hi(w.w); }
; __device__ __forceinline__ v4u pack8(const float (&f)[8]) { v4u w; w.x = cvt_pk_bf16(f[0], f[1]); w.y = cvt_pk_bf16(f[2], f[3]); w.z = cvt_pk_bf16(f[4], f[5]); w.w = cvt_pk_bf16(f[6], f[7]); return w; }
; template <int W> __device__ __forceinline__ void pool_group(const bf16* zrow  , const bf16* pw  , bf16* orow  , int pos, bool prev_ok) {
;     ...
;     for (int kk = 0; kk < 4; ++kk) {
;         if (kk < 3) {
; #pragma unroll
;             for (int dt = 0; dt < 8; ++dt) aw[(kk + 1) & 1][dt] = *(const GAS v4u*)(pw + (size_t)16 * dt * 128 + 32 * (kk + 1)); }
;         float own[8], c[8], p[8];
;         unpack8(cw[kk], own); unpack8(pv[kk], p);
; #pragma unroll
;         for (int j = 0; j < 8; ++j) c[j] = own[j];
;         win_step<1>(c, p);
;         if (W >= 4) win_step<2>(c, p);
;         if (W >= 8) win_step<4>(c, p);
;         if (W >= 16) win_step<8>(c, p);
;         float pl[8];
; #pragma unroll
;         for (int j = 0; j < 8; ++j) pl[j] = c[j] * inv - own[j];
;         const v4u pwk = pack8(pl); const bf16x8 pf = __builtin_bit_cast(bf16x8, pwk);
; #pragma unroll
;         for (int dt = 0; dt < 8; ++dt) acc[dt] = __builtin_amdgcn_mfma_f32_16x16x32_bf16(__builtin_bit_cast(bf16x8, aw[kk & 1][dt]), pf, acc[dt], 0, 0, 0);
	v_lshlrev_b32_e32 v108, 16, v12
	v_and_b32_e32 v109, 0xffff0000, v12
	v_lshlrev_b32_e32 v110, 16, v13
	v_and_b32_e32 v111, 0xffff0000, v13
	v_lshlrev_b32_e32 v112, 16, v14
	v_and_b32_e32 v113, 0xffff0000, v14
	v_lshlrev_b32_e32 v114, 16, v15
	v_and_b32_e32 v115, 0xffff0000, v15
	v_lshlrev_b32_e32 v124, 16, v16
	v_and_b32_e32 v125, 0xffff0000, v16
	v_lshlrev_b32_e32 v126, 16, v17
	v_and_b32_e32 v127, 0xffff0000, v17
	v_lshlrev_b32_e32 v128, 16, v18
	v_and_b32_e32 v129, 0xffff0000, v18
	v_lshlrev_b32_e32 v130, 16, v19
	v_and_b32_e32 v131, 0xffff0000, v19
	v_cndmask_b32_e64 v124, 0, v124, s[40:41]
	v_cndmask_b32_e64 v125, 0, v125, s[40:41]
	v_cndmask_b32_e64 v126, 0, v126, s[40:41]
	v_cndmask_b32_e64 v127, 0, v127, s[40:41]
	v_cndmask_b32_e64 v128, 0, v128, s[40:41]
	v_cndmask_b32_e64 v129, 0, v129, s[40:41]
	v_cndmask_b32_e64 v130, 0, v130, s[40:41]
	v_cndmask_b32_e64 v131, 0, v131, s[40:41]
	global_load_dwordx4 v[12:15], v11, s[38:39] offset:512
	global_load_dwordx4 v[16:19], v11, s[48:49] offset:512
	v_mov_b32_e32 v116, v108
	v_mov_b32_e32 v117, v109
	v_mov_b32_e32 v118, v110
	v_mov_b32_e32 v119, v111
	v_mov_b32_e32 v120, v112
	v_mov_b32_e32 v121, v113
	v_mov_b32_e32 v122, v114
	v_mov_b32_e32 v123, v115
	v_add_f32_dpp v132, v116, v116 row_shr:1 row_mask:0xf bank_mask:0xf bound_ctrl:1
	v_add_f32_dpp v116, v124, v132 row_shl:15 row_mask:0xf bank_mask:0xf bound_ctrl:1
	v_add_f32_dpp v124, v124, v124 row_shr:1 row_mask:0xf bank_mask:0xf bound_ctrl:1
	v_add_f32_dpp v132, v117, v117 row_shr:1 row_mask:0xf bank_mask:0xf bound_ctrl:1
	v_add_f32_dpp v117, v125, v132 row_shl:15 row_mask:0xf bank_mask:0xf bound_ctrl:1
	v_add_f32_dpp v125, v125, v125 row_shr:1 row_mask:0xf bank_mask:0xf bound_ctrl:1
	v_add_f32_dpp v132, v118, v118 row_shr:1 row_mask:0xf bank_mask:0xf bound_ctrl:1
	v_add_f32_dpp v118, v126, v132 row_shl:15 row_mask:0xf bank_mask:0xf bound_ctrl:1
	v_add_f32_dpp v126, v126, v126 row_shr:1 row_mask:0xf bank_mask:0xf bound_ctrl:1
	v_add_f32_dpp v132, v119, v119 row_shr:1 row_mask:0xf bank_mask:0xf bound_ctrl:1
	v_add_f32_dpp v119, v127, v132 row_shl:15 row_mask:0xf bank_mask:0xf bound_ctrl:1
	v_add_f32_dpp v127, v127, v127 row_shr:1 row_mask:0xf bank_mask:0xf bound_ctrl:1
	v_add_f32_dpp v132, v120, v120 row_shr:1 row_mask:0xf bank_mask:0xf bound_ctrl:1
	v_add_f32_dpp v120, v128, v132 row_shl:15 row_mask:0xf bank_mask:0xf bound_ctrl:1
	v_add_f32_dpp v128, v128, v128 row_shr:1 row_mask:0xf bank_mask:0xf bound_ctrl:1
	v_add_f32_dpp v132, v121, v121 row_shr:1 row_mask:0xf bank_mask:0xf bound_ctrl:1
	v_add_f32_dpp v121, v129, v132 row_shl:15 row_mask:0xf bank_mask:0xf bound_ctrl:1
	v_add_f32_dpp v129, v129, v129 row_shr:1 row_mask:0xf bank_mask:0xf bound_ctrl:1
	v_add_f32_dpp v132, v122, v122 row_shr:1 row_mask:0xf bank_mask:0xf bound_ctrl:1
	v_add_f32_dpp v122, v130, v132 row_shl:15 row_mask:0xf bank_mask:0xf bound_ctrl:1
	v_add_f32_dpp v130, v130, v130 row_shr:1 row_mask:0xf bank_mask:0xf bound_ctrl:1
	v_add_f32_dpp v132, v123, v123 row_shr:1 row_mask:0xf bank_mask:0xf bound_ctrl:1
	v_add_f32_dpp v123, v131, v132 row_shl:15 row_mask:0xf bank_mask:0xf bound_ctrl:1
	v_add_f32_dpp v131, v131, v131 row_shr:1 row_mask:0xf bank_mask:0xf bound_ctrl:1
	v_add_f32_dpp v132, v116, v116 row_shr:2 row_mask:0xf bank_mask:0xf bound_ctrl:1
	v_add_f32_dpp v116, v124, v132 row_shl:14 row_mask:0xf bank_mask:0xf bound_ctrl:1
	v_add_f32_dpp v124, v124, v124 row_shr:2 row_mask:0xf bank_mask:0xf bound_ctrl:1
	v_add_f32_dpp v132, v117, v117 row_shr:2 row_mask:0xf bank_mask:0xf bound_ctrl:1
	v_add_f32_dpp v117, v125, v132 row_shl:14 row_mask:0xf bank_mask:0xf bound_ctrl:1
	v_add_f32_dpp v125, v125, v125 row_shr:2 row_mask:0xf bank_mask:0xf bound_ctrl:1
	v_add_f32_dpp v132, v118, v118 row_shr:2 row_mask:0xf bank_mask:0xf bound_ctrl:1
	v_add_f32_dpp v118, v126, v132 row_shl:14 row_mask:0xf bank_mask:0xf bound_ctrl:1
	v_add_f32_dpp v126, v126, v126 row_shr:2 row_mask:0xf bank_mask:0xf bound_ctrl:1
	v_add_f32_dpp v132, v119, v119 row_shr:2 row_mask:0xf bank_mask:0xf bound_ctrl:1
	v_add_f32_dpp v119, v127, v132 row_shl:14 row_mask:0xf bank_mask:0xf bound_ctrl:1
	v_add_f32_dpp v127, v127, v127 row_shr:2 row_mask:0xf bank_mask:0xf bound_ctrl:1
	v_add_f32_dpp v132, v120, v120 row_shr:2 row_mask:0xf bank_mask:0xf bound_ctrl:1
	v_add_f32_dpp v120, v128, v132 row_shl:14 row_mask:0xf bank_mask:0xf bound_ctrl:1
	v_add_f32_dpp v128, v128, v128 row_shr:2 row_mask:0xf bank_mask:0xf bound_ctrl:1
	v_add_f32_dpp v132, v121, v121 row_shr:2 row_mask:0xf bank_mask:0xf bound_ctrl:1
	v_add_f32_dpp v121, v129, v132 row_shl:14 row_mask:0xf bank_mask:0xf bound_ctrl:1
	v_add_f32_dpp v129, v129, v129 row_shr:2 row_mask:0xf bank_mask:0xf bound_ctrl:1
	v_add_f32_dpp v132, v122, v122 row_shr:2 row_mask:0xf bank_mask:0xf bound_ctrl:1
	v_add_f32_dpp v122, v130, v132 row_shl:14 row_mask:0xf bank_mask:0xf bound_ctrl:1
	v_add_f32_dpp v130, v130, v130 row_shr:2 row_mask:0xf bank_mask:0xf bound_ctrl:1
	v_add_f32_dpp v132, v123, v123 row_shr:2 row_mask:0xf bank_mask:0xf bound_ctrl:1
	v_add_f32_dpp v123, v131, v132 row_shl:14 row_mask:0xf bank_mask:0xf bound_ctrl:1
	v_add_f32_dpp v131, v131, v131 row_shr:2 row_mask:0xf bank_mask:0xf bound_ctrl:1
	v_fma_f32 v116, v116, v138, -v108
	v_fma_f32 v117, v117, v138, -v109
	v_fma_f32 v118, v118, v138, -v110
	v_fma_f32 v119, v119, v138, -v111
	v_fma_f32 v120, v120, v138, -v112
	v_fma_f32 v121, v121, v138, -v113
	v_fma_f32 v122, v122, v138, -v114
	v_fma_f32 v123, v123, v138, -v115
	v_cvt_pk_bf16_f32 v134, v116, v117
	v_cvt_pk_bf16_f32 v135, v118, v119
	v_cvt_pk_bf16_f32 v136, v120, v121
	v_cvt_pk_bf16_f32 v137, v122, v123
	s_waitcnt lgkmcnt(0)
; #define GAS __attribute__((address_space(1)))
; __device__ __forceinline__ void unpack8(const v4u w, float (&f)[8]) { f[0] = bf_lo(w.x); f[1] = bf_hi(w.x); f[2] = bf_lo(w.y); f[3] = bf_hi(w.y); f[4] = bf_lo(w.z); f[5] = bf_hi(w.z); f[6] = bf_lo(w.w); f[7] = bf_hi(w.w); }
; __device__ __forceinline__ v4u pack8(const float (&f)[8]) { v4u w; w.x = cvt_pk_bf16(f[0], f[1]); w.y = cvt_pk_bf16(f[2], f[3]); w.z = cvt_pk_bf16(f[4], f[5]); w.w = cvt_pk_bf16(f[6], f[7]); return w; }
; template <int W> __device__ __forceinline__ void pool_group(const bf16* zrow  , const bf16* pw  , bf16* orow  , int pos, bool prev_ok) {
;     ...
;     for (int kk = 0; kk < 4; ++kk) {
;         if (kk < 3) {
; #pragma unroll
;             for (int dt = 0; dt < 8; ++dt) aw[(kk + 1) & 1][dt] = *(const GAS v4u*)(pw + (size_t)16 * dt * 128 + 32 * (kk + 1)); }
;         float own[8], c[8], p[8];
;         unpack8(cw[kk], own); unpack8(pv[kk], p);
; #pragma unroll
;         for (int j = 0; j < 8; ++j) c[j] = own[j];
;         win_step<1>(c, p);
;         if (W >= 4) win_step<2>(c, p);
;         if (W >= 8) win_step<4>(c, p);
;         if (W >= 16) win_step<8>(c, p);
;         float pl[8];
; #pragma unroll
;         for (int j = 0; j < 8; ++j) pl[j] = c[j] * inv - own[j];
;         const v4u pwk = pack8(pl); const bf16x8 pf = __builtin_bit_cast(bf16x8, pwk);
; #pragma unroll
;         for (int dt = 0; dt < 8; ++dt) acc[dt] = __builtin_amdgcn_mfma_f32_16x16x32_bf16(__builtin_bit_cast(bf16x8, aw[kk & 1][dt]), pf, acc[dt], 0, 0, 0);
	s_nop 0
	v_mfma_f32_16x16x32_bf16 v[76:79], v[44:47], v[134:137], 0
	v_mfma_f32_16x16x32_bf16 v[80:83], v[48:51], v[134:137], 0
	v_mfma_f32_16x16x32_bf16 v[84:87], v[52:55], v[134:137], 0
	v_mfma_f32_16x16x32_bf16 v[88:91], v[56:59], v[134:137], 0
	v_mfma_f32_16x16x32_bf16 v[92:95], v[60:63], v[134:137], 0
	v_mfma_f32_16x16x32_bf16 v[96:99], v[64:67], v[134:137], 0
	v_mfma_f32_16x16x32_bf16 v[100:103], v[68:71], v[134:137], 0
	v_mfma_f32_16x16x32_bf16 v[104:107], v[72:75], v[134:137], 0
	v_add_u32_e32 v147, 32768, v144
	ds_read_b128 v[44:47], v147
	ds_read_b128 v[48:51], v147 offset:4096
	ds_read_b128 v[52:55], v147 offset:8192
	ds_read_b128 v[56:59], v147 offset:12288
	ds_read_b128 v[60:63], v147 offset:16384
	ds_read_b128 v[64:67], v147 offset:20480
	ds_read_b128 v[68:71], v147 offset:24576
	ds_read_b128 v[72:75], v147 offset:28672
	s_waitcnt vmcnt(14)
	v_lshlrev_b32_e32 v108, 16, v20
	v_and_b32_e32 v109, 0xffff0000, v20
	v_lshlrev_b32_e32 v110, 16, v21
	v_and_b32_e32 v111, 0xffff0000, v21
	v_lshlrev_b32_e32 v112, 16, v22
	v_and_b32_e32 v113, 0xffff0000, v22
	v_lshlrev_b32_e32 v114, 16, v23
	v_and_b32_e32 v115, 0xffff0000, v23
	v_lshlrev_b32_e32 v124, 16, v24
	v_and_b32_e32 v125, 0xffff0000, v24
	v_lshlrev_b32_e32 v126, 16, v25
	v_and_b32_e32 v127, 0xffff0000, v25
	v_lshlrev_b32_e32 v128, 16, v26
	v_and_b32_e32 v129, 0xffff0000, v26
	v_lshlrev_b32_e32 v130, 16, v27
	v_and_b32_e32 v131, 0xffff0000, v27
	v_cndmask_b32_e64 v124, 0, v124, s[40:41]
	v_cndmask_b32_e64 v125, 0, v125, s[40:41]
	v_cndmask_b32_e64 v126, 0, v126, s[40:41]
	v_cndmask_b32_e64 v127, 0, v127, s[40:41]
	v_cndmask_b32_e64 v128, 0, v128, s[40:41]
	v_cndmask_b32_e64 v129, 0, v129, s[40:41]
	v_cndmask_b32_e64 v130, 0, v130, s[40:41]
	v_cndmask_b32_e64 v131, 0, v131, s[40:41]
	global_load_dwordx4 v[20:23], v11, s[38:39] offset:576
	global_load_dwordx4 v[24:27], v11, s[48:49] offset:576
	v_mov_b32_e32 v116, v108
	v_mov_b32_e32 v117, v109
	v_mov_b32_e32 v118, v110
	v_mov_b32_e32 v119, v111
	v_mov_b32_e32 v120, v112
	v_mov_b32_e32 v121, v113
	v_mov_b32_e32 v122, v114
	v_mov_b32_e32 v123, v115
	v_add_f32_dpp v132, v116, v116 row_shr:1 row_mask:0xf bank_mask:0xf bound_ctrl:1
	v_add_f32_dpp v116, v124, v132 row_shl:15 row_mask:0xf bank_mask:0xf bound_ctrl:1
	v_add_f32_dpp v124, v124, v124 row_shr:1 row_mask:0xf bank_mask:0xf bound_ctrl:1
	v_add_f32_dpp v132, v117, v117 row_shr:1 row_mask:0xf bank_mask:0xf bound_ctrl:1
	v_add_f32_dpp v117, v125, v132 row_shl:15 row_mask:0xf bank_mask:0xf bound_ctrl:1
	v_add_f32_dpp v125, v125, v125 row_shr:1 row_mask:0xf bank_mask:0xf bound_ctrl:1
	v_add_f32_dpp v132, v118, v118 row_shr:1 row_mask:0xf bank_mask:0xf bound_ctrl:1
	v_add_f32_dpp v118, v126, v132 row_shl:15 row_mask:0xf bank_mask:0xf bound_ctrl:1
	v_add_f32_dpp v126, v126, v126 row_shr:1 row_mask:0xf bank_mask:0xf bound_ctrl:1
	v_add_f32_dpp v132, v119, v119 row_shr:1 row_mask:0xf bank_mask:0xf bound_ctrl:1
	v_add_f32_dpp v119, v127, v132 row_shl:15 row_mask:0xf bank_mask:0xf bound_ctrl:1
	v_add_f32_dpp v127, v127, v127 row_shr:1 row_mask:0xf bank_mask:0xf bound_ctrl:1
	v_add_f32_dpp v132, v120, v120 row_shr:1 row_mask:0xf bank_mask:0xf bound_ctrl:1
	v_add_f32_dpp v120, v128, v132 row_shl:15 row_mask:0xf bank_mask:0xf bound_ctrl:1
	v_add_f32_dpp v128, v128, v128 row_shr:1 row_mask:0xf bank_mask:0xf bound_ctrl:1
	v_add_f32_dpp v132, v121, v121 row_shr:1 row_mask:0xf bank_mask:0xf bound_ctrl:1
	v_add_f32_dpp v121, v129, v132 row_shl:15 row_mask:0xf bank_mask:0xf bound_ctrl:1
	v_add_f32_dpp v129, v129, v129 row_shr:1 row_mask:0xf bank_mask:0xf bound_ctrl:1
	v_add_f32_dpp v132, v122, v122 row_shr:1 row_mask:0xf bank_mask:0xf bound_ctrl:1
	v_add_f32_dpp v122, v130, v132 row_shl:15 row_mask:0xf bank_mask:0xf bound_ctrl:1
	v_add_f32_dpp v130, v130, v130 row_shr:1 row_mask:0xf bank_mask:0xf bound_ctrl:1
	v_add_f32_dpp v132, v123, v123 row_shr:1 row_mask:0xf bank_mask:0xf bound_ctrl:1
	v_add_f32_dpp v123, v131, v132 row_shl:15 row_mask:0xf bank_mask:0xf bound_ctrl:1
	v_add_f32_dpp v131, v131, v131 row_shr:1 row_mask:0xf bank_mask:0xf bound_ctrl:1
	v_add_f32_dpp v132, v116, v116 row_shr:2 row_mask:0xf bank_mask:0xf bound_ctrl:1
	v_add_f32_dpp v116, v124, v132 row_shl:14 row_mask:0xf bank_mask:0xf bound_ctrl:1
	v_add_f32_dpp v124, v124, v124 row_shr:2 row_mask:0xf bank_mask:0xf bound_ctrl:1
	v_add_f32_dpp v132, v117, v117 row_shr:2 row_mask:0xf bank_mask:0xf bound_ctrl:1
	v_add_f32_dpp v117, v125, v132 row_shl:14 row_mask:0xf bank_mask:0xf bound_ctrl:1
	v_add_f32_dpp v125, v125, v125 row_shr:2 row_mask:0xf bank_mask:0xf bound_ctrl:1
	v_add_f32_dpp v132, v118, v118 row_shr:2 row_mask:0xf bank_mask:0xf bound_ctrl:1
	v_add_f32_dpp v118, v126, v132 row_shl:14 row_mask:0xf bank_mask:0xf bound_ctrl:1
	v_add_f32_dpp v126, v126, v126 row_shr:2 row_mask:0xf bank_mask:0xf bound_ctrl:1
	v_add_f32_dpp v132, v119, v119 row_shr:2 row_mask:0xf bank_mask:0xf bound_ctrl:1
	v_add_f32_dpp v119, v127, v132 row_shl:14 row_mask:0xf bank_mask:0xf bound_ctrl:1
	v_add_f32_dpp v127, v127, v127 row_shr:2 row_mask:0xf bank_mask:0xf bound_ctrl:1
	v_add_f32_dpp v132, v120, v120 row_shr:2 row_mask:0xf bank_mask:0xf bound_ctrl:1
	v_add_f32_dpp v120, v128, v132 row_shl:14 row_mask:0xf bank_mask:0xf bound_ctrl:1
	v_add_f32_dpp v128, v128, v128 row_shr:2 row_mask:0xf bank_mask:0xf bound_ctrl:1
	v_add_f32_dpp v132, v121, v121 row_shr:2 row_mask:0xf bank_mask:0xf bound_ctrl:1
	v_add_f32_dpp v121, v129, v132 row_shl:14 row_mask:0xf bank_mask:0xf bound_ctrl:1
	v_add_f32_dpp v129, v129, v129 row_shr:2 row_mask:0xf bank_mask:0xf bound_ctrl:1
	v_add_f32_dpp v132, v122, v122 row_shr:2 row_mask:0xf bank_mask:0xf bound_ctrl:1
	v_add_f32_dpp v122, v130, v132 row_shl:14 row_mask:0xf bank_mask:0xf bound_ctrl:1
	v_add_f32_dpp v130, v130, v130 row_shr:2 row_mask:0xf bank_mask:0xf bound_ctrl:1
	v_add_f32_dpp v132, v123, v123 row_shr:2 row_mask:0xf bank_mask:0xf bound_ctrl:1
	v_add_f32_dpp v123, v131, v132 row_shl:14 row_mask:0xf bank_mask:0xf bound_ctrl:1
	v_add_f32_dpp v131, v131, v131 row_shr:2 row_mask:0xf bank_mask:0xf bound_ctrl:1
	v_fma_f32 v116, v116, v138, -v108
	v_fma_f32 v117, v117, v138, -v109
	v_fma_f32 v118, v118, v138, -v110
	v_fma_f32 v119, v119, v138, -v111
	v_fma_f32 v120, v120, v138, -v112
	v_fma_f32 v121, v121, v138, -v113
	v_fma_f32 v122, v122, v138, -v114
	v_fma_f32 v123, v123, v138, -v115
	v_cvt_pk_bf16_f32 v134, v116, v117
	v_cvt_pk_bf16_f32 v135, v118, v119
	v_cvt_pk_bf16_f32 v136, v120, v121
	v_cvt_pk_bf16_f32 v137, v122, v123
	s_waitcnt lgkmcnt(0)
; #define GAS __attribute__((address_space(1)))
; __device__ __forceinline__ void unpack8(const v4u w, float (&f)[8]) { f[0] = bf_lo(w.x); f[1] = bf_hi(w.x); f[2] = bf_lo(w.y); f[3] = bf_hi(w.y); f[4] = bf_lo(w.z); f[5] = bf_hi(w.z); f[6] = bf_lo(w.w); f[7] = bf_hi(w.w); }
; __device__ __forceinline__ v4u pack8(const float (&f)[8]) { v4u w; w.x = cvt_pk_bf16(f[0], f[1]); w.y = cvt_pk_bf16(f[2], f[3]); w.z = cvt_pk_bf16(f[4], f[5]); w.w = cvt_pk_bf16(f[6], f[7]); return w; }
; template <int W> __device__ __forceinline__ void pool_group(const bf16* zrow  , const bf16* pw  , bf16* orow  , int pos, bool prev_ok) {
;     ...
;     for (int kk = 0; kk < 4; ++kk) {
;         if (kk < 3) {
; #pragma unroll
;             for (int dt = 0; dt < 8; ++dt) aw[(kk + 1) & 1][dt] = *(const GAS v4u*)(pw + (size_t)16 * dt * 128 + 32 * (kk + 1)); }
;         float own[8], c[8], p[8];
;         unpack8(cw[kk], own); unpack8(pv[kk], p);
; #pragma unroll
;         for (int j = 0; j < 8; ++j) c[j] = own[j];
;         win_step<1>(c, p);
;         if (W >= 4) win_step<2>(c, p);
;         if (W >= 8) win_step<4>(c, p);
;         if (W >= 16) win_step<8>(c, p);
;         float pl[8];
; #pragma unroll
;         for (int j = 0; j < 8; ++j) pl[j] = c[j] * inv - own[j];
;         const v4u pwk = pack8(pl); const bf16x8 pf = __builtin_bit_cast(bf16x8, pwk);
; #pragma unroll
;         for (int dt = 0; dt < 8; ++dt) acc[dt] = __builtin_amdgcn_mfma_f32_16x16x32_bf16(__builtin_bit_cast(bf16x8, aw[kk & 1][dt]), pf, acc[dt], 0, 0, 0);
;     }
	s_nop 0
	v_mfma_f32_16x16x32_bf16 v[76:79], v[44:47], v[134:137], v[76:79]
	v_mfma_f32_16x16x32_bf16 v[80:83], v[48:51], v[134:137], v[80:83]
	v_mfma_f32_16x16x32_bf16 v[84:87], v[52:55], v[134:137], v[84:87]
	v_mfma_f32_16x16x32_bf16 v[88:91], v[56:59], v[134:137], v[88:91]
	v_mfma_f32_16x16x32_bf16 v[92:95], v[60:63], v[134:137], v[92:95]
	v_mfma_f32_16x16x32_bf16 v[96:99], v[64:67], v[134:137], v[96:99]
	v_mfma_f32_16x16x32_bf16 v[100:103], v[68:71], v[134:137], v[100:103]
	v_mfma_f32_16x16x32_bf16 v[104:107], v[72:75], v[134:137], v[104:107]
	v_add_u32_e32 v147, 32768, v145
	ds_read_b128 v[44:47], v147
	ds_read_b128 v[48:51], v147 offset:4096
	ds_read_b128 v[52:55], v147 offset:8192
	ds_read_b128 v[56:59], v147 offset:12288
	ds_read_b128 v[60:63], v147 offset:16384
	ds_read_b128 v[64:67], v147 offset:20480
	ds_read_b128 v[68:71], v147 offset:24576
	ds_read_b128 v[72:75], v147 offset:28672
	s_waitcnt vmcnt(14)
	v_lshlrev_b32_e32 v108, 16, v28
	v_and_b32_e32 v109, 0xffff0000, v28
	v_lshlrev_b32_e32 v110, 16, v29
	v_and_b32_e32 v111, 0xffff0000, v29
	v_lshlrev_b32_e32 v112, 16, v30
	v_and_b32_e32 v113, 0xffff0000, v30
	v_lshlrev_b32_e32 v114, 16, v31
	v_and_b32_e32 v115, 0xffff0000, v31
	v_lshlrev_b32_e32 v124, 16, v32
	v_and_b32_e32 v125, 0xffff0000, v32
	v_lshlrev_b32_e32 v126, 16, v33
	v_and_b32_e32 v127, 0xffff0000, v33
	v_lshlrev_b32_e32 v128, 16, v34
	v_and_b32_e32 v129, 0xffff0000, v34
	v_lshlrev_b32_e32 v130, 16, v35
	v_and_b32_e32 v131, 0xffff0000, v35
	v_cndmask_b32_e64 v124, 0, v124, s[40:41]
	v_cndmask_b32_e64 v125, 0, v125, s[40:41]
	v_cndmask_b32_e64 v126, 0, v126, s[40:41]
	v_cndmask_b32_e64 v127, 0, v127, s[40:41]
	v_cndmask_b32_e64 v128, 0, v128, s[40:41]
	v_cndmask_b32_e64 v129, 0, v129, s[40:41]
	v_cndmask_b32_e64 v130, 0, v130, s[40:41]
	v_cndmask_b32_e64 v131, 0, v131, s[40:41]
	global_load_dwordx4 v[28:31], v11, s[38:39] offset:640
	global_load_dwordx4 v[32:35], v11, s[48:49] offset:640
	v_mov_b32_e32 v116, v108
	v_mov_b32_e32 v117, v109
	v_mov_b32_e32 v118, v110
	v_mov_b32_e32 v119, v111
	v_mov_b32_e32 v120, v112
	v_mov_b32_e32 v121, v113
	v_mov_b32_e32 v122, v114
	v_mov_b32_e32 v123, v115
	v_add_f32_dpp v132, v116, v116 row_shr:1 row_mask:0xf bank_mask:0xf bound_ctrl:1
	v_add_f32_dpp v116, v124, v132 row_shl:15 row_mask:0xf bank_mask:0xf bound_ctrl:1
	v_add_f32_dpp v124, v124, v124 row_shr:1 row_mask:0xf bank_mask:0xf bound_ctrl:1
	v_add_f32_dpp v132, v117, v117 row_shr:1 row_mask:0xf bank_mask:0xf bound_ctrl:1
	v_add_f32_dpp v117, v125, v132 row_shl:15 row_mask:0xf bank_mask:0xf bound_ctrl:1
	v_add_f32_dpp v125, v125, v125 row_shr:1 row_mask:0xf bank_mask:0xf bound_ctrl:1
	v_add_f32_dpp v132, v118, v118 row_shr:1 row_mask:0xf bank_mask:0xf bound_ctrl:1
	v_add_f32_dpp v118, v126, v132 row_shl:15 row_mask:0xf bank_mask:0xf bound_ctrl:1
	v_add_f32_dpp v126, v126, v126 row_shr:1 row_mask:0xf bank_mask:0xf bound_ctrl:1
	v_add_f32_dpp v132, v119, v119 row_shr:1 row_mask:0xf bank_mask:0xf bound_ctrl:1
	v_add_f32_dpp v119, v127, v132 row_shl:15 row_mask:0xf bank_mask:0xf bound_ctrl:1
	v_add_f32_dpp v127, v127, v127 row_shr:1 row_mask:0xf bank_mask:0xf bound_ctrl:1
	v_add_f32_dpp v132, v120, v120 row_shr:1 row_mask:0xf bank_mask:0xf bound_ctrl:1
	v_add_f32_dpp v120, v128, v132 row_shl:15 row_mask:0xf bank_mask:0xf bound_ctrl:1
	v_add_f32_dpp v128, v128, v128 row_shr:1 row_mask:0xf bank_mask:0xf bound_ctrl:1
	v_add_f32_dpp v132, v121, v121 row_shr:1 row_mask:0xf bank_mask:0xf bound_ctrl:1
	v_add_f32_dpp v121, v129, v132 row_shl:15 row_mask:0xf bank_mask:0xf bound_ctrl:1
	v_add_f32_dpp v129, v129, v129 row_shr:1 row_mask:0xf bank_mask:0xf bound_ctrl:1
	v_add_f32_dpp v132, v122, v122 row_shr:1 row_mask:0xf bank_mask:0xf bound_ctrl:1
	v_add_f32_dpp v122, v130, v132 row_shl:15 row_mask:0xf bank_mask:0xf bound_ctrl:1
	v_add_f32_dpp v130, v130, v130 row_shr:1 row_mask:0xf bank_mask:0xf bound_ctrl:1
	v_add_f32_dpp v132, v123, v123 row_shr:1 row_mask:0xf bank_mask:0xf bound_ctrl:1
	v_add_f32_dpp v123, v131, v132 row_shl:15 row_mask:0xf bank_mask:0xf bound_ctrl:1
	v_add_f32_dpp v131, v131, v131 row_shr:1 row_mask:0xf bank_mask:0xf bound_ctrl:1
	v_add_f32_dpp v132, v116, v116 row_shr:2 row_mask:0xf bank_mask:0xf bound_ctrl:1
	v_add_f32_dpp v116, v124, v132 row_shl:14 row_mask:0xf bank_mask:0xf bound_ctrl:1
	v_add_f32_dpp v124, v124, v124 row_shr:2 row_mask:0xf bank_mask:0xf bound_ctrl:1
	v_add_f32_dpp v132, v117, v117 row_shr:2 row_mask:0xf bank_mask:0xf bound_ctrl:1
	v_add_f32_dpp v117, v125, v132 row_shl:14 row_mask:0xf bank_mask:0xf bound_ctrl:1
	v_add_f32_dpp v125, v125, v125 row_shr:2 row_mask:0xf bank_mask:0xf bound_ctrl:1
	v_add_f32_dpp v132, v118, v118 row_shr:2 row_mask:0xf bank_mask:0xf bound_ctrl:1
	v_add_f32_dpp v118, v126, v132 row_shl:14 row_mask:0xf bank_mask:0xf bound_ctrl:1
	v_add_f32_dpp v126, v126, v126 row_shr:2 row_mask:0xf bank_mask:0xf bound_ctrl:1
	v_add_f32_dpp v132, v119, v119 row_shr:2 row_mask:0xf bank_mask:0xf bound_ctrl:1
	v_add_f32_dpp v119, v127, v132 row_shl:14 row_mask:0xf bank_mask:0xf bound_ctrl:1
	v_add_f32_dpp v127, v127, v127 row_shr:2 row_mask:0xf bank_mask:0xf bound_ctrl:1
	v_add_f32_dpp v132, v120, v120 row_shr:2 row_mask:0xf bank_mask:0xf bound_ctrl:1
	v_add_f32_dpp v120, v128, v132 row_shl:14 row_mask:0xf bank_mask:0xf bound_ctrl:1
	v_add_f32_dpp v128, v128, v128 row_shr:2 row_mask:0xf bank_mask:0xf bound_ctrl:1
	v_add_f32_dpp v132, v121, v121 row_shr:2 row_mask:0xf bank_mask:0xf bound_ctrl:1
	v_add_f32_dpp v121, v129, v132 row_shl:14 row_mask:0xf bank_mask:0xf bound_ctrl:1
	v_add_f32_dpp v129, v129, v129 row_shr:2 row_mask:0xf bank_mask:0xf bound_ctrl:1
	v_add_f32_dpp v132, v122, v122 row_shr:2 row_mask:0xf bank_mask:0xf bound_ctrl:1
	v_add_f32_dpp v122, v130, v132 row_shl:14 row_mask:0xf bank_mask:0xf bound_ctrl:1
	v_add_f32_dpp v130, v130, v130 row_shr:2 row_mask:0xf bank_mask:0xf bound_ctrl:1
	v_add_f32_dpp v132, v123, v123 row_shr:2 row_mask:0xf bank_mask:0xf bound_ctrl:1
	v_add_f32_dpp v123, v131, v132 row_shl:14 row_mask:0xf bank_mask:0xf bound_ctrl:1
	v_add_f32_dpp v131, v131, v131 row_shr:2 row_mask:0xf bank_mask:0xf bound_ctrl:1
	v_fma_f32 v116, v116, v138, -v108
	v_fma_f32 v117, v117, v138, -v109
	v_fma_f32 v118, v118, v138, -v110
	v_fma_f32 v119, v119, v138, -v111
	v_fma_f32 v120, v120, v138, -v112
	v_fma_f32 v121, v121, v138, -v113
	v_fma_f32 v122, v122, v138, -v114
	v_fma_f32 v123, v123, v138, -v115
	v_cvt_pk_bf16_f32 v134, v116, v117
	v_cvt_pk_bf16_f32 v135, v118, v119
	v_cvt_pk_bf16_f32 v136, v120, v121
	v_cvt_pk_bf16_f32 v137, v122, v123
	s_waitcnt lgkmcnt(0)
; #define GAS __attribute__((address_space(1)))
; __device__ __forceinline__ void unpack8(const v4u w, float (&f)[8]) { f[0] = bf_lo(w.x); f[1] = bf_hi(w.x); f[2] = bf_lo(w.y); f[3] = bf_hi(w.y); f[4] = bf_lo(w.z); f[5] = bf_hi(w.z); f[6] = bf_lo(w.w); f[7] = bf_hi(w.w); }
; __device__ __forceinline__ v4u pack8(const float (&f)[8]) { v4u w; w.x = cvt_pk_bf16(f[0], f[1]); w.y = cvt_pk_bf16(f[2], f[3]); w.z = cvt_pk_bf16(f[4], f[5]); w.w = cvt_pk_bf16(f[6], f[7]); return w; }
; template <int W> __device__ __forceinline__ void pool_group(const bf16* zrow  , const bf16* pw  , bf16* orow  , int pos, bool prev_ok) {
;     ...
;     for (int kk = 0; kk < 4; ++kk) {
;         if (kk < 3) {
; #pragma unroll
;             for (int dt = 0; dt < 8; ++dt) aw[(kk + 1) & 1][dt] = *(const GAS v4u*)(pw + (size_t)16 * dt * 128 + 32 * (kk + 1)); }
;         float own[8], c[8], p[8];
;         unpack8(cw[kk], own); unpack8(pv[kk], p);
; #pragma unroll
;         for (int j = 0; j < 8; ++j) c[j] = own[j];
;         win_step<1>(c, p);
;         if (W >= 4) win_step<2>(c, p);
;         if (W >= 8) win_step<4>(c, p);
;         if (W >= 16) win_step<8>(c, p);
;         float pl[8];
; #pragma unroll
;         for (int j = 0; j < 8; ++j) pl[j] = c[j] * inv - own[j];
;         const v4u pwk = pack8(pl); const bf16x8 pf = __builtin_bit_cast(bf16x8, pwk);
; #pragma unroll
;         for (int dt = 0; dt < 8; ++dt) acc[dt] = __builtin_amdgcn_mfma_f32_16x16x32_bf16(__builtin_bit_cast(bf16x8, aw[kk & 1][dt]), pf, acc[dt], 0, 0, 0);
;     }
	s_nop 0
	v_mfma_f32_16x16x32_bf16 v[76:79], v[44:47], v[134:137], v[76:79]
	v_mfma_f32_16x16x32_bf16 v[80:83], v[48:51], v[134:137], v[80:83]
	v_mfma_f32_16x16x32_bf16 v[84:87], v[52:55], v[134:137], v[84:87]
	v_mfma_f32_16x16x32_bf16 v[88:91], v[56:59], v[134:137], v[88:91]
	v_mfma_f32_16x16x32_bf16 v[92:95], v[60:63], v[134:137], v[92:95]
	v_mfma_f32_16x16x32_bf16 v[96:99], v[64:67], v[134:137], v[96:99]
	v_mfma_f32_16x16x32_bf16 v[100:103], v[68:71], v[134:137], v[100:103]
	v_mfma_f32_16x16x32_bf16 v[104:107], v[72:75], v[134:137], v[104:107]
	v_add_u32_e32 v147, 32768, v146
	ds_read_b128 v[44:47], v147
	ds_read_b128 v[48:51], v147 offset:4096
	ds_read_b128 v[52:55], v147 offset:8192
	ds_read_b128 v[56:59], v147 offset:12288
	ds_read_b128 v[60:63], v147 offset:16384
	ds_read_b128 v[64:67], v147 offset:20480
	ds_read_b128 v[68:71], v147 offset:24576
	ds_read_b128 v[72:75], v147 offset:28672
	s_waitcnt vmcnt(14)
	v_lshlrev_b32_e32 v108, 16, v36
	v_and_b32_e32 v109, 0xffff0000, v36
	v_lshlrev_b32_e32 v110, 16, v37
	v_and_b32_e32 v111, 0xffff0000, v37
	v_lshlrev_b32_e32 v112, 16, v38
	v_and_b32_e32 v113, 0xffff0000, v38
	v_lshlrev_b32_e32 v114, 16, v39
	v_and_b32_e32 v115, 0xffff0000, v39
	v_lshlrev_b32_e32 v124, 16, v40
	v_and_b32_e32 v125, 0xffff0000, v40
	v_lshlrev_b32_e32 v126, 16, v41
	v_and_b32_e32 v127, 0xffff0000, v41
	v_lshlrev_b32_e32 v128, 16, v42
	v_and_b32_e32 v129, 0xffff0000, v42
	v_lshlrev_b32_e32 v130, 16, v43
	v_and_b32_e32 v131, 0xffff0000, v43
	v_cndmask_b32_e64 v124, 0, v124, s[40:41]
	v_cndmask_b32_e64 v125, 0, v125, s[40:41]
	v_cndmask_b32_e64 v126, 0, v126, s[40:41]
	v_cndmask_b32_e64 v127, 0, v127, s[40:41]
	v_cndmask_b32_e64 v128, 0, v128, s[40:41]
	v_cndmask_b32_e64 v129, 0, v129, s[40:41]
	v_cndmask_b32_e64 v130, 0, v130, s[40:41]
	v_cndmask_b32_e64 v131, 0, v131, s[40:41]
	global_load_dwordx4 v[36:39], v11, s[38:39] offset:704
	global_load_dwordx4 v[40:43], v11, s[48:49] offset:704
	v_mov_b32_e32 v116, v108
	v_mov_b32_e32 v117, v109
	v_mov_b32_e32 v118, v110
	v_mov_b32_e32 v119, v111
	v_mov_b32_e32 v120, v112
	v_mov_b32_e32 v121, v113
	v_mov_b32_e32 v122, v114
	v_mov_b32_e32 v123, v115
	v_add_f32_dpp v132, v116, v116 row_shr:1 row_mask:0xf bank_mask:0xf bound_ctrl:1
	v_add_f32_dpp v116, v124, v132 row_shl:15 row_mask:0xf bank_mask:0xf bound_ctrl:1
	v_add_f32_dpp v124, v124, v124 row_shr:1 row_mask:0xf bank_mask:0xf bound_ctrl:1
	v_add_f32_dpp v132, v117, v117 row_shr:1 row_mask:0xf bank_mask:0xf bound_ctrl:1
	v_add_f32_dpp v117, v125, v132 row_shl:15 row_mask:0xf bank_mask:0xf bound_ctrl:1
	v_add_f32_dpp v125, v125, v125 row_shr:1 row_mask:0xf bank_mask:0xf bound_ctrl:1
	v_add_f32_dpp v132, v118, v118 row_shr:1 row_mask:0xf bank_mask:0xf bound_ctrl:1
	v_add_f32_dpp v118, v126, v132 row_shl:15 row_mask:0xf bank_mask:0xf bound_ctrl:1
	v_add_f32_dpp v126, v126, v126 row_shr:1 row_mask:0xf bank_mask:0xf bound_ctrl:1
	v_add_f32_dpp v132, v119, v119 row_shr:1 row_mask:0xf bank_mask:0xf bound_ctrl:1
	v_add_f32_dpp v119, v127, v132 row_shl:15 row_mask:0xf bank_mask:0xf bound_ctrl:1
	v_add_f32_dpp v127, v127, v127 row_shr:1 row_mask:0xf bank_mask:0xf bound_ctrl:1
	v_add_f32_dpp v132, v120, v120 row_shr:1 row_mask:0xf bank_mask:0xf bound_ctrl:1
	v_add_f32_dpp v120, v128, v132 row_shl:15 row_mask:0xf bank_mask:0xf bound_ctrl:1
	v_add_f32_dpp v128, v128, v128 row_shr:1 row_mask:0xf bank_mask:0xf bound_ctrl:1
	v_add_f32_dpp v132, v121, v121 row_shr:1 row_mask:0xf bank_mask:0xf bound_ctrl:1
	v_add_f32_dpp v121, v129, v132 row_shl:15 row_mask:0xf bank_mask:0xf bound_ctrl:1
	v_add_f32_dpp v129, v129, v129 row_shr:1 row_mask:0xf bank_mask:0xf bound_ctrl:1
	v_add_f32_dpp v132, v122, v122 row_shr:1 row_mask:0xf bank_mask:0xf bound_ctrl:1
	v_add_f32_dpp v122, v130, v132 row_shl:15 row_mask:0xf bank_mask:0xf bound_ctrl:1
	v_add_f32_dpp v130, v130, v130 row_shr:1 row_mask:0xf bank_mask:0xf bound_ctrl:1
	v_add_f32_dpp v132, v123, v123 row_shr:1 row_mask:0xf bank_mask:0xf bound_ctrl:1
	v_add_f32_dpp v123, v131, v132 row_shl:15 row_mask:0xf bank_mask:0xf bound_ctrl:1
	v_add_f32_dpp v131, v131, v131 row_shr:1 row_mask:0xf bank_mask:0xf bound_ctrl:1
	v_add_f32_dpp v132, v116, v116 row_shr:2 row_mask:0xf bank_mask:0xf bound_ctrl:1
	v_add_f32_dpp v116, v124, v132 row_shl:14 row_mask:0xf bank_mask:0xf bound_ctrl:1
	v_add_f32_dpp v124, v124, v124 row_shr:2 row_mask:0xf bank_mask:0xf bound_ctrl:1
	v_add_f32_dpp v132, v117, v117 row_shr:2 row_mask:0xf bank_mask:0xf bound_ctrl:1
	v_add_f32_dpp v117, v125, v132 row_shl:14 row_mask:0xf bank_mask:0xf bound_ctrl:1
	v_add_f32_dpp v125, v125, v125 row_shr:2 row_mask:0xf bank_mask:0xf bound_ctrl:1
	v_add_f32_dpp v132, v118, v118 row_shr:2 row_mask:0xf bank_mask:0xf bound_ctrl:1
	v_add_f32_dpp v118, v126, v132 row_shl:14 row_mask:0xf bank_mask:0xf bound_ctrl:1
	v_add_f32_dpp v126, v126, v126 row_shr:2 row_mask:0xf bank_mask:0xf bound_ctrl:1
	v_add_f32_dpp v132, v119, v119 row_shr:2 row_mask:0xf bank_mask:0xf bound_ctrl:1
	v_add_f32_dpp v119, v127, v132 row_shl:14 row_mask:0xf bank_mask:0xf bound_ctrl:1
	v_add_f32_dpp v127, v127, v127 row_shr:2 row_mask:0xf bank_mask:0xf bound_ctrl:1
	v_add_f32_dpp v132, v120, v120 row_shr:2 row_mask:0xf bank_mask:0xf bound_ctrl:1
	v_add_f32_dpp v120, v128, v132 row_shl:14 row_mask:0xf bank_mask:0xf bound_ctrl:1
	v_add_f32_dpp v128, v128, v128 row_shr:2 row_mask:0xf bank_mask:0xf bound_ctrl:1
	v_add_f32_dpp v132, v121, v121 row_shr:2 row_mask:0xf bank_mask:0xf bound_ctrl:1
	v_add_f32_dpp v121, v129, v132 row_shl:14 row_mask:0xf bank_mask:0xf bound_ctrl:1
	v_add_f32_dpp v129, v129, v129 row_shr:2 row_mask:0xf bank_mask:0xf bound_ctrl:1
	v_add_f32_dpp v132, v122, v122 row_shr:2 row_mask:0xf bank_mask:0xf bound_ctrl:1
	v_add_f32_dpp v122, v130, v132 row_shl:14 row_mask:0xf bank_mask:0xf bound_ctrl:1
	v_add_f32_dpp v130, v130, v130 row_shr:2 row_mask:0xf bank_mask:0xf bound_ctrl:1
	v_add_f32_dpp v132, v123, v123 row_shr:2 row_mask:0xf bank_mask:0xf bound_ctrl:1
	v_add_f32_dpp v123, v131, v132 row_shl:14 row_mask:0xf bank_mask:0xf bound_ctrl:1
	v_add_f32_dpp v131, v131, v131 row_shr:2 row_mask:0xf bank_mask:0xf bound_ctrl:1
	v_fma_f32 v116, v116, v138, -v108
	v_fma_f32 v117, v117, v138, -v109
	v_fma_f32 v118, v118, v138, -v110
	v_fma_f32 v119, v119, v138, -v111
	v_fma_f32 v120, v120, v138, -v112
	v_fma_f32 v121, v121, v138, -v113
	v_fma_f32 v122, v122, v138, -v114
	v_fma_f32 v123, v123, v138, -v115
	v_cvt_pk_bf16_f32 v134, v116, v117
	v_cvt_pk_bf16_f32 v135, v118, v119
	v_cvt_pk_bf16_f32 v136, v120, v121
	v_cvt_pk_bf16_f32 v137, v122, v123
	s_waitcnt lgkmcnt(0)
; __device__ __forceinline__ unsigned cvt_pk_bf16(float lo, float hi) { return __builtin_bit_cast(unsigned, __builtin_convertvector((f32x2_t){lo, hi}, bf16x2_t)); }
; #define GAS __attribute__((address_space(1)))
; __device__ __forceinline__ void unpack8(const v4u w, float (&f)[8]) { f[0] = bf_lo(w.x); f[1] = bf_hi(w.x); f[2] = bf_lo(w.y); f[3] = bf_hi(w.y); f[4] = bf_lo(w.z); f[5] = bf_hi(w.z); f[6] = bf_lo(w.w); f[7] = bf_hi(w.w); }
; template <int W> __device__ __forceinline__ void pool_group(const bf16* zrow  , const bf16* pw  , bf16* orow  , int pos, bool prev_ok) {
;     const float inv = 1.0f / (float)((pos + 1) < W ? (pos + 1) : W);
;     f32x4 acc[8];
; #pragma unroll
;     for (int dt = 0; dt < 8; ++dt) acc[dt] = (f32x4){0.f, 0.f, 0.f, 0.f};
;     v4u cw[4], pv[4], aw[2][8];
; #pragma unroll
;     for (int kk = 0; kk < 4; ++kk) { cw[kk] = *(const GAS v4u*)(zrow + 32 * kk); pv[kk] = prev_ok ? *(const GAS v4u*)(zrow + 32 * kk - (ptrdiff_t)16 * ZC) : (v4u){0u, 0u, 0u, 0u}; }
; #pragma unroll
;     for (int dt = 0; dt < 8; ++dt) aw[0][dt] = *(const GAS v4u*)(pw + (size_t)16 * dt * 128);
; #pragma unroll
;     for (int kk = 0; kk < 4; ++kk) {
;         if (kk < 3) {
; #pragma unroll
;             for (int dt = 0; dt < 8; ++dt) aw[(kk + 1) & 1][dt] = *(const GAS v4u*)(pw + (size_t)16 * dt * 128 + 32 * (kk + 1)); }
;         float own[8], c[8], p[8];
;         unpack8(cw[kk], own); unpack8(pv[kk], p);
; #pragma unroll
;         for (int j = 0; j < 8; ++j) c[j] = own[j];
;         win_step<1>(c, p);
;         if (W >= 4) win_step<2>(c, p);
;         if (W >= 8) win_step<4>(c, p);
;         if (W >= 16) win_step<8>(c, p);
;         float pl[8];
; #pragma unroll
;         for (int j = 0; j < 8; ++j) pl[j] = c[j] * inv - own[j];
;         const v4u pwk = pack8(pl); const bf16x8 pf = __builtin_bit_cast(bf16x8, pwk);
; #pragma unroll
;         for (int dt = 0; dt < 8; ++dt) acc[dt] = __builtin_amdgcn_mfma_f32_16x16x32_bf16(__builtin_bit_cast(bf16x8, aw[kk & 1][dt]), pf, acc[dt], 0, 0, 0);
;     }
; #pragma unroll
;     for (int dt = 0; dt < 8; ++dt) { v2u w; w.x = cvt_pk_bf16(acc[dt][0], acc[dt][1]); w.y = cvt_pk_bf16(acc[dt][2], acc[dt][3]); *(GAS v2u*)(orow + 16 * dt) = w; }
	s_nop 0
	v_mfma_f32_16x16x32_bf16 v[76:79], v[44:47], v[134:137], v[76:79]
	v_mfma_f32_16x16x32_bf16 v[80:83], v[48:51], v[134:137], v[80:83]
	v_mfma_f32_16x16x32_bf16 v[84:87], v[52:55], v[134:137], v[84:87]
	v_mfma_f32_16x16x32_bf16 v[88:91], v[56:59], v[134:137], v[88:91]
	v_mfma_f32_16x16x32_bf16 v[92:95], v[60:63], v[134:137], v[92:95]
	v_mfma_f32_16x16x32_bf16 v[96:99], v[64:67], v[134:137], v[96:99]
	v_mfma_f32_16x16x32_bf16 v[100:103], v[68:71], v[134:137], v[100:103]
	v_mfma_f32_16x16x32_bf16 v[104:107], v[72:75], v[134:137], v[104:107]
	s_nop 7
	s_nop 1
	v_cvt_pk_bf16_f32 v132, v76, v77
	v_cvt_pk_bf16_f32 v133, v78, v79
	global_store_dwordx2 v142, v[132:133], s[46:47] offset:256
	s_nop 0
	v_cvt_pk_bf16_f32 v132, v80, v81
	v_cvt_pk_bf16_f32 v133, v82, v83
	global_store_dwordx2 v142, v[132:133], s[46:47] offset:288
	s_nop 0
	v_cvt_pk_bf16_f32 v132, v84, v85
	v_cvt_pk_bf16_f32 v133, v86, v87
	global_store_dwordx2 v142, v[132:133], s[46:47] offset:320
	s_nop 0
	v_cvt_pk_bf16_f32 v132, v88, v89
	v_cvt_pk_bf16_f32 v133, v90, v91
	global_store_dwordx2 v142, v[132:133], s[46:47] offset:352
	s_nop 0
	v_cvt_pk_bf16_f32 v132, v92, v93
	v_cvt_pk_bf16_f32 v133, v94, v95
	global_store_dwordx2 v142, v[132:133], s[46:47] offset:384
	s_nop 0
	v_cvt_pk_bf16_f32 v132, v96, v97
	v_cvt_pk_bf16_f32 v133, v98, v99
	global_store_dwordx2 v142, v[132:133], s[46:47] offset:416
	s_nop 0
	v_cvt_pk_bf16_f32 v132, v100, v101
	v_cvt_pk_bf16_f32 v133, v102, v103
	global_store_dwordx2 v142, v[132:133], s[46:47] offset:448
	s_nop 0
	v_cvt_pk_bf16_f32 v132, v104, v105
	v_cvt_pk_bf16_f32 v133, v106, v107
	global_store_dwordx2 v142, v[132:133], s[46:47] offset:480
	s_nop 0
	v_min_i32_e32 v139, 8, v140
	v_cvt_f32_i32_e32 v139, v139
	v_div_scale_f32 v1, s[42:43], v139, v139, 1.0
	v_rcp_f32_e32 v2, v1
	s_nop 0
	v_fma_f32 v7, -v1, v2, 1.0
	v_fmac_f32_e32 v2, v7, v2
	v_div_scale_f32 v3, vcc, 1.0, v139, 1.0
	v_mul_f32_e32 v6, v3, v2
	v_fma_f32 v7, -v1, v6, v3
	v_fmac_f32_e32 v6, v7, v2
	v_fma_f32 v1, -v1, v6, v3
	s_nop 1
	v_div_fmas_f32 v1, v1, v2, v6
	v_div_fixup_f32 v138, v1, v139, 1.0
	v_add_u32_e32 v147, 65536, v143
	ds_read_b128 v[44:47], v147
	ds_read_b128 v[48:51], v147 offset:4096
	ds_read_b128 v[52:55], v147 offset:8192
	ds_read_b128 v[56:59], v147 offset:12288
	ds_read_b128 v[60:63], v147 offset:16384
	ds_read_b128 v[64:67], v147 offset:20480
	ds_read_b128 v[68:71], v147 offset:24576
	ds_read_b128 v[72:75], v147 offset:28672
	s_waitcnt vmcnt(14)
	v_lshlrev_b32_e32 v108, 16, v12
	v_and_b32_e32 v109, 0xffff0000, v12
	v_lshlrev_b32_e32 v110, 16, v13
	v_and_b32_e32 v111, 0xffff0000, v13
	v_lshlrev_b32_e32 v112, 16, v14
	v_and_b32_e32 v113, 0xffff0000, v14
	v_lshlrev_b32_e32 v114, 16, v15
	v_and_b32_e32 v115, 0xffff0000, v15
	v_lshlrev_b32_e32 v124, 16, v16
	v_and_b32_e32 v125, 0xffff0000, v16
	v_lshlrev_b32_e32 v126, 16, v17
	v_and_b32_e32 v127, 0xffff0000, v17
	v_lshlrev_b32_e32 v128, 16, v18
	v_and_b32_e32 v129, 0xffff0000, v18
	v_lshlrev_b32_e32 v130, 16, v19
	v_and_b32_e32 v131, 0xffff0000, v19
	v_cndmask_b32_e64 v124, 0, v124, s[40:41]
	v_cndmask_b32_e64 v125, 0, v125, s[40:41]
	v_cndmask_b32_e64 v126, 0, v126, s[40:41]
	v_cndmask_b32_e64 v127, 0, v127, s[40:41]
	v_cndmask_b32_e64 v128, 0, v128, s[40:41]
	v_cndmask_b32_e64 v129, 0, v129, s[40:41]
	v_cndmask_b32_e64 v130, 0, v130, s[40:41]
	v_cndmask_b32_e64 v131, 0, v131, s[40:41]
	global_load_dwordx4 v[12:15], v11, s[38:39] offset:768
	global_load_dwordx4 v[16:19], v11, s[48:49] offset:768
	v_mov_b32_e32 v116, v108
	v_mov_b32_e32 v117, v109
	v_mov_b32_e32 v118, v110
	v_mov_b32_e32 v119, v111
	v_mov_b32_e32 v120, v112
	v_mov_b32_e32 v121, v113
	v_mov_b32_e32 v122, v114
	v_mov_b32_e32 v123, v115
	v_add_f32_dpp v132, v116, v116 row_shr:1 row_mask:0xf bank_mask:0xf bound_ctrl:1
	v_add_f32_dpp v116, v124, v132 row_shl:15 row_mask:0xf bank_mask:0xf bound_ctrl:1
	v_add_f32_dpp v124, v124, v124 row_shr:1 row_mask:0xf bank_mask:0xf bound_ctrl:1
	v_add_f32_dpp v132, v117, v117 row_shr:1 row_mask:0xf bank_mask:0xf bound_ctrl:1
	v_add_f32_dpp v117, v125, v132 row_shl:15 row_mask:0xf bank_mask:0xf bound_ctrl:1
	v_add_f32_dpp v125, v125, v125 row_shr:1 row_mask:0xf bank_mask:0xf bound_ctrl:1
	v_add_f32_dpp v132, v118, v118 row_shr:1 row_mask:0xf bank_mask:0xf bound_ctrl:1
	v_add_f32_dpp v118, v126, v132 row_shl:15 row_mask:0xf bank_mask:0xf bound_ctrl:1
	v_add_f32_dpp v126, v126, v126 row_shr:1 row_mask:0xf bank_mask:0xf bound_ctrl:1
	v_add_f32_dpp v132, v119, v119 row_shr:1 row_mask:0xf bank_mask:0xf bound_ctrl:1
	v_add_f32_dpp v119, v127, v132 row_shl:15 row_mask:0xf bank_mask:0xf bound_ctrl:1
	v_add_f32_dpp v127, v127, v127 row_shr:1 row_mask:0xf bank_mask:0xf bound_ctrl:1
	v_add_f32_dpp v132, v120, v120 row_shr:1 row_mask:0xf bank_mask:0xf bound_ctrl:1
	v_add_f32_dpp v120, v128, v132 row_shl:15 row_mask:0xf bank_mask:0xf bound_ctrl:1
	v_add_f32_dpp v128, v128, v128 row_shr:1 row_mask:0xf bank_mask:0xf bound_ctrl:1
	v_add_f32_dpp v132, v121, v121 row_shr:1 row_mask:0xf bank_mask:0xf bound_ctrl:1
	v_add_f32_dpp v121, v129, v132 row_shl:15 row_mask:0xf bank_mask:0xf bound_ctrl:1
	v_add_f32_dpp v129, v129, v129 row_shr:1 row_mask:0xf bank_mask:0xf bound_ctrl:1
	v_add_f32_dpp v132, v122, v122 row_shr:1 row_mask:0xf bank_mask:0xf bound_ctrl:1
	v_add_f32_dpp v122, v130, v132 row_shl:15 row_mask:0xf bank_mask:0xf bound_ctrl:1
	v_add_f32_dpp v130, v130, v130 row_shr:1 row_mask:0xf bank_mask:0xf bound_ctrl:1
	v_add_f32_dpp v132, v123, v123 row_shr:1 row_mask:0xf bank_mask:0xf bound_ctrl:1
	v_add_f32_dpp v123, v131, v132 row_shl:15 row_mask:0xf bank_mask:0xf bound_ctrl:1
	v_add_f32_dpp v131, v131, v131 row_shr:1 row_mask:0xf bank_mask:0xf bound_ctrl:1
; #define GAS __attribute__((address_space(1)))
; __device__ __forceinline__ void unpack8(const v4u w, float (&f)[8]) { f[0] = bf_lo(w.x); f[1] = bf_hi(w.x); f[2] = bf_lo(w.y); f[3] = bf_hi(w.y); f[4] = bf_lo(w.z); f[5] = bf_hi(w.z); f[6] = bf_lo(w.w); f[7] = bf_hi(w.w); }
; __device__ __forceinline__ v4u pack8(const float (&f)[8]) { v4u w; w.x = cvt_pk_bf16(f[0], f[1]); w.y = cvt_pk_bf16(f[2], f[3]); w.z = cvt_pk_bf16(f[4], f[5]); w.w = cvt_pk_bf16(f[6], f[7]); return w; }
; template <int W> __device__ __forceinline__ void pool_group(const bf16* zrow  , const bf16* pw  , bf16* orow  , int pos, bool prev_ok) {
;     ...
;     for (int kk = 0; kk < 4; ++kk) {
;         if (kk < 3) {
; #pragma unroll
;             for (int dt = 0; dt < 8; ++dt) aw[(kk + 1) & 1][dt] = *(const GAS v4u*)(pw + (size_t)16 * dt * 128 + 32 * (kk + 1)); }
;         float own[8], c[8], p[8];
;         unpack8(cw[kk], own); unpack8(pv[kk], p);
; #pragma unroll
;         for (int j = 0; j < 8; ++j) c[j] = own[j];
;         win_step<1>(c, p);
;         if (W >= 4) win_step<2>(c, p);
;         if (W >= 8) win_step<4>(c, p);
;         if (W >= 16) win_step<8>(c, p);
;         float pl[8];
; #pragma unroll
;         for (int j = 0; j < 8; ++j) pl[j] = c[j] * inv - own[j];
;         const v4u pwk = pack8(pl); const bf16x8 pf = __builtin_bit_cast(bf16x8, pwk);
; #pragma unroll
;         for (int dt = 0; dt < 8; ++dt) acc[dt] = __builtin_amdgcn_mfma_f32_16x16x32_bf16(__builtin_bit_cast(bf16x8, aw[kk & 1][dt]), pf, acc[dt], 0, 0, 0);
;     }
	v_add_f32_dpp v132, v116, v116 row_shr:2 row_mask:0xf bank_mask:0xf bound_ctrl:1
	v_add_f32_dpp v116, v124, v132 row_shl:14 row_mask:0xf bank_mask:0xf bound_ctrl:1
	v_add_f32_dpp v124, v124, v124 row_shr:2 row_mask:0xf bank_mask:0xf bound_ctrl:1
	v_add_f32_dpp v132, v117, v117 row_shr:2 row_mask:0xf bank_mask:0xf bound_ctrl:1
	v_add_f32_dpp v117, v125, v132 row_shl:14 row_mask:0xf bank_mask:0xf bound_ctrl:1
	v_add_f32_dpp v125, v125, v125 row_shr:2 row_mask:0xf bank_mask:0xf bound_ctrl:1
	v_add_f32_dpp v132, v118, v118 row_shr:2 row_mask:0xf bank_mask:0xf bound_ctrl:1
	v_add_f32_dpp v118, v126, v132 row_shl:14 row_mask:0xf bank_mask:0xf bound_ctrl:1
	v_add_f32_dpp v126, v126, v126 row_shr:2 row_mask:0xf bank_mask:0xf bound_ctrl:1
	v_add_f32_dpp v132, v119, v119 row_shr:2 row_mask:0xf bank_mask:0xf bound_ctrl:1
	v_add_f32_dpp v119, v127, v132 row_shl:14 row_mask:0xf bank_mask:0xf bound_ctrl:1
	v_add_f32_dpp v127, v127, v127 row_shr:2 row_mask:0xf bank_mask:0xf bound_ctrl:1
	v_add_f32_dpp v132, v120, v120 row_shr:2 row_mask:0xf bank_mask:0xf bound_ctrl:1
	v_add_f32_dpp v120, v128, v132 row_shl:14 row_mask:0xf bank_mask:0xf bound_ctrl:1
	v_add_f32_dpp v128, v128, v128 row_shr:2 row_mask:0xf bank_mask:0xf bound_ctrl:1
	v_add_f32_dpp v132, v121, v121 row_shr:2 row_mask:0xf bank_mask:0xf bound_ctrl:1
	v_add_f32_dpp v121, v129, v132 row_shl:14 row_mask:0xf bank_mask:0xf bound_ctrl:1
	v_add_f32_dpp v129, v129, v129 row_shr:2 row_mask:0xf bank_mask:0xf bound_ctrl:1
	v_add_f32_dpp v132, v122, v122 row_shr:2 row_mask:0xf bank_mask:0xf bound_ctrl:1
	v_add_f32_dpp v122, v130, v132 row_shl:14 row_mask:0xf bank_mask:0xf bound_ctrl:1
	v_add_f32_dpp v130, v130, v130 row_shr:2 row_mask:0xf bank_mask:0xf bound_ctrl:1
	v_add_f32_dpp v132, v123, v123 row_shr:2 row_mask:0xf bank_mask:0xf bound_ctrl:1
	v_add_f32_dpp v123, v131, v132 row_shl:14 row_mask:0xf bank_mask:0xf bound_ctrl:1
	v_add_f32_dpp v131, v131, v131 row_shr:2 row_mask:0xf bank_mask:0xf bound_ctrl:1
	v_add_f32_dpp v132, v116, v116 row_shr:4 row_mask:0xf bank_mask:0xf bound_ctrl:1
	v_add_f32_dpp v116, v124, v132 row_shl:12 row_mask:0xf bank_mask:0xf bound_ctrl:1
	v_add_f32_dpp v124, v124, v124 row_shr:4 row_mask:0xf bank_mask:0xf bound_ctrl:1
	v_add_f32_dpp v132, v117, v117 row_shr:4 row_mask:0xf bank_mask:0xf bound_ctrl:1
	v_add_f32_dpp v117, v125, v132 row_shl:12 row_mask:0xf bank_mask:0xf bound_ctrl:1
	v_add_f32_dpp v125, v125, v125 row_shr:4 row_mask:0xf bank_mask:0xf bound_ctrl:1
	v_add_f32_dpp v132, v118, v118 row_shr:4 row_mask:0xf bank_mask:0xf bound_ctrl:1
	v_add_f32_dpp v118, v126, v132 row_shl:12 row_mask:0xf bank_mask:0xf bound_ctrl:1
	v_add_f32_dpp v126, v126, v126 row_shr:4 row_mask:0xf bank_mask:0xf bound_ctrl:1
	v_add_f32_dpp v132, v119, v119 row_shr:4 row_mask:0xf bank_mask:0xf bound_ctrl:1
	v_add_f32_dpp v119, v127, v132 row_shl:12 row_mask:0xf bank_mask:0xf bound_ctrl:1
	v_add_f32_dpp v127, v127, v127 row_shr:4 row_mask:0xf bank_mask:0xf bound_ctrl:1
	v_add_f32_dpp v132, v120, v120 row_shr:4 row_mask:0xf bank_mask:0xf bound_ctrl:1
	v_add_f32_dpp v120, v128, v132 row_shl:12 row_mask:0xf bank_mask:0xf bound_ctrl:1
	v_add_f32_dpp v128, v128, v128 row_shr:4 row_mask:0xf bank_mask:0xf bound_ctrl:1
	v_add_f32_dpp v132, v121, v121 row_shr:4 row_mask:0xf bank_mask:0xf bound_ctrl:1
	v_add_f32_dpp v121, v129, v132 row_shl:12 row_mask:0xf bank_mask:0xf bound_ctrl:1
	v_add_f32_dpp v129, v129, v129 row_shr:4 row_mask:0xf bank_mask:0xf bound_ctrl:1
	v_add_f32_dpp v132, v122, v122 row_shr:4 row_mask:0xf bank_mask:0xf bound_ctrl:1
	v_add_f32_dpp v122, v130, v132 row_shl:12 row_mask:0xf bank_mask:0xf bound_ctrl:1
	v_add_f32_dpp v130, v130, v130 row_shr:4 row_mask:0xf bank_mask:0xf bound_ctrl:1
	v_add_f32_dpp v132, v123, v123 row_shr:4 row_mask:0xf bank_mask:0xf bound_ctrl:1
	v_add_f32_dpp v123, v131, v132 row_shl:12 row_mask:0xf bank_mask:0xf bound_ctrl:1
	v_add_f32_dpp v131, v131, v131 row_shr:4 row_mask:0xf bank_mask:0xf bound_ctrl:1
	v_fma_f32 v116, v116, v138, -v108
	v_fma_f32 v117, v117, v138, -v109
	v_fma_f32 v118, v118, v138, -v110
	v_fma_f32 v119, v119, v138, -v111
	v_fma_f32 v120, v120, v138, -v112
	v_fma_f32 v121, v121, v138, -v113
	v_fma_f32 v122, v122, v138, -v114
	v_fma_f32 v123, v123, v138, -v115
	v_cvt_pk_bf16_f32 v134, v116, v117
	v_cvt_pk_bf16_f32 v135, v118, v119
	v_cvt_pk_bf16_f32 v136, v120, v121
	v_cvt_pk_bf16_f32 v137, v122, v123
	s_waitcnt lgkmcnt(0)
	s_nop 0
	v_mfma_f32_16x16x32_bf16 v[76:79], v[44:47], v[134:137], 0
	v_mfma_f32_16x16x32_bf16 v[80:83], v[48:51], v[134:137], 0
	v_mfma_f32_16x16x32_bf16 v[84:87], v[52:55], v[134:137], 0
	v_mfma_f32_16x16x32_bf16 v[88:91], v[56:59], v[134:137], 0
	v_mfma_f32_16x16x32_bf16 v[92:95], v[60:63], v[134:137], 0
	v_mfma_f32_16x16x32_bf16 v[96:99], v[64:67], v[134:137], 0
	v_mfma_f32_16x16x32_bf16 v[100:103], v[68:71], v[134:137], 0
	v_mfma_f32_16x16x32_bf16 v[104:107], v[72:75], v[134:137], 0
	v_add_u32_e32 v147, 65536, v144
	ds_read_b128 v[44:47], v147
	ds_read_b128 v[48:51], v147 offset:4096
	ds_read_b128 v[52:55], v147 offset:8192
	ds_read_b128 v[56:59], v147 offset:12288
	ds_read_b128 v[60:63], v147 offset:16384
	ds_read_b128 v[64:67], v147 offset:20480
	ds_read_b128 v[68:71], v147 offset:24576
	ds_read_b128 v[72:75], v147 offset:28672
	s_waitcnt vmcnt(14)
; #define GAS __attribute__((address_space(1)))
; __device__ __forceinline__ void unpack8(const v4u w, float (&f)[8]) { f[0] = bf_lo(w.x); f[1] = bf_hi(w.x); f[2] = bf_lo(w.y); f[3] = bf_hi(w.y); f[4] = bf_lo(w.z); f[5] = bf_hi(w.z); f[6] = bf_lo(w.w); f[7] = bf_hi(w.w); }
; template <int W> __device__ __forceinline__ void pool_group(const bf16* zrow  , const bf16* pw  , bf16* orow  , int pos, bool prev_ok) {
;     ...
;             for (int dt = 0; dt < 8; ++dt) aw[(kk + 1) & 1][dt] = *(const GAS v4u*)(pw + (size_t)16 * dt * 128 + 32 * (kk + 1)); }
;         float own[8], c[8], p[8];
;         unpack8(cw[kk], own); unpack8(pv[kk], p);
; #pragma unroll
;         for (int j = 0; j < 8; ++j) c[j] = own[j];
;         win_step<1>(c, p);
;         if (W >= 4) win_step<2>(c, p);
;         if (W >= 8) win_step<4>(c, p);
;         if (W >= 16) win_step<8>(c, p);
	v_lshlrev_b32_e32 v108, 16, v20
	v_and_b32_e32 v109, 0xffff0000, v20
	v_lshlrev_b32_e32 v110, 16, v21
	v_and_b32_e32 v111, 0xffff0000, v21
	v_lshlrev_b32_e32 v112, 16, v22
	v_and_b32_e32 v113, 0xffff0000, v22
	v_lshlrev_b32_e32 v114, 16, v23
	v_and_b32_e32 v115, 0xffff0000, v23
	v_lshlrev_b32_e32 v124, 16, v24
	v_and_b32_e32 v125, 0xffff0000, v24
	v_lshlrev_b32_e32 v126, 16, v25
	v_and_b32_e32 v127, 0xffff0000, v25
	v_lshlrev_b32_e32 v128, 16, v26
	v_and_b32_e32 v129, 0xffff0000, v26
	v_lshlrev_b32_e32 v130, 16, v27
	v_and_b32_e32 v131, 0xffff0000, v27
	v_cndmask_b32_e64 v124, 0, v124, s[40:41]
	v_cndmask_b32_e64 v125, 0, v125, s[40:41]
	v_cndmask_b32_e64 v126, 0, v126, s[40:41]
	v_cndmask_b32_e64 v127, 0, v127, s[40:41]
	v_cndmask_b32_e64 v128, 0, v128, s[40:41]
	v_cndmask_b32_e64 v129, 0, v129, s[40:41]
	v_cndmask_b32_e64 v130, 0, v130, s[40:41]
	v_cndmask_b32_e64 v131, 0, v131, s[40:41]
	global_load_dwordx4 v[20:23], v11, s[38:39] offset:832
	global_load_dwordx4 v[24:27], v11, s[48:49] offset:832
	v_mov_b32_e32 v116, v108
	v_mov_b32_e32 v117, v109
	v_mov_b32_e32 v118, v110
	v_mov_b32_e32 v119, v111
	v_mov_b32_e32 v120, v112
	v_mov_b32_e32 v121, v113
	v_mov_b32_e32 v122, v114
	v_mov_b32_e32 v123, v115
	v_add_f32_dpp v132, v116, v116 row_shr:1 row_mask:0xf bank_mask:0xf bound_ctrl:1
	v_add_f32_dpp v116, v124, v132 row_shl:15 row_mask:0xf bank_mask:0xf bound_ctrl:1
	v_add_f32_dpp v124, v124, v124 row_shr:1 row_mask:0xf bank_mask:0xf bound_ctrl:1
	v_add_f32_dpp v132, v117, v117 row_shr:1 row_mask:0xf bank_mask:0xf bound_ctrl:1
	v_add_f32_dpp v117, v125, v132 row_shl:15 row_mask:0xf bank_mask:0xf bound_ctrl:1
	v_add_f32_dpp v125, v125, v125 row_shr:1 row_mask:0xf bank_mask:0xf bound_ctrl:1
	v_add_f32_dpp v132, v118, v118 row_shr:1 row_mask:0xf bank_mask:0xf bound_ctrl:1
	v_add_f32_dpp v118, v126, v132 row_shl:15 row_mask:0xf bank_mask:0xf bound_ctrl:1
	v_add_f32_dpp v126, v126, v126 row_shr:1 row_mask:0xf bank_mask:0xf bound_ctrl:1
	v_add_f32_dpp v132, v119, v119 row_shr:1 row_mask:0xf bank_mask:0xf bound_ctrl:1
	v_add_f32_dpp v119, v127, v132 row_shl:15 row_mask:0xf bank_mask:0xf bound_ctrl:1
	v_add_f32_dpp v127, v127, v127 row_shr:1 row_mask:0xf bank_mask:0xf bound_ctrl:1
	v_add_f32_dpp v132, v120, v120 row_shr:1 row_mask:0xf bank_mask:0xf bound_ctrl:1
	v_add_f32_dpp v120, v128, v132 row_shl:15 row_mask:0xf bank_mask:0xf bound_ctrl:1
	v_add_f32_dpp v128, v128, v128 row_shr:1 row_mask:0xf bank_mask:0xf bound_ctrl:1
	v_add_f32_dpp v132, v121, v121 row_shr:1 row_mask:0xf bank_mask:0xf bound_ctrl:1
	v_add_f32_dpp v121, v129, v132 row_shl:15 row_mask:0xf bank_mask:0xf bound_ctrl:1
	v_add_f32_dpp v129, v129, v129 row_shr:1 row_mask:0xf bank_mask:0xf bound_ctrl:1
	v_add_f32_dpp v132, v122, v122 row_shr:1 row_mask:0xf bank_mask:0xf bound_ctrl:1
	v_add_f32_dpp v122, v130, v132 row_shl:15 row_mask:0xf bank_mask:0xf bound_ctrl:1
	v_add_f32_dpp v130, v130, v130 row_shr:1 row_mask:0xf bank_mask:0xf bound_ctrl:1
	v_add_f32_dpp v132, v123, v123 row_shr:1 row_mask:0xf bank_mask:0xf bound_ctrl:1
	v_add_f32_dpp v123, v131, v132 row_shl:15 row_mask:0xf bank_mask:0xf bound_ctrl:1
	v_add_f32_dpp v131, v131, v131 row_shr:1 row_mask:0xf bank_mask:0xf bound_ctrl:1
	v_add_f32_dpp v132, v116, v116 row_shr:2 row_mask:0xf bank_mask:0xf bound_ctrl:1
	v_add_f32_dpp v116, v124, v132 row_shl:14 row_mask:0xf bank_mask:0xf bound_ctrl:1
	v_add_f32_dpp v124, v124, v124 row_shr:2 row_mask:0xf bank_mask:0xf bound_ctrl:1
	v_add_f32_dpp v132, v117, v117 row_shr:2 row_mask:0xf bank_mask:0xf bound_ctrl:1
	v_add_f32_dpp v117, v125, v132 row_shl:14 row_mask:0xf bank_mask:0xf bound_ctrl:1
	v_add_f32_dpp v125, v125, v125 row_shr:2 row_mask:0xf bank_mask:0xf bound_ctrl:1
	v_add_f32_dpp v132, v118, v118 row_shr:2 row_mask:0xf bank_mask:0xf bound_ctrl:1
	v_add_f32_dpp v118, v126, v132 row_shl:14 row_mask:0xf bank_mask:0xf bound_ctrl:1
	v_add_f32_dpp v126, v126, v126 row_shr:2 row_mask:0xf bank_mask:0xf bound_ctrl:1
	v_add_f32_dpp v132, v119, v119 row_shr:2 row_mask:0xf bank_mask:0xf bound_ctrl:1
	v_add_f32_dpp v119, v127, v132 row_shl:14 row_mask:0xf bank_mask:0xf bound_ctrl:1
	v_add_f32_dpp v127, v127, v127 row_shr:2 row_mask:0xf bank_mask:0xf bound_ctrl:1
	v_add_f32_dpp v132, v120, v120 row_shr:2 row_mask:0xf bank_mask:0xf bound_ctrl:1
	v_add_f32_dpp v120, v128, v132 row_shl:14 row_mask:0xf bank_mask:0xf bound_ctrl:1
	v_add_f32_dpp v128, v128, v128 row_shr:2 row_mask:0xf bank_mask:0xf bound_ctrl:1
	v_add_f32_dpp v132, v121, v121 row_shr:2 row_mask:0xf bank_mask:0xf bound_ctrl:1
	v_add_f32_dpp v121, v129, v132 row_shl:14 row_mask:0xf bank_mask:0xf bound_ctrl:1
	v_add_f32_dpp v129, v129, v129 row_shr:2 row_mask:0xf bank_mask:0xf bound_ctrl:1
	v_add_f32_dpp v132, v122, v122 row_shr:2 row_mask:0xf bank_mask:0xf bound_ctrl:1
	v_add_f32_dpp v122, v130, v132 row_shl:14 row_mask:0xf bank_mask:0xf bound_ctrl:1
	v_add_f32_dpp v130, v130, v130 row_shr:2 row_mask:0xf bank_mask:0xf bound_ctrl:1
	v_add_f32_dpp v132, v123, v123 row_shr:2 row_mask:0xf bank_mask:0xf bound_ctrl:1
	v_add_f32_dpp v123, v131, v132 row_shl:14 row_mask:0xf bank_mask:0xf bound_ctrl:1
	v_add_f32_dpp v131, v131, v131 row_shr:2 row_mask:0xf bank_mask:0xf bound_ctrl:1
	v_add_f32_dpp v132, v116, v116 row_shr:4 row_mask:0xf bank_mask:0xf bound_ctrl:1
	v_add_f32_dpp v116, v124, v132 row_shl:12 row_mask:0xf bank_mask:0xf bound_ctrl:1
	v_add_f32_dpp v124, v124, v124 row_shr:4 row_mask:0xf bank_mask:0xf bound_ctrl:1
	v_add_f32_dpp v132, v117, v117 row_shr:4 row_mask:0xf bank_mask:0xf bound_ctrl:1
	v_add_f32_dpp v117, v125, v132 row_shl:12 row_mask:0xf bank_mask:0xf bound_ctrl:1
	v_add_f32_dpp v125, v125, v125 row_shr:4 row_mask:0xf bank_mask:0xf bound_ctrl:1
; #define GAS __attribute__((address_space(1)))
; __device__ __forceinline__ void unpack8(const v4u w, float (&f)[8]) { f[0] = bf_lo(w.x); f[1] = bf_hi(w.x); f[2] = bf_lo(w.y); f[3] = bf_hi(w.y); f[4] = bf_lo(w.z); f[5] = bf_hi(w.z); f[6] = bf_lo(w.w); f[7] = bf_hi(w.w); }
; __device__ __forceinline__ v4u pack8(const float (&f)[8]) { v4u w; w.x = cvt_pk_bf16(f[0], f[1]); w.y = cvt_pk_bf16(f[2], f[3]); w.z = cvt_pk_bf16(f[4], f[5]); w.w = cvt_pk_bf16(f[6], f[7]); return w; }
; template <int W> __device__ __forceinline__ void pool_group(const bf16* zrow  , const bf16* pw  , bf16* orow  , int pos, bool prev_ok) {
;     ...
;     for (int kk = 0; kk < 4; ++kk) {
;         if (kk < 3) {
; #pragma unroll
;             for (int dt = 0; dt < 8; ++dt) aw[(kk + 1) & 1][dt] = *(const GAS v4u*)(pw + (size_t)16 * dt * 128 + 32 * (kk + 1)); }
;         float own[8], c[8], p[8];
;         unpack8(cw[kk], own); unpack8(pv[kk], p);
; #pragma unroll
;         for (int j = 0; j < 8; ++j) c[j] = own[j];
;         win_step<1>(c, p);
;         if (W >= 4) win_step<2>(c, p);
;         if (W >= 8) win_step<4>(c, p);
;         if (W >= 16) win_step<8>(c, p);
;         float pl[8];
; #pragma unroll
;         for (int j = 0; j < 8; ++j) pl[j] = c[j] * inv - own[j];
;         const v4u pwk = pack8(pl); const bf16x8 pf = __builtin_bit_cast(bf16x8, pwk);
; #pragma unroll
;         for (int dt = 0; dt < 8; ++dt) acc[dt] = __builtin_amdgcn_mfma_f32_16x16x32_bf16(__builtin_bit_cast(bf16x8, aw[kk & 1][dt]), pf, acc[dt], 0, 0, 0);
;     }
	v_add_f32_dpp v132, v118, v118 row_shr:4 row_mask:0xf bank_mask:0xf bound_ctrl:1
	v_add_f32_dpp v118, v126, v132 row_shl:12 row_mask:0xf bank_mask:0xf bound_ctrl:1
	v_add_f32_dpp v126, v126, v126 row_shr:4 row_mask:0xf bank_mask:0xf bound_ctrl:1
	v_add_f32_dpp v132, v119, v119 row_shr:4 row_mask:0xf bank_mask:0xf bound_ctrl:1
	v_add_f32_dpp v119, v127, v132 row_shl:12 row_mask:0xf bank_mask:0xf bound_ctrl:1
	v_add_f32_dpp v127, v127, v127 row_shr:4 row_mask:0xf bank_mask:0xf bound_ctrl:1
	v_add_f32_dpp v132, v120, v120 row_shr:4 row_mask:0xf bank_mask:0xf bound_ctrl:1
	v_add_f32_dpp v120, v128, v132 row_shl:12 row_mask:0xf bank_mask:0xf bound_ctrl:1
	v_add_f32_dpp v128, v128, v128 row_shr:4 row_mask:0xf bank_mask:0xf bound_ctrl:1
	v_add_f32_dpp v132, v121, v121 row_shr:4 row_mask:0xf bank_mask:0xf bound_ctrl:1
	v_add_f32_dpp v121, v129, v132 row_shl:12 row_mask:0xf bank_mask:0xf bound_ctrl:1
	v_add_f32_dpp v129, v129, v129 row_shr:4 row_mask:0xf bank_mask:0xf bound_ctrl:1
	v_add_f32_dpp v132, v122, v122 row_shr:4 row_mask:0xf bank_mask:0xf bound_ctrl:1
	v_add_f32_dpp v122, v130, v132 row_shl:12 row_mask:0xf bank_mask:0xf bound_ctrl:1
	v_add_f32_dpp v130, v130, v130 row_shr:4 row_mask:0xf bank_mask:0xf bound_ctrl:1
	v_add_f32_dpp v132, v123, v123 row_shr:4 row_mask:0xf bank_mask:0xf bound_ctrl:1
	v_add_f32_dpp v123, v131, v132 row_shl:12 row_mask:0xf bank_mask:0xf bound_ctrl:1
	v_add_f32_dpp v131, v131, v131 row_shr:4 row_mask:0xf bank_mask:0xf bound_ctrl:1
	v_fma_f32 v116, v116, v138, -v108
	v_fma_f32 v117, v117, v138, -v109
	v_fma_f32 v118, v118, v138, -v110
	v_fma_f32 v119, v119, v138, -v111
	v_fma_f32 v120, v120, v138, -v112
	v_fma_f32 v121, v121, v138, -v113
	v_fma_f32 v122, v122, v138, -v114
	v_fma_f32 v123, v123, v138, -v115
	v_cvt_pk_bf16_f32 v134, v116, v117
	v_cvt_pk_bf16_f32 v135, v118, v119
	v_cvt_pk_bf16_f32 v136, v120, v121
	v_cvt_pk_bf16_f32 v137, v122, v123
	s_waitcnt lgkmcnt(0)
	s_nop 0
	v_mfma_f32_16x16x32_bf16 v[76:79], v[44:47], v[134:137], v[76:79]
	v_mfma_f32_16x16x32_bf16 v[80:83], v[48:51], v[134:137], v[80:83]
	v_mfma_f32_16x16x32_bf16 v[84:87], v[52:55], v[134:137], v[84:87]
	v_mfma_f32_16x16x32_bf16 v[88:91], v[56:59], v[134:137], v[88:91]
	v_mfma_f32_16x16x32_bf16 v[92:95], v[60:63], v[134:137], v[92:95]
	v_mfma_f32_16x16x32_bf16 v[96:99], v[64:67], v[134:137], v[96:99]
	v_mfma_f32_16x16x32_bf16 v[100:103], v[68:71], v[134:137], v[100:103]
	v_mfma_f32_16x16x32_bf16 v[104:107], v[72:75], v[134:137], v[104:107]
	v_add_u32_e32 v147, 65536, v145
	ds_read_b128 v[44:47], v147
	ds_read_b128 v[48:51], v147 offset:4096
	ds_read_b128 v[52:55], v147 offset:8192
	ds_read_b128 v[56:59], v147 offset:12288
	ds_read_b128 v[60:63], v147 offset:16384
	ds_read_b128 v[64:67], v147 offset:20480
	ds_read_b128 v[68:71], v147 offset:24576
	ds_read_b128 v[72:75], v147 offset:28672
	s_waitcnt vmcnt(14)
	v_lshlrev_b32_e32 v108, 16, v28
	v_and_b32_e32 v109, 0xffff0000, v28
	v_lshlrev_b32_e32 v110, 16, v29
	v_and_b32_e32 v111, 0xffff0000, v29
	v_lshlrev_b32_e32 v112, 16, v30
	v_and_b32_e32 v113, 0xffff0000, v30
	v_lshlrev_b32_e32 v114, 16, v31
	v_and_b32_e32 v115, 0xffff0000, v31
	v_lshlrev_b32_e32 v124, 16, v32
	v_and_b32_e32 v125, 0xffff0000, v32
	v_lshlrev_b32_e32 v126, 16, v33
	v_and_b32_e32 v127, 0xffff0000, v33
	v_lshlrev_b32_e32 v128, 16, v34
	v_and_b32_e32 v129, 0xffff0000, v34
	v_lshlrev_b32_e32 v130, 16, v35
	v_and_b32_e32 v131, 0xffff0000, v35
	v_cndmask_b32_e64 v124, 0, v124, s[40:41]
	v_cndmask_b32_e64 v125, 0, v125, s[40:41]
	v_cndmask_b32_e64 v126, 0, v126, s[40:41]
	v_cndmask_b32_e64 v127, 0, v127, s[40:41]
	v_cndmask_b32_e64 v128, 0, v128, s[40:41]
	v_cndmask_b32_e64 v129, 0, v129, s[40:41]
	v_cndmask_b32_e64 v130, 0, v130, s[40:41]
	v_cndmask_b32_e64 v131, 0, v131, s[40:41]
	global_load_dwordx4 v[28:31], v11, s[38:39] offset:896
	global_load_dwordx4 v[32:35], v11, s[48:49] offset:896
	v_mov_b32_e32 v116, v108
	v_mov_b32_e32 v117, v109
	v_mov_b32_e32 v118, v110
	v_mov_b32_e32 v119, v111
	v_mov_b32_e32 v120, v112
	v_mov_b32_e32 v121, v113
	v_mov_b32_e32 v122, v114
	v_mov_b32_e32 v123, v115
	v_add_f32_dpp v132, v116, v116 row_shr:1 row_mask:0xf bank_mask:0xf bound_ctrl:1
	v_add_f32_dpp v116, v124, v132 row_shl:15 row_mask:0xf bank_mask:0xf bound_ctrl:1
	v_add_f32_dpp v124, v124, v124 row_shr:1 row_mask:0xf bank_mask:0xf bound_ctrl:1
	v_add_f32_dpp v132, v117, v117 row_shr:1 row_mask:0xf bank_mask:0xf bound_ctrl:1
	v_add_f32_dpp v117, v125, v132 row_shl:15 row_mask:0xf bank_mask:0xf bound_ctrl:1
	v_add_f32_dpp v125, v125, v125 row_shr:1 row_mask:0xf bank_mask:0xf bound_ctrl:1
	v_add_f32_dpp v132, v118, v118 row_shr:1 row_mask:0xf bank_mask:0xf bound_ctrl:1
	v_add_f32_dpp v118, v126, v132 row_shl:15 row_mask:0xf bank_mask:0xf bound_ctrl:1
	v_add_f32_dpp v126, v126, v126 row_shr:1 row_mask:0xf bank_mask:0xf bound_ctrl:1
	v_add_f32_dpp v132, v119, v119 row_shr:1 row_mask:0xf bank_mask:0xf bound_ctrl:1
	v_add_f32_dpp v119, v127, v132 row_shl:15 row_mask:0xf bank_mask:0xf bound_ctrl:1
	v_add_f32_dpp v127, v127, v127 row_shr:1 row_mask:0xf bank_mask:0xf bound_ctrl:1
	v_add_f32_dpp v132, v120, v120 row_shr:1 row_mask:0xf bank_mask:0xf bound_ctrl:1
	v_add_f32_dpp v120, v128, v132 row_shl:15 row_mask:0xf bank_mask:0xf bound_ctrl:1
	v_add_f32_dpp v128, v128, v128 row_shr:1 row_mask:0xf bank_mask:0xf bound_ctrl:1
	v_add_f32_dpp v132, v121, v121 row_shr:1 row_mask:0xf bank_mask:0xf bound_ctrl:1
	v_add_f32_dpp v121, v129, v132 row_shl:15 row_mask:0xf bank_mask:0xf bound_ctrl:1
	v_add_f32_dpp v129, v129, v129 row_shr:1 row_mask:0xf bank_mask:0xf bound_ctrl:1
	v_add_f32_dpp v132, v122, v122 row_shr:1 row_mask:0xf bank_mask:0xf bound_ctrl:1
; #define GAS __attribute__((address_space(1)))
; __device__ __forceinline__ void unpack8(const v4u w, float (&f)[8]) { f[0] = bf_lo(w.x); f[1] = bf_hi(w.x); f[2] = bf_lo(w.y); f[3] = bf_hi(w.y); f[4] = bf_lo(w.z); f[5] = bf_hi(w.z); f[6] = bf_lo(w.w); f[7] = bf_hi(w.w); }
; __device__ __forceinline__ v4u pack8(const float (&f)[8]) { v4u w; w.x = cvt_pk_bf16(f[0], f[1]); w.y = cvt_pk_bf16(f[2], f[3]); w.z = cvt_pk_bf16(f[4], f[5]); w.w = cvt_pk_bf16(f[6], f[7]); return w; }
; template <int W> __device__ __forceinline__ void pool_group(const bf16* zrow  , const bf16* pw  , bf16* orow  , int pos, bool prev_ok) {
;     ...
;     for (int kk = 0; kk < 4; ++kk) {
;         if (kk < 3) {
; #pragma unroll
;             for (int dt = 0; dt < 8; ++dt) aw[(kk + 1) & 1][dt] = *(const GAS v4u*)(pw + (size_t)16 * dt * 128 + 32 * (kk + 1)); }
;         float own[8], c[8], p[8];
;         unpack8(cw[kk], own); unpack8(pv[kk], p);
; #pragma unroll
;         for (int j = 0; j < 8; ++j) c[j] = own[j];
;         win_step<1>(c, p);
;         if (W >= 4) win_step<2>(c, p);
;         if (W >= 8) win_step<4>(c, p);
;         if (W >= 16) win_step<8>(c, p);
;         float pl[8];
; #pragma unroll
;         for (int j = 0; j < 8; ++j) pl[j] = c[j] * inv - own[j];
;         const v4u pwk = pack8(pl); const bf16x8 pf = __builtin_bit_cast(bf16x8, pwk);
; #pragma unroll
;         for (int dt = 0; dt < 8; ++dt) acc[dt] = __builtin_amdgcn_mfma_f32_16x16x32_bf16(__builtin_bit_cast(bf16x8, aw[kk & 1][dt]), pf, acc[dt], 0, 0, 0);
;     }
	v_add_f32_dpp v122, v130, v132 row_shl:15 row_mask:0xf bank_mask:0xf bound_ctrl:1
	v_add_f32_dpp v130, v130, v130 row_shr:1 row_mask:0xf bank_mask:0xf bound_ctrl:1
	v_add_f32_dpp v132, v123, v123 row_shr:1 row_mask:0xf bank_mask:0xf bound_ctrl:1
	v_add_f32_dpp v123, v131, v132 row_shl:15 row_mask:0xf bank_mask:0xf bound_ctrl:1
	v_add_f32_dpp v131, v131, v131 row_shr:1 row_mask:0xf bank_mask:0xf bound_ctrl:1
	v_add_f32_dpp v132, v116, v116 row_shr:2 row_mask:0xf bank_mask:0xf bound_ctrl:1
	v_add_f32_dpp v116, v124, v132 row_shl:14 row_mask:0xf bank_mask:0xf bound_ctrl:1
	v_add_f32_dpp v124, v124, v124 row_shr:2 row_mask:0xf bank_mask:0xf bound_ctrl:1
	v_add_f32_dpp v132, v117, v117 row_shr:2 row_mask:0xf bank_mask:0xf bound_ctrl:1
	v_add_f32_dpp v117, v125, v132 row_shl:14 row_mask:0xf bank_mask:0xf bound_ctrl:1
	v_add_f32_dpp v125, v125, v125 row_shr:2 row_mask:0xf bank_mask:0xf bound_ctrl:1
	v_add_f32_dpp v132, v118, v118 row_shr:2 row_mask:0xf bank_mask:0xf bound_ctrl:1
	v_add_f32_dpp v118, v126, v132 row_shl:14 row_mask:0xf bank_mask:0xf bound_ctrl:1
	v_add_f32_dpp v126, v126, v126 row_shr:2 row_mask:0xf bank_mask:0xf bound_ctrl:1
	v_add_f32_dpp v132, v119, v119 row_shr:2 row_mask:0xf bank_mask:0xf bound_ctrl:1
	v_add_f32_dpp v119, v127, v132 row_shl:14 row_mask:0xf bank_mask:0xf bound_ctrl:1
	v_add_f32_dpp v127, v127, v127 row_shr:2 row_mask:0xf bank_mask:0xf bound_ctrl:1
	v_add_f32_dpp v132, v120, v120 row_shr:2 row_mask:0xf bank_mask:0xf bound_ctrl:1
	v_add_f32_dpp v120, v128, v132 row_shl:14 row_mask:0xf bank_mask:0xf bound_ctrl:1
	v_add_f32_dpp v128, v128, v128 row_shr:2 row_mask:0xf bank_mask:0xf bound_ctrl:1
	v_add_f32_dpp v132, v121, v121 row_shr:2 row_mask:0xf bank_mask:0xf bound_ctrl:1
	v_add_f32_dpp v121, v129, v132 row_shl:14 row_mask:0xf bank_mask:0xf bound_ctrl:1
	v_add_f32_dpp v129, v129, v129 row_shr:2 row_mask:0xf bank_mask:0xf bound_ctrl:1
	v_add_f32_dpp v132, v122, v122 row_shr:2 row_mask:0xf bank_mask:0xf bound_ctrl:1
	v_add_f32_dpp v122, v130, v132 row_shl:14 row_mask:0xf bank_mask:0xf bound_ctrl:1
	v_add_f32_dpp v130, v130, v130 row_shr:2 row_mask:0xf bank_mask:0xf bound_ctrl:1
	v_add_f32_dpp v132, v123, v123 row_shr:2 row_mask:0xf bank_mask:0xf bound_ctrl:1
	v_add_f32_dpp v123, v131, v132 row_shl:14 row_mask:0xf bank_mask:0xf bound_ctrl:1
	v_add_f32_dpp v131, v131, v131 row_shr:2 row_mask:0xf bank_mask:0xf bound_ctrl:1
	v_add_f32_dpp v132, v116, v116 row_shr:4 row_mask:0xf bank_mask:0xf bound_ctrl:1
	v_add_f32_dpp v116, v124, v132 row_shl:12 row_mask:0xf bank_mask:0xf bound_ctrl:1
	v_add_f32_dpp v124, v124, v124 row_shr:4 row_mask:0xf bank_mask:0xf bound_ctrl:1
	v_add_f32_dpp v132, v117, v117 row_shr:4 row_mask:0xf bank_mask:0xf bound_ctrl:1
	v_add_f32_dpp v117, v125, v132 row_shl:12 row_mask:0xf bank_mask:0xf bound_ctrl:1
	v_add_f32_dpp v125, v125, v125 row_shr:4 row_mask:0xf bank_mask:0xf bound_ctrl:1
	v_add_f32_dpp v132, v118, v118 row_shr:4 row_mask:0xf bank_mask:0xf bound_ctrl:1
	v_add_f32_dpp v118, v126, v132 row_shl:12 row_mask:0xf bank_mask:0xf bound_ctrl:1
	v_add_f32_dpp v126, v126, v126 row_shr:4 row_mask:0xf bank_mask:0xf bound_ctrl:1
	v_add_f32_dpp v132, v119, v119 row_shr:4 row_mask:0xf bank_mask:0xf bound_ctrl:1
	v_add_f32_dpp v119, v127, v132 row_shl:12 row_mask:0xf bank_mask:0xf bound_ctrl:1
	v_add_f32_dpp v127, v127, v127 row_shr:4 row_mask:0xf bank_mask:0xf bound_ctrl:1
	v_add_f32_dpp v132, v120, v120 row_shr:4 row_mask:0xf bank_mask:0xf bound_ctrl:1
	v_add_f32_dpp v120, v128, v132 row_shl:12 row_mask:0xf bank_mask:0xf bound_ctrl:1
	v_add_f32_dpp v128, v128, v128 row_shr:4 row_mask:0xf bank_mask:0xf bound_ctrl:1
	v_add_f32_dpp v132, v121, v121 row_shr:4 row_mask:0xf bank_mask:0xf bound_ctrl:1
	v_add_f32_dpp v121, v129, v132 row_shl:12 row_mask:0xf bank_mask:0xf bound_ctrl:1
	v_add_f32_dpp v129, v129, v129 row_shr:4 row_mask:0xf bank_mask:0xf bound_ctrl:1
	v_add_f32_dpp v132, v122, v122 row_shr:4 row_mask:0xf bank_mask:0xf bound_ctrl:1
	v_add_f32_dpp v122, v130, v132 row_shl:12 row_mask:0xf bank_mask:0xf bound_ctrl:1
	v_add_f32_dpp v130, v130, v130 row_shr:4 row_mask:0xf bank_mask:0xf bound_ctrl:1
	v_add_f32_dpp v132, v123, v123 row_shr:4 row_mask:0xf bank_mask:0xf bound_ctrl:1
	v_add_f32_dpp v123, v131, v132 row_shl:12 row_mask:0xf bank_mask:0xf bound_ctrl:1
	v_add_f32_dpp v131, v131, v131 row_shr:4 row_mask:0xf bank_mask:0xf bound_ctrl:1
	v_fma_f32 v116, v116, v138, -v108
	v_fma_f32 v117, v117, v138, -v109
	v_fma_f32 v118, v118, v138, -v110
	v_fma_f32 v119, v119, v138, -v111
	v_fma_f32 v120, v120, v138, -v112
	v_fma_f32 v121, v121, v138, -v113
	v_fma_f32 v122, v122, v138, -v114
	v_fma_f32 v123, v123, v138, -v115
	v_cvt_pk_bf16_f32 v134, v116, v117
	v_cvt_pk_bf16_f32 v135, v118, v119
	v_cvt_pk_bf16_f32 v136, v120, v121
	v_cvt_pk_bf16_f32 v137, v122, v123
	s_waitcnt lgkmcnt(0)
	s_nop 0
	v_mfma_f32_16x16x32_bf16 v[76:79], v[44:47], v[134:137], v[76:79]
	v_mfma_f32_16x16x32_bf16 v[80:83], v[48:51], v[134:137], v[80:83]
	v_mfma_f32_16x16x32_bf16 v[84:87], v[52:55], v[134:137], v[84:87]
	v_mfma_f32_16x16x32_bf16 v[88:91], v[56:59], v[134:137], v[88:91]
	v_mfma_f32_16x16x32_bf16 v[92:95], v[60:63], v[134:137], v[92:95]
	v_mfma_f32_16x16x32_bf16 v[96:99], v[64:67], v[134:137], v[96:99]
	v_mfma_f32_16x16x32_bf16 v[100:103], v[68:71], v[134:137], v[100:103]
	v_mfma_f32_16x16x32_bf16 v[104:107], v[72:75], v[134:137], v[104:107]
	v_add_u32_e32 v147, 65536, v146
	ds_read_b128 v[44:47], v147
	ds_read_b128 v[48:51], v147 offset:4096
	ds_read_b128 v[52:55], v147 offset:8192
	ds_read_b128 v[56:59], v147 offset:12288
	ds_read_b128 v[60:63], v147 offset:16384
	ds_read_b128 v[64:67], v147 offset:20480
	ds_read_b128 v[68:71], v147 offset:24576
	ds_read_b128 v[72:75], v147 offset:28672
	s_waitcnt vmcnt(14)
; #define GAS __attribute__((address_space(1)))
; __device__ __forceinline__ void unpack8(const v4u w, float (&f)[8]) { f[0] = bf_lo(w.x); f[1] = bf_hi(w.x); f[2] = bf_lo(w.y); f[3] = bf_hi(w.y); f[4] = bf_lo(w.z); f[5] = bf_hi(w.z); f[6] = bf_lo(w.w); f[7] = bf_hi(w.w); }
; template <int W> __device__ __forceinline__ void pool_group(const bf16* zrow  , const bf16* pw  , bf16* orow  , int pos, bool prev_ok) {
;     ...
;             for (int dt = 0; dt < 8; ++dt) aw[(kk + 1) & 1][dt] = *(const GAS v4u*)(pw + (size_t)16 * dt * 128 + 32 * (kk + 1)); }
;         float own[8], c[8], p[8];
;         unpack8(cw[kk], own); unpack8(pv[kk], p);
; #pragma unroll
;         for (int j = 0; j < 8; ++j) c[j] = own[j];
;         win_step<1>(c, p);
;         if (W >= 4) win_step<2>(c, p);
;         if (W >= 8) win_step<4>(c, p);
;         if (W >= 16) win_step<8>(c, p);
	v_lshlrev_b32_e32 v108, 16, v36
	v_and_b32_e32 v109, 0xffff0000, v36
	v_lshlrev_b32_e32 v110, 16, v37
	v_and_b32_e32 v111, 0xffff0000, v37
	v_lshlrev_b32_e32 v112, 16, v38
	v_and_b32_e32 v113, 0xffff0000, v38
	v_lshlrev_b32_e32 v114, 16, v39
	v_and_b32_e32 v115, 0xffff0000, v39
	v_lshlrev_b32_e32 v124, 16, v40
	v_and_b32_e32 v125, 0xffff0000, v40
	v_lshlrev_b32_e32 v126, 16, v41
	v_and_b32_e32 v127, 0xffff0000, v41
	v_lshlrev_b32_e32 v128, 16, v42
	v_and_b32_e32 v129, 0xffff0000, v42
	v_lshlrev_b32_e32 v130, 16, v43
	v_and_b32_e32 v131, 0xffff0000, v43
	v_cndmask_b32_e64 v124, 0, v124, s[40:41]
	v_cndmask_b32_e64 v125, 0, v125, s[40:41]
	v_cndmask_b32_e64 v126, 0, v126, s[40:41]
	v_cndmask_b32_e64 v127, 0, v127, s[40:41]
	v_cndmask_b32_e64 v128, 0, v128, s[40:41]
	v_cndmask_b32_e64 v129, 0, v129, s[40:41]
	v_cndmask_b32_e64 v130, 0, v130, s[40:41]
	v_cndmask_b32_e64 v131, 0, v131, s[40:41]
	global_load_dwordx4 v[36:39], v11, s[38:39] offset:960
	global_load_dwordx4 v[40:43], v11, s[48:49] offset:960
	v_mov_b32_e32 v116, v108
	v_mov_b32_e32 v117, v109
	v_mov_b32_e32 v118, v110
	v_mov_b32_e32 v119, v111
	v_mov_b32_e32 v120, v112
	v_mov_b32_e32 v121, v113
	v_mov_b32_e32 v122, v114
	v_mov_b32_e32 v123, v115
	v_add_f32_dpp v132, v116, v116 row_shr:1 row_mask:0xf bank_mask:0xf bound_ctrl:1
	v_add_f32_dpp v116, v124, v132 row_shl:15 row_mask:0xf bank_mask:0xf bound_ctrl:1
	v_add_f32_dpp v124, v124, v124 row_shr:1 row_mask:0xf bank_mask:0xf bound_ctrl:1
	v_add_f32_dpp v132, v117, v117 row_shr:1 row_mask:0xf bank_mask:0xf bound_ctrl:1
	v_add_f32_dpp v117, v125, v132 row_shl:15 row_mask:0xf bank_mask:0xf bound_ctrl:1
	v_add_f32_dpp v125, v125, v125 row_shr:1 row_mask:0xf bank_mask:0xf bound_ctrl:1
	v_add_f32_dpp v132, v118, v118 row_shr:1 row_mask:0xf bank_mask:0xf bound_ctrl:1
	v_add_f32_dpp v118, v126, v132 row_shl:15 row_mask:0xf bank_mask:0xf bound_ctrl:1
	v_add_f32_dpp v126, v126, v126 row_shr:1 row_mask:0xf bank_mask:0xf bound_ctrl:1
	v_add_f32_dpp v132, v119, v119 row_shr:1 row_mask:0xf bank_mask:0xf bound_ctrl:1
	v_add_f32_dpp v119, v127, v132 row_shl:15 row_mask:0xf bank_mask:0xf bound_ctrl:1
	v_add_f32_dpp v127, v127, v127 row_shr:1 row_mask:0xf bank_mask:0xf bound_ctrl:1
	v_add_f32_dpp v132, v120, v120 row_shr:1 row_mask:0xf bank_mask:0xf bound_ctrl:1
	v_add_f32_dpp v120, v128, v132 row_shl:15 row_mask:0xf bank_mask:0xf bound_ctrl:1
	v_add_f32_dpp v128, v128, v128 row_shr:1 row_mask:0xf bank_mask:0xf bound_ctrl:1
	v_add_f32_dpp v132, v121, v121 row_shr:1 row_mask:0xf bank_mask:0xf bound_ctrl:1
	v_add_f32_dpp v121, v129, v132 row_shl:15 row_mask:0xf bank_mask:0xf bound_ctrl:1
	v_add_f32_dpp v129, v129, v129 row_shr:1 row_mask:0xf bank_mask:0xf bound_ctrl:1
	v_add_f32_dpp v132, v122, v122 row_shr:1 row_mask:0xf bank_mask:0xf bound_ctrl:1
	v_add_f32_dpp v122, v130, v132 row_shl:15 row_mask:0xf bank_mask:0xf bound_ctrl:1
	v_add_f32_dpp v130, v130, v130 row_shr:1 row_mask:0xf bank_mask:0xf bound_ctrl:1
	v_add_f32_dpp v132, v123, v123 row_shr:1 row_mask:0xf bank_mask:0xf bound_ctrl:1
	v_add_f32_dpp v123, v131, v132 row_shl:15 row_mask:0xf bank_mask:0xf bound_ctrl:1
	v_add_f32_dpp v131, v131, v131 row_shr:1 row_mask:0xf bank_mask:0xf bound_ctrl:1
	v_add_f32_dpp v132, v116, v116 row_shr:2 row_mask:0xf bank_mask:0xf bound_ctrl:1
	v_add_f32_dpp v116, v124, v132 row_shl:14 row_mask:0xf bank_mask:0xf bound_ctrl:1
	v_add_f32_dpp v124, v124, v124 row_shr:2 row_mask:0xf bank_mask:0xf bound_ctrl:1
	v_add_f32_dpp v132, v117, v117 row_shr:2 row_mask:0xf bank_mask:0xf bound_ctrl:1
	v_add_f32_dpp v117, v125, v132 row_shl:14 row_mask:0xf bank_mask:0xf bound_ctrl:1
	v_add_f32_dpp v125, v125, v125 row_shr:2 row_mask:0xf bank_mask:0xf bound_ctrl:1
	v_add_f32_dpp v132, v118, v118 row_shr:2 row_mask:0xf bank_mask:0xf bound_ctrl:1
	v_add_f32_dpp v118, v126, v132 row_shl:14 row_mask:0xf bank_mask:0xf bound_ctrl:1
	v_add_f32_dpp v126, v126, v126 row_shr:2 row_mask:0xf bank_mask:0xf bound_ctrl:1
	v_add_f32_dpp v132, v119, v119 row_shr:2 row_mask:0xf bank_mask:0xf bound_ctrl:1
	v_add_f32_dpp v119, v127, v132 row_shl:14 row_mask:0xf bank_mask:0xf bound_ctrl:1
	v_add_f32_dpp v127, v127, v127 row_shr:2 row_mask:0xf bank_mask:0xf bound_ctrl:1
	v_add_f32_dpp v132, v120, v120 row_shr:2 row_mask:0xf bank_mask:0xf bound_ctrl:1
	v_add_f32_dpp v120, v128, v132 row_shl:14 row_mask:0xf bank_mask:0xf bound_ctrl:1
	v_add_f32_dpp v128, v128, v128 row_shr:2 row_mask:0xf bank_mask:0xf bound_ctrl:1
	v_add_f32_dpp v132, v121, v121 row_shr:2 row_mask:0xf bank_mask:0xf bound_ctrl:1
	v_add_f32_dpp v121, v129, v132 row_shl:14 row_mask:0xf bank_mask:0xf bound_ctrl:1
	v_add_f32_dpp v129, v129, v129 row_shr:2 row_mask:0xf bank_mask:0xf bound_ctrl:1
	v_add_f32_dpp v132, v122, v122 row_shr:2 row_mask:0xf bank_mask:0xf bound_ctrl:1
	v_add_f32_dpp v122, v130, v132 row_shl:14 row_mask:0xf bank_mask:0xf bound_ctrl:1
	v_add_f32_dpp v130, v130, v130 row_shr:2 row_mask:0xf bank_mask:0xf bound_ctrl:1
	v_add_f32_dpp v132, v123, v123 row_shr:2 row_mask:0xf bank_mask:0xf bound_ctrl:1
	v_add_f32_dpp v123, v131, v132 row_shl:14 row_mask:0xf bank_mask:0xf bound_ctrl:1
	v_add_f32_dpp v131, v131, v131 row_shr:2 row_mask:0xf bank_mask:0xf bound_ctrl:1
	v_add_f32_dpp v132, v116, v116 row_shr:4 row_mask:0xf bank_mask:0xf bound_ctrl:1
	v_add_f32_dpp v116, v124, v132 row_shl:12 row_mask:0xf bank_mask:0xf bound_ctrl:1
	v_add_f32_dpp v124, v124, v124 row_shr:4 row_mask:0xf bank_mask:0xf bound_ctrl:1
	v_add_f32_dpp v132, v117, v117 row_shr:4 row_mask:0xf bank_mask:0xf bound_ctrl:1
	v_add_f32_dpp v117, v125, v132 row_shl:12 row_mask:0xf bank_mask:0xf bound_ctrl:1
	v_add_f32_dpp v125, v125, v125 row_shr:4 row_mask:0xf bank_mask:0xf bound_ctrl:1
; __device__ __forceinline__ unsigned cvt_pk_bf16(float lo, float hi) { return __builtin_bit_cast(unsigned, __builtin_convertvector((f32x2_t){lo, hi}, bf16x2_t)); }
; #define GAS __attribute__((address_space(1)))
; __device__ __forceinline__ void unpack8(const v4u w, float (&f)[8]) { f[0] = bf_lo(w.x); f[1] = bf_hi(w.x); f[2] = bf_lo(w.y); f[3] = bf_hi(w.y); f[4] = bf_lo(w.z); f[5] = bf_hi(w.z); f[6] = bf_lo(w.w); f[7] = bf_hi(w.w); }
; template <int W> __device__ __forceinline__ void pool_group(const bf16* zrow  , const bf16* pw  , bf16* orow  , int pos, bool prev_ok) {
;     const float inv = 1.0f / (float)((pos + 1) < W ? (pos + 1) : W);
;     f32x4 acc[8];
; #pragma unroll
;     for (int dt = 0; dt < 8; ++dt) acc[dt] = (f32x4){0.f, 0.f, 0.f, 0.f};
;     v4u cw[4], pv[4], aw[2][8];
; #pragma unroll
;     for (int kk = 0; kk < 4; ++kk) { cw[kk] = *(const GAS v4u*)(zrow + 32 * kk); pv[kk] = prev_ok ? *(const GAS v4u*)(zrow + 32 * kk - (ptrdiff_t)16 * ZC) : (v4u){0u, 0u, 0u, 0u}; }
; #pragma unroll
;     for (int dt = 0; dt < 8; ++dt) aw[0][dt] = *(const GAS v4u*)(pw + (size_t)16 * dt * 128);
; #pragma unroll
;     for (int kk = 0; kk < 4; ++kk) {
;         if (kk < 3) {
; #pragma unroll
;             for (int dt = 0; dt < 8; ++dt) aw[(kk + 1) & 1][dt] = *(const GAS v4u*)(pw + (size_t)16 * dt * 128 + 32 * (kk + 1)); }
;         float own[8], c[8], p[8];
;         unpack8(cw[kk], own); unpack8(pv[kk], p);
; #pragma unroll
;         for (int j = 0; j < 8; ++j) c[j] = own[j];
;         win_step<1>(c, p);
;         if (W >= 4) win_step<2>(c, p);
;         if (W >= 8) win_step<4>(c, p);
;         if (W >= 16) win_step<8>(c, p);
;         float pl[8];
; #pragma unroll
;         for (int j = 0; j < 8; ++j) pl[j] = c[j] * inv - own[j];
;         const v4u pwk = pack8(pl); const bf16x8 pf = __builtin_bit_cast(bf16x8, pwk);
; #pragma unroll
;         for (int dt = 0; dt < 8; ++dt) acc[dt] = __builtin_amdgcn_mfma_f32_16x16x32_bf16(__builtin_bit_cast(bf16x8, aw[kk & 1][dt]), pf, acc[dt], 0, 0, 0);
;     }
; #pragma unroll
;     for (int dt = 0; dt < 8; ++dt) { v2u w; w.x = cvt_pk_bf16(acc[dt][0], acc[dt][1]); w.y = cvt_pk_bf16(acc[dt][2], acc[dt][3]); *(GAS v2u*)(orow + 16 * dt) = w; }
	v_add_f32_dpp v132, v118, v118 row_shr:4 row_mask:0xf bank_mask:0xf bound_ctrl:1
	v_add_f32_dpp v118, v126, v132 row_shl:12 row_mask:0xf bank_mask:0xf bound_ctrl:1
	v_add_f32_dpp v126, v126, v126 row_shr:4 row_mask:0xf bank_mask:0xf bound_ctrl:1
	v_add_f32_dpp v132, v119, v119 row_shr:4 row_mask:0xf bank_mask:0xf bound_ctrl:1
	v_add_f32_dpp v119, v127, v132 row_shl:12 row_mask:0xf bank_mask:0xf bound_ctrl:1
	v_add_f32_dpp v127, v127, v127 row_shr:4 row_mask:0xf bank_mask:0xf bound_ctrl:1
	v_add_f32_dpp v132, v120, v120 row_shr:4 row_mask:0xf bank_mask:0xf bound_ctrl:1
	v_add_f32_dpp v120, v128, v132 row_shl:12 row_mask:0xf bank_mask:0xf bound_ctrl:1
	v_add_f32_dpp v128, v128, v128 row_shr:4 row_mask:0xf bank_mask:0xf bound_ctrl:1
	v_add_f32_dpp v132, v121, v121 row_shr:4 row_mask:0xf bank_mask:0xf bound_ctrl:1
	v_add_f32_dpp v121, v129, v132 row_shl:12 row_mask:0xf bank_mask:0xf bound_ctrl:1
	v_add_f32_dpp v129, v129, v129 row_shr:4 row_mask:0xf bank_mask:0xf bound_ctrl:1
	v_add_f32_dpp v132, v122, v122 row_shr:4 row_mask:0xf bank_mask:0xf bound_ctrl:1
	v_add_f32_dpp v122, v130, v132 row_shl:12 row_mask:0xf bank_mask:0xf bound_ctrl:1
	v_add_f32_dpp v130, v130, v130 row_shr:4 row_mask:0xf bank_mask:0xf bound_ctrl:1
	v_add_f32_dpp v132, v123, v123 row_shr:4 row_mask:0xf bank_mask:0xf bound_ctrl:1
	v_add_f32_dpp v123, v131, v132 row_shl:12 row_mask:0xf bank_mask:0xf bound_ctrl:1
	v_add_f32_dpp v131, v131, v131 row_shr:4 row_mask:0xf bank_mask:0xf bound_ctrl:1
	v_fma_f32 v116, v116, v138, -v108
	v_fma_f32 v117, v117, v138, -v109
	v_fma_f32 v118, v118, v138, -v110
	v_fma_f32 v119, v119, v138, -v111
	v_fma_f32 v120, v120, v138, -v112
	v_fma_f32 v121, v121, v138, -v113
	v_fma_f32 v122, v122, v138, -v114
	v_fma_f32 v123, v123, v138, -v115
	v_cvt_pk_bf16_f32 v134, v116, v117
	v_cvt_pk_bf16_f32 v135, v118, v119
	v_cvt_pk_bf16_f32 v136, v120, v121
	v_cvt_pk_bf16_f32 v137, v122, v123
	s_waitcnt lgkmcnt(0)
	s_nop 0
	v_mfma_f32_16x16x32_bf16 v[76:79], v[44:47], v[134:137], v[76:79]
	v_mfma_f32_16x16x32_bf16 v[80:83], v[48:51], v[134:137], v[80:83]
	v_mfma_f32_16x16x32_bf16 v[84:87], v[52:55], v[134:137], v[84:87]
	v_mfma_f32_16x16x32_bf16 v[88:91], v[56:59], v[134:137], v[88:91]
	v_mfma_f32_16x16x32_bf16 v[92:95], v[60:63], v[134:137], v[92:95]
	v_mfma_f32_16x16x32_bf16 v[96:99], v[64:67], v[134:137], v[96:99]
	v_mfma_f32_16x16x32_bf16 v[100:103], v[68:71], v[134:137], v[100:103]
	v_mfma_f32_16x16x32_bf16 v[104:107], v[72:75], v[134:137], v[104:107]
	s_nop 7
	s_nop 1
	v_cvt_pk_bf16_f32 v132, v76, v77
	v_cvt_pk_bf16_f32 v133, v78, v79
	global_store_dwordx2 v142, v[132:133], s[46:47] offset:512
	s_nop 0
	v_cvt_pk_bf16_f32 v132, v80, v81
	v_cvt_pk_bf16_f32 v133, v82, v83
	global_store_dwordx2 v142, v[132:133], s[46:47] offset:544
	s_nop 0
	v_cvt_pk_bf16_f32 v132, v84, v85
	v_cvt_pk_bf16_f32 v133, v86, v87
	global_store_dwordx2 v142, v[132:133], s[46:47] offset:576
	s_nop 0
	v_cvt_pk_bf16_f32 v132, v88, v89
	v_cvt_pk_bf16_f32 v133, v90, v91
	global_store_dwordx2 v142, v[132:133], s[46:47] offset:608
	s_nop 0
	v_cvt_pk_bf16_f32 v132, v92, v93
	v_cvt_pk_bf16_f32 v133, v94, v95
	global_store_dwordx2 v142, v[132:133], s[46:47] offset:640
	s_nop 0
	v_cvt_pk_bf16_f32 v132, v96, v97
	v_cvt_pk_bf16_f32 v133, v98, v99
	global_store_dwordx2 v142, v[132:133], s[46:47] offset:672
	s_nop 0
	v_cvt_pk_bf16_f32 v132, v100, v101
	v_cvt_pk_bf16_f32 v133, v102, v103
	global_store_dwordx2 v142, v[132:133], s[46:47] offset:704
	s_nop 0
	v_cvt_pk_bf16_f32 v132, v104, v105
	v_cvt_pk_bf16_f32 v133, v106, v107
	global_store_dwordx2 v142, v[132:133], s[46:47] offset:736
	s_nop 0
	v_min_i32_e32 v139, 16, v140
	v_cvt_f32_i32_e32 v139, v139
	v_div_scale_f32 v1, s[42:43], v139, v139, 1.0
	v_rcp_f32_e32 v2, v1
	s_nop 0
	v_fma_f32 v7, -v1, v2, 1.0
	v_fmac_f32_e32 v2, v7, v2
	v_div_scale_f32 v3, vcc, 1.0, v139, 1.0
	v_mul_f32_e32 v6, v3, v2
	v_fma_f32 v7, -v1, v6, v3
	v_fmac_f32_e32 v6, v7, v2
	v_fma_f32 v1, -v1, v6, v3
	s_nop 1
	v_div_fmas_f32 v1, v1, v2, v6
	v_div_fixup_f32 v138, v1, v139, 1.0
	v_add_u32_e32 v147, 98304, v143
	ds_read_b128 v[44:47], v147
	ds_read_b128 v[48:51], v147 offset:4096
	ds_read_b128 v[52:55], v147 offset:8192
	ds_read_b128 v[56:59], v147 offset:12288
	ds_read_b128 v[60:63], v147 offset:16384
	ds_read_b128 v[64:67], v147 offset:20480
	ds_read_b128 v[68:71], v147 offset:24576
	ds_read_b128 v[72:75], v147 offset:28672
	s_waitcnt vmcnt(14)
; #define GAS __attribute__((address_space(1)))
; __device__ __forceinline__ void unpack8(const v4u w, float (&f)[8]) { f[0] = bf_lo(w.x); f[1] = bf_hi(w.x); f[2] = bf_lo(w.y); f[3] = bf_hi(w.y); f[4] = bf_lo(w.z); f[5] = bf_hi(w.z); f[6] = bf_lo(w.w); f[7] = bf_hi(w.w); }
; template <int W> __device__ __forceinline__ void pool_group(const bf16* zrow  , const bf16* pw  , bf16* orow  , int pos, bool prev_ok) {
;     ...
;             for (int dt = 0; dt < 8; ++dt) aw[(kk + 1) & 1][dt] = *(const GAS v4u*)(pw + (size_t)16 * dt * 128 + 32 * (kk + 1)); }
;         float own[8], c[8], p[8];
;         unpack8(cw[kk], own); unpack8(pv[kk], p);
; #pragma unroll
;         for (int j = 0; j < 8; ++j) c[j] = own[j];
;         win_step<1>(c, p);
;         if (W >= 4) win_step<2>(c, p);
;         if (W >= 8) win_step<4>(c, p);
;         if (W >= 16) win_step<8>(c, p);
	v_lshlrev_b32_e32 v108, 16, v12
	v_and_b32_e32 v109, 0xffff0000, v12
	v_lshlrev_b32_e32 v110, 16, v13
	v_and_b32_e32 v111, 0xffff0000, v13
	v_lshlrev_b32_e32 v112, 16, v14
	v_and_b32_e32 v113, 0xffff0000, v14
	v_lshlrev_b32_e32 v114, 16, v15
	v_and_b32_e32 v115, 0xffff0000, v15
	v_lshlrev_b32_e32 v124, 16, v16
	v_and_b32_e32 v125, 0xffff0000, v16
	v_lshlrev_b32_e32 v126, 16, v17
	v_and_b32_e32 v127, 0xffff0000, v17
	v_lshlrev_b32_e32 v128, 16, v18
	v_and_b32_e32 v129, 0xffff0000, v18
	v_lshlrev_b32_e32 v130, 16, v19
	v_and_b32_e32 v131, 0xffff0000, v19
	v_cndmask_b32_e64 v124, 0, v124, s[40:41]
	v_cndmask_b32_e64 v125, 0, v125, s[40:41]
	v_cndmask_b32_e64 v126, 0, v126, s[40:41]
	v_cndmask_b32_e64 v127, 0, v127, s[40:41]
	v_cndmask_b32_e64 v128, 0, v128, s[40:41]
	v_cndmask_b32_e64 v129, 0, v129, s[40:41]
	v_cndmask_b32_e64 v130, 0, v130, s[40:41]
	v_cndmask_b32_e64 v131, 0, v131, s[40:41]
	v_mov_b32_e32 v116, v108
	v_mov_b32_e32 v117, v109
	v_mov_b32_e32 v118, v110
	v_mov_b32_e32 v119, v111
	v_mov_b32_e32 v120, v112
	v_mov_b32_e32 v121, v113
	v_mov_b32_e32 v122, v114
	v_mov_b32_e32 v123, v115
	v_add_f32_dpp v132, v116, v116 row_shr:1 row_mask:0xf bank_mask:0xf bound_ctrl:1
	v_add_f32_dpp v116, v124, v132 row_shl:15 row_mask:0xf bank_mask:0xf bound_ctrl:1
	v_add_f32_dpp v124, v124, v124 row_shr:1 row_mask:0xf bank_mask:0xf bound_ctrl:1
	v_add_f32_dpp v132, v117, v117 row_shr:1 row_mask:0xf bank_mask:0xf bound_ctrl:1
	v_add_f32_dpp v117, v125, v132 row_shl:15 row_mask:0xf bank_mask:0xf bound_ctrl:1
	v_add_f32_dpp v125, v125, v125 row_shr:1 row_mask:0xf bank_mask:0xf bound_ctrl:1
	v_add_f32_dpp v132, v118, v118 row_shr:1 row_mask:0xf bank_mask:0xf bound_ctrl:1
	v_add_f32_dpp v118, v126, v132 row_shl:15 row_mask:0xf bank_mask:0xf bound_ctrl:1
	v_add_f32_dpp v126, v126, v126 row_shr:1 row_mask:0xf bank_mask:0xf bound_ctrl:1
	v_add_f32_dpp v132, v119, v119 row_shr:1 row_mask:0xf bank_mask:0xf bound_ctrl:1
	v_add_f32_dpp v119, v127, v132 row_shl:15 row_mask:0xf bank_mask:0xf bound_ctrl:1
	v_add_f32_dpp v127, v127, v127 row_shr:1 row_mask:0xf bank_mask:0xf bound_ctrl:1
	v_add_f32_dpp v132, v120, v120 row_shr:1 row_mask:0xf bank_mask:0xf bound_ctrl:1
	v_add_f32_dpp v120, v128, v132 row_shl:15 row_mask:0xf bank_mask:0xf bound_ctrl:1
	v_add_f32_dpp v128, v128, v128 row_shr:1 row_mask:0xf bank_mask:0xf bound_ctrl:1
	v_add_f32_dpp v132, v121, v121 row_shr:1 row_mask:0xf bank_mask:0xf bound_ctrl:1
	v_add_f32_dpp v121, v129, v132 row_shl:15 row_mask:0xf bank_mask:0xf bound_ctrl:1
	v_add_f32_dpp v129, v129, v129 row_shr:1 row_mask:0xf bank_mask:0xf bound_ctrl:1
	v_add_f32_dpp v132, v122, v122 row_shr:1 row_mask:0xf bank_mask:0xf bound_ctrl:1
	v_add_f32_dpp v122, v130, v132 row_shl:15 row_mask:0xf bank_mask:0xf bound_ctrl:1
	v_add_f32_dpp v130, v130, v130 row_shr:1 row_mask:0xf bank_mask:0xf bound_ctrl:1
	v_add_f32_dpp v132, v123, v123 row_shr:1 row_mask:0xf bank_mask:0xf bound_ctrl:1
	v_add_f32_dpp v123, v131, v132 row_shl:15 row_mask:0xf bank_mask:0xf bound_ctrl:1
	v_add_f32_dpp v131, v131, v131 row_shr:1 row_mask:0xf bank_mask:0xf bound_ctrl:1
	v_add_f32_dpp v132, v116, v116 row_shr:2 row_mask:0xf bank_mask:0xf bound_ctrl:1
	v_add_f32_dpp v116, v124, v132 row_shl:14 row_mask:0xf bank_mask:0xf bound_ctrl:1
	v_add_f32_dpp v124, v124, v124 row_shr:2 row_mask:0xf bank_mask:0xf bound_ctrl:1
	v_add_f32_dpp v132, v117, v117 row_shr:2 row_mask:0xf bank_mask:0xf bound_ctrl:1
	v_add_f32_dpp v117, v125, v132 row_shl:14 row_mask:0xf bank_mask:0xf bound_ctrl:1
	v_add_f32_dpp v125, v125, v125 row_shr:2 row_mask:0xf bank_mask:0xf bound_ctrl:1
	v_add_f32_dpp v132, v118, v118 row_shr:2 row_mask:0xf bank_mask:0xf bound_ctrl:1
	v_add_f32_dpp v118, v126, v132 row_shl:14 row_mask:0xf bank_mask:0xf bound_ctrl:1
	v_add_f32_dpp v126, v126, v126 row_shr:2 row_mask:0xf bank_mask:0xf bound_ctrl:1
	v_add_f32_dpp v132, v119, v119 row_shr:2 row_mask:0xf bank_mask:0xf bound_ctrl:1
	v_add_f32_dpp v119, v127, v132 row_shl:14 row_mask:0xf bank_mask:0xf bound_ctrl:1
	v_add_f32_dpp v127, v127, v127 row_shr:2 row_mask:0xf bank_mask:0xf bound_ctrl:1
	v_add_f32_dpp v132, v120, v120 row_shr:2 row_mask:0xf bank_mask:0xf bound_ctrl:1
	v_add_f32_dpp v120, v128, v132 row_shl:14 row_mask:0xf bank_mask:0xf bound_ctrl:1
	v_add_f32_dpp v128, v128, v128 row_shr:2 row_mask:0xf bank_mask:0xf bound_ctrl:1
	v_add_f32_dpp v132, v121, v121 row_shr:2 row_mask:0xf bank_mask:0xf bound_ctrl:1
	v_add_f32_dpp v121, v129, v132 row_shl:14 row_mask:0xf bank_mask:0xf bound_ctrl:1
	v_add_f32_dpp v129, v129, v129 row_shr:2 row_mask:0xf bank_mask:0xf bound_ctrl:1
	v_add_f32_dpp v132, v122, v122 row_shr:2 row_mask:0xf bank_mask:0xf bound_ctrl:1
	v_add_f32_dpp v122, v130, v132 row_shl:14 row_mask:0xf bank_mask:0xf bound_ctrl:1
	v_add_f32_dpp v130, v130, v130 row_shr:2 row_mask:0xf bank_mask:0xf bound_ctrl:1
	v_add_f32_dpp v132, v123, v123 row_shr:2 row_mask:0xf bank_mask:0xf bound_ctrl:1
	v_add_f32_dpp v123, v131, v132 row_shl:14 row_mask:0xf bank_mask:0xf bound_ctrl:1
	v_add_f32_dpp v131, v131, v131 row_shr:2 row_mask:0xf bank_mask:0xf bound_ctrl:1
	v_add_f32_dpp v132, v116, v116 row_shr:4 row_mask:0xf bank_mask:0xf bound_ctrl:1
	v_add_f32_dpp v116, v124, v132 row_shl:12 row_mask:0xf bank_mask:0xf bound_ctrl:1
	v_add_f32_dpp v124, v124, v124 row_shr:4 row_mask:0xf bank_mask:0xf bound_ctrl:1
	v_add_f32_dpp v132, v117, v117 row_shr:4 row_mask:0xf bank_mask:0xf bound_ctrl:1
	v_add_f32_dpp v117, v125, v132 row_shl:12 row_mask:0xf bank_mask:0xf bound_ctrl:1
	v_add_f32_dpp v125, v125, v125 row_shr:4 row_mask:0xf bank_mask:0xf bound_ctrl:1
	v_add_f32_dpp v132, v118, v118 row_shr:4 row_mask:0xf bank_mask:0xf bound_ctrl:1
; __device__ __forceinline__ v4u pack8(const float (&f)[8]) { v4u w; w.x = cvt_pk_bf16(f[0], f[1]); w.y = cvt_pk_bf16(f[2], f[3]); w.z = cvt_pk_bf16(f[4], f[5]); w.w = cvt_pk_bf16(f[6], f[7]); return w; }
; template <int W> __device__ __forceinline__ void pool_group(const bf16* zrow  , const bf16* pw  , bf16* orow  , int pos, bool prev_ok) {
;     ...
;         win_step<1>(c, p);
;         if (W >= 4) win_step<2>(c, p);
;         if (W >= 8) win_step<4>(c, p);
;         if (W >= 16) win_step<8>(c, p);
;         float pl[8];
; #pragma unroll
;         for (int j = 0; j < 8; ++j) pl[j] = c[j] * inv - own[j];
;         const v4u pwk = pack8(pl); const bf16x8 pf = __builtin_bit_cast(bf16x8, pwk);
; #pragma unroll
;         for (int dt = 0; dt < 8; ++dt) acc[dt] = __builtin_amdgcn_mfma_f32_16x16x32_bf16(__builtin_bit_cast(bf16x8, aw[kk & 1][dt]), pf, acc[dt], 0, 0, 0);
;     }
	v_add_f32_dpp v118, v126, v132 row_shl:12 row_mask:0xf bank_mask:0xf bound_ctrl:1
	v_add_f32_dpp v126, v126, v126 row_shr:4 row_mask:0xf bank_mask:0xf bound_ctrl:1
	v_add_f32_dpp v132, v119, v119 row_shr:4 row_mask:0xf bank_mask:0xf bound_ctrl:1
	v_add_f32_dpp v119, v127, v132 row_shl:12 row_mask:0xf bank_mask:0xf bound_ctrl:1
	v_add_f32_dpp v127, v127, v127 row_shr:4 row_mask:0xf bank_mask:0xf bound_ctrl:1
	v_add_f32_dpp v132, v120, v120 row_shr:4 row_mask:0xf bank_mask:0xf bound_ctrl:1
	v_add_f32_dpp v120, v128, v132 row_shl:12 row_mask:0xf bank_mask:0xf bound_ctrl:1
	v_add_f32_dpp v128, v128, v128 row_shr:4 row_mask:0xf bank_mask:0xf bound_ctrl:1
	v_add_f32_dpp v132, v121, v121 row_shr:4 row_mask:0xf bank_mask:0xf bound_ctrl:1
	v_add_f32_dpp v121, v129, v132 row_shl:12 row_mask:0xf bank_mask:0xf bound_ctrl:1
	v_add_f32_dpp v129, v129, v129 row_shr:4 row_mask:0xf bank_mask:0xf bound_ctrl:1
	v_add_f32_dpp v132, v122, v122 row_shr:4 row_mask:0xf bank_mask:0xf bound_ctrl:1
	v_add_f32_dpp v122, v130, v132 row_shl:12 row_mask:0xf bank_mask:0xf bound_ctrl:1
	v_add_f32_dpp v130, v130, v130 row_shr:4 row_mask:0xf bank_mask:0xf bound_ctrl:1
	v_add_f32_dpp v132, v123, v123 row_shr:4 row_mask:0xf bank_mask:0xf bound_ctrl:1
	v_add_f32_dpp v123, v131, v132 row_shl:12 row_mask:0xf bank_mask:0xf bound_ctrl:1
	v_add_f32_dpp v131, v131, v131 row_shr:4 row_mask:0xf bank_mask:0xf bound_ctrl:1
	v_add_f32_dpp v132, v116, v116 row_shr:8 row_mask:0xf bank_mask:0xf bound_ctrl:1
	v_add_f32_dpp v116, v124, v132 row_shl:8 row_mask:0xf bank_mask:0xf bound_ctrl:1
	v_add_f32_dpp v124, v124, v124 row_shr:8 row_mask:0xf bank_mask:0xf bound_ctrl:1
	v_add_f32_dpp v132, v117, v117 row_shr:8 row_mask:0xf bank_mask:0xf bound_ctrl:1
	v_add_f32_dpp v117, v125, v132 row_shl:8 row_mask:0xf bank_mask:0xf bound_ctrl:1
	v_add_f32_dpp v125, v125, v125 row_shr:8 row_mask:0xf bank_mask:0xf bound_ctrl:1
	v_add_f32_dpp v132, v118, v118 row_shr:8 row_mask:0xf bank_mask:0xf bound_ctrl:1
	v_add_f32_dpp v118, v126, v132 row_shl:8 row_mask:0xf bank_mask:0xf bound_ctrl:1
	v_add_f32_dpp v126, v126, v126 row_shr:8 row_mask:0xf bank_mask:0xf bound_ctrl:1
	v_add_f32_dpp v132, v119, v119 row_shr:8 row_mask:0xf bank_mask:0xf bound_ctrl:1
	v_add_f32_dpp v119, v127, v132 row_shl:8 row_mask:0xf bank_mask:0xf bound_ctrl:1
	v_add_f32_dpp v127, v127, v127 row_shr:8 row_mask:0xf bank_mask:0xf bound_ctrl:1
	v_add_f32_dpp v132, v120, v120 row_shr:8 row_mask:0xf bank_mask:0xf bound_ctrl:1
	v_add_f32_dpp v120, v128, v132 row_shl:8 row_mask:0xf bank_mask:0xf bound_ctrl:1
	v_add_f32_dpp v128, v128, v128 row_shr:8 row_mask:0xf bank_mask:0xf bound_ctrl:1
	v_add_f32_dpp v132, v121, v121 row_shr:8 row_mask:0xf bank_mask:0xf bound_ctrl:1
	v_add_f32_dpp v121, v129, v132 row_shl:8 row_mask:0xf bank_mask:0xf bound_ctrl:1
	v_add_f32_dpp v129, v129, v129 row_shr:8 row_mask:0xf bank_mask:0xf bound_ctrl:1
	v_add_f32_dpp v132, v122, v122 row_shr:8 row_mask:0xf bank_mask:0xf bound_ctrl:1
	v_add_f32_dpp v122, v130, v132 row_shl:8 row_mask:0xf bank_mask:0xf bound_ctrl:1
	v_add_f32_dpp v130, v130, v130 row_shr:8 row_mask:0xf bank_mask:0xf bound_ctrl:1
	v_add_f32_dpp v132, v123, v123 row_shr:8 row_mask:0xf bank_mask:0xf bound_ctrl:1
	v_add_f32_dpp v123, v131, v132 row_shl:8 row_mask:0xf bank_mask:0xf bound_ctrl:1
	v_add_f32_dpp v131, v131, v131 row_shr:8 row_mask:0xf bank_mask:0xf bound_ctrl:1
	v_fma_f32 v116, v116, v138, -v108
	v_fma_f32 v117, v117, v138, -v109
	v_fma_f32 v118, v118, v138, -v110
	v_fma_f32 v119, v119, v138, -v111
	v_fma_f32 v120, v120, v138, -v112
	v_fma_f32 v121, v121, v138, -v113
	v_fma_f32 v122, v122, v138, -v114
	v_fma_f32 v123, v123, v138, -v115
	v_cvt_pk_bf16_f32 v134, v116, v117
	v_cvt_pk_bf16_f32 v135, v118, v119
	v_cvt_pk_bf16_f32 v136, v120, v121
	v_cvt_pk_bf16_f32 v137, v122, v123
	s_waitcnt lgkmcnt(0)
	s_nop 0
	v_mfma_f32_16x16x32_bf16 v[76:79], v[44:47], v[134:137], 0
	v_mfma_f32_16x16x32_bf16 v[80:83], v[48:51], v[134:137], 0
	v_mfma_f32_16x16x32_bf16 v[84:87], v[52:55], v[134:137], 0
	v_mfma_f32_16x16x32_bf16 v[88:91], v[56:59], v[134:137], 0
	v_mfma_f32_16x16x32_bf16 v[92:95], v[60:63], v[134:137], 0
	v_mfma_f32_16x16x32_bf16 v[96:99], v[64:67], v[134:137], 0
	v_mfma_f32_16x16x32_bf16 v[100:103], v[68:71], v[134:137], 0
	v_mfma_f32_16x16x32_bf16 v[104:107], v[72:75], v[134:137], 0
	v_add_u32_e32 v147, 98304, v144
	ds_read_b128 v[44:47], v147
	ds_read_b128 v[48:51], v147 offset:4096
	ds_read_b128 v[52:55], v147 offset:8192
	ds_read_b128 v[56:59], v147 offset:12288
	ds_read_b128 v[60:63], v147 offset:16384
	ds_read_b128 v[64:67], v147 offset:20480
	ds_read_b128 v[68:71], v147 offset:24576
	ds_read_b128 v[72:75], v147 offset:28672
	s_waitcnt vmcnt(12)
; #define GAS __attribute__((address_space(1)))
; __device__ __forceinline__ void unpack8(const v4u w, float (&f)[8]) { f[0] = bf_lo(w.x); f[1] = bf_hi(w.x); f[2] = bf_lo(w.y); f[3] = bf_hi(w.y); f[4] = bf_lo(w.z); f[5] = bf_hi(w.z); f[6] = bf_lo(w.w); f[7] = bf_hi(w.w); }
; template <int W> __device__ __forceinline__ void pool_group(const bf16* zrow  , const bf16* pw  , bf16* orow  , int pos, bool prev_ok) {
;     ...
;             for (int dt = 0; dt < 8; ++dt) aw[(kk + 1) & 1][dt] = *(const GAS v4u*)(pw + (size_t)16 * dt * 128 + 32 * (kk + 1)); }
;         float own[8], c[8], p[8];
;         unpack8(cw[kk], own); unpack8(pv[kk], p);
; #pragma unroll
;         for (int j = 0; j < 8; ++j) c[j] = own[j];
;         win_step<1>(c, p);
;         if (W >= 4) win_step<2>(c, p);
;         if (W >= 8) win_step<4>(c, p);
;         if (W >= 16) win_step<8>(c, p);
	v_lshlrev_b32_e32 v108, 16, v20
	v_and_b32_e32 v109, 0xffff0000, v20
	v_lshlrev_b32_e32 v110, 16, v21
	v_and_b32_e32 v111, 0xffff0000, v21
	v_lshlrev_b32_e32 v112, 16, v22
	v_and_b32_e32 v113, 0xffff0000, v22
	v_lshlrev_b32_e32 v114, 16, v23
	v_and_b32_e32 v115, 0xffff0000, v23
	v_lshlrev_b32_e32 v124, 16, v24
	v_and_b32_e32 v125, 0xffff0000, v24
	v_lshlrev_b32_e32 v126, 16, v25
	v_and_b32_e32 v127, 0xffff0000, v25
	v_lshlrev_b32_e32 v128, 16, v26
	v_and_b32_e32 v129, 0xffff0000, v26
	v_lshlrev_b32_e32 v130, 16, v27
	v_and_b32_e32 v131, 0xffff0000, v27
	v_cndmask_b32_e64 v124, 0, v124, s[40:41]
	v_cndmask_b32_e64 v125, 0, v125, s[40:41]
	v_cndmask_b32_e64 v126, 0, v126, s[40:41]
	v_cndmask_b32_e64 v127, 0, v127, s[40:41]
	v_cndmask_b32_e64 v128, 0, v128, s[40:41]
	v_cndmask_b32_e64 v129, 0, v129, s[40:41]
	v_cndmask_b32_e64 v130, 0, v130, s[40:41]
	v_cndmask_b32_e64 v131, 0, v131, s[40:41]
	v_mov_b32_e32 v116, v108
	v_mov_b32_e32 v117, v109
	v_mov_b32_e32 v118, v110
	v_mov_b32_e32 v119, v111
	v_mov_b32_e32 v120, v112
	v_mov_b32_e32 v121, v113
	v_mov_b32_e32 v122, v114
	v_mov_b32_e32 v123, v115
	v_add_f32_dpp v132, v116, v116 row_shr:1 row_mask:0xf bank_mask:0xf bound_ctrl:1
	v_add_f32_dpp v116, v124, v132 row_shl:15 row_mask:0xf bank_mask:0xf bound_ctrl:1
	v_add_f32_dpp v124, v124, v124 row_shr:1 row_mask:0xf bank_mask:0xf bound_ctrl:1
	v_add_f32_dpp v132, v117, v117 row_shr:1 row_mask:0xf bank_mask:0xf bound_ctrl:1
	v_add_f32_dpp v117, v125, v132 row_shl:15 row_mask:0xf bank_mask:0xf bound_ctrl:1
	v_add_f32_dpp v125, v125, v125 row_shr:1 row_mask:0xf bank_mask:0xf bound_ctrl:1
	v_add_f32_dpp v132, v118, v118 row_shr:1 row_mask:0xf bank_mask:0xf bound_ctrl:1
	v_add_f32_dpp v118, v126, v132 row_shl:15 row_mask:0xf bank_mask:0xf bound_ctrl:1
	v_add_f32_dpp v126, v126, v126 row_shr:1 row_mask:0xf bank_mask:0xf bound_ctrl:1
	v_add_f32_dpp v132, v119, v119 row_shr:1 row_mask:0xf bank_mask:0xf bound_ctrl:1
	v_add_f32_dpp v119, v127, v132 row_shl:15 row_mask:0xf bank_mask:0xf bound_ctrl:1
	v_add_f32_dpp v127, v127, v127 row_shr:1 row_mask:0xf bank_mask:0xf bound_ctrl:1
	v_add_f32_dpp v132, v120, v120 row_shr:1 row_mask:0xf bank_mask:0xf bound_ctrl:1
	v_add_f32_dpp v120, v128, v132 row_shl:15 row_mask:0xf bank_mask:0xf bound_ctrl:1
	v_add_f32_dpp v128, v128, v128 row_shr:1 row_mask:0xf bank_mask:0xf bound_ctrl:1
	v_add_f32_dpp v132, v121, v121 row_shr:1 row_mask:0xf bank_mask:0xf bound_ctrl:1
	v_add_f32_dpp v121, v129, v132 row_shl:15 row_mask:0xf bank_mask:0xf bound_ctrl:1
	v_add_f32_dpp v129, v129, v129 row_shr:1 row_mask:0xf bank_mask:0xf bound_ctrl:1
	v_add_f32_dpp v132, v122, v122 row_shr:1 row_mask:0xf bank_mask:0xf bound_ctrl:1
	v_add_f32_dpp v122, v130, v132 row_shl:15 row_mask:0xf bank_mask:0xf bound_ctrl:1
	v_add_f32_dpp v130, v130, v130 row_shr:1 row_mask:0xf bank_mask:0xf bound_ctrl:1
	v_add_f32_dpp v132, v123, v123 row_shr:1 row_mask:0xf bank_mask:0xf bound_ctrl:1
	v_add_f32_dpp v123, v131, v132 row_shl:15 row_mask:0xf bank_mask:0xf bound_ctrl:1
	v_add_f32_dpp v131, v131, v131 row_shr:1 row_mask:0xf bank_mask:0xf bound_ctrl:1
	v_add_f32_dpp v132, v116, v116 row_shr:2 row_mask:0xf bank_mask:0xf bound_ctrl:1
	v_add_f32_dpp v116, v124, v132 row_shl:14 row_mask:0xf bank_mask:0xf bound_ctrl:1
	v_add_f32_dpp v124, v124, v124 row_shr:2 row_mask:0xf bank_mask:0xf bound_ctrl:1
	v_add_f32_dpp v132, v117, v117 row_shr:2 row_mask:0xf bank_mask:0xf bound_ctrl:1
	v_add_f32_dpp v117, v125, v132 row_shl:14 row_mask:0xf bank_mask:0xf bound_ctrl:1
	v_add_f32_dpp v125, v125, v125 row_shr:2 row_mask:0xf bank_mask:0xf bound_ctrl:1
	v_add_f32_dpp v132, v118, v118 row_shr:2 row_mask:0xf bank_mask:0xf bound_ctrl:1
	v_add_f32_dpp v118, v126, v132 row_shl:14 row_mask:0xf bank_mask:0xf bound_ctrl:1
	v_add_f32_dpp v126, v126, v126 row_shr:2 row_mask:0xf bank_mask:0xf bound_ctrl:1
	v_add_f32_dpp v132, v119, v119 row_shr:2 row_mask:0xf bank_mask:0xf bound_ctrl:1
	v_add_f32_dpp v119, v127, v132 row_shl:14 row_mask:0xf bank_mask:0xf bound_ctrl:1
	v_add_f32_dpp v127, v127, v127 row_shr:2 row_mask:0xf bank_mask:0xf bound_ctrl:1
	v_add_f32_dpp v132, v120, v120 row_shr:2 row_mask:0xf bank_mask:0xf bound_ctrl:1
	v_add_f32_dpp v120, v128, v132 row_shl:14 row_mask:0xf bank_mask:0xf bound_ctrl:1
	v_add_f32_dpp v128, v128, v128 row_shr:2 row_mask:0xf bank_mask:0xf bound_ctrl:1
	v_add_f32_dpp v132, v121, v121 row_shr:2 row_mask:0xf bank_mask:0xf bound_ctrl:1
	v_add_f32_dpp v121, v129, v132 row_shl:14 row_mask:0xf bank_mask:0xf bound_ctrl:1
	v_add_f32_dpp v129, v129, v129 row_shr:2 row_mask:0xf bank_mask:0xf bound_ctrl:1
	v_add_f32_dpp v132, v122, v122 row_shr:2 row_mask:0xf bank_mask:0xf bound_ctrl:1
	v_add_f32_dpp v122, v130, v132 row_shl:14 row_mask:0xf bank_mask:0xf bound_ctrl:1
	v_add_f32_dpp v130, v130, v130 row_shr:2 row_mask:0xf bank_mask:0xf bound_ctrl:1
	v_add_f32_dpp v132, v123, v123 row_shr:2 row_mask:0xf bank_mask:0xf bound_ctrl:1
	v_add_f32_dpp v123, v131, v132 row_shl:14 row_mask:0xf bank_mask:0xf bound_ctrl:1
	v_add_f32_dpp v131, v131, v131 row_shr:2 row_mask:0xf bank_mask:0xf bound_ctrl:1
	v_add_f32_dpp v132, v116, v116 row_shr:4 row_mask:0xf bank_mask:0xf bound_ctrl:1
	v_add_f32_dpp v116, v124, v132 row_shl:12 row_mask:0xf bank_mask:0xf bound_ctrl:1
	v_add_f32_dpp v124, v124, v124 row_shr:4 row_mask:0xf bank_mask:0xf bound_ctrl:1
	v_add_f32_dpp v132, v117, v117 row_shr:4 row_mask:0xf bank_mask:0xf bound_ctrl:1
	v_add_f32_dpp v117, v125, v132 row_shl:12 row_mask:0xf bank_mask:0xf bound_ctrl:1
	v_add_f32_dpp v125, v125, v125 row_shr:4 row_mask:0xf bank_mask:0xf bound_ctrl:1
	v_add_f32_dpp v132, v118, v118 row_shr:4 row_mask:0xf bank_mask:0xf bound_ctrl:1
; __device__ __forceinline__ v4u pack8(const float (&f)[8]) { v4u w; w.x = cvt_pk_bf16(f[0], f[1]); w.y = cvt_pk_bf16(f[2], f[3]); w.z = cvt_pk_bf16(f[4], f[5]); w.w = cvt_pk_bf16(f[6], f[7]); return w; }
; template <int W> __device__ __forceinline__ void pool_group(const bf16* zrow  , const bf16* pw  , bf16* orow  , int pos, bool prev_ok) {
;     ...
;         win_step<1>(c, p);
;         if (W >= 4) win_step<2>(c, p);
;         if (W >= 8) win_step<4>(c, p);
;         if (W >= 16) win_step<8>(c, p);
;         float pl[8];
; #pragma unroll
;         for (int j = 0; j < 8; ++j) pl[j] = c[j] * inv - own[j];
;         const v4u pwk = pack8(pl); const bf16x8 pf = __builtin_bit_cast(bf16x8, pwk);
; #pragma unroll
;         for (int dt = 0; dt < 8; ++dt) acc[dt] = __builtin_amdgcn_mfma_f32_16x16x32_bf16(__builtin_bit_cast(bf16x8, aw[kk & 1][dt]), pf, acc[dt], 0, 0, 0);
;     }
	v_add_f32_dpp v118, v126, v132 row_shl:12 row_mask:0xf bank_mask:0xf bound_ctrl:1
	v_add_f32_dpp v126, v126, v126 row_shr:4 row_mask:0xf bank_mask:0xf bound_ctrl:1
	v_add_f32_dpp v132, v119, v119 row_shr:4 row_mask:0xf bank_mask:0xf bound_ctrl:1
	v_add_f32_dpp v119, v127, v132 row_shl:12 row_mask:0xf bank_mask:0xf bound_ctrl:1
	v_add_f32_dpp v127, v127, v127 row_shr:4 row_mask:0xf bank_mask:0xf bound_ctrl:1
	v_add_f32_dpp v132, v120, v120 row_shr:4 row_mask:0xf bank_mask:0xf bound_ctrl:1
	v_add_f32_dpp v120, v128, v132 row_shl:12 row_mask:0xf bank_mask:0xf bound_ctrl:1
	v_add_f32_dpp v128, v128, v128 row_shr:4 row_mask:0xf bank_mask:0xf bound_ctrl:1
	v_add_f32_dpp v132, v121, v121 row_shr:4 row_mask:0xf bank_mask:0xf bound_ctrl:1
	v_add_f32_dpp v121, v129, v132 row_shl:12 row_mask:0xf bank_mask:0xf bound_ctrl:1
	v_add_f32_dpp v129, v129, v129 row_shr:4 row_mask:0xf bank_mask:0xf bound_ctrl:1
	v_add_f32_dpp v132, v122, v122 row_shr:4 row_mask:0xf bank_mask:0xf bound_ctrl:1
	v_add_f32_dpp v122, v130, v132 row_shl:12 row_mask:0xf bank_mask:0xf bound_ctrl:1
	v_add_f32_dpp v130, v130, v130 row_shr:4 row_mask:0xf bank_mask:0xf bound_ctrl:1
	v_add_f32_dpp v132, v123, v123 row_shr:4 row_mask:0xf bank_mask:0xf bound_ctrl:1
	v_add_f32_dpp v123, v131, v132 row_shl:12 row_mask:0xf bank_mask:0xf bound_ctrl:1
	v_add_f32_dpp v131, v131, v131 row_shr:4 row_mask:0xf bank_mask:0xf bound_ctrl:1
	v_add_f32_dpp v132, v116, v116 row_shr:8 row_mask:0xf bank_mask:0xf bound_ctrl:1
	v_add_f32_dpp v116, v124, v132 row_shl:8 row_mask:0xf bank_mask:0xf bound_ctrl:1
	v_add_f32_dpp v124, v124, v124 row_shr:8 row_mask:0xf bank_mask:0xf bound_ctrl:1
	v_add_f32_dpp v132, v117, v117 row_shr:8 row_mask:0xf bank_mask:0xf bound_ctrl:1
	v_add_f32_dpp v117, v125, v132 row_shl:8 row_mask:0xf bank_mask:0xf bound_ctrl:1
	v_add_f32_dpp v125, v125, v125 row_shr:8 row_mask:0xf bank_mask:0xf bound_ctrl:1
	v_add_f32_dpp v132, v118, v118 row_shr:8 row_mask:0xf bank_mask:0xf bound_ctrl:1
	v_add_f32_dpp v118, v126, v132 row_shl:8 row_mask:0xf bank_mask:0xf bound_ctrl:1
	v_add_f32_dpp v126, v126, v126 row_shr:8 row_mask:0xf bank_mask:0xf bound_ctrl:1
	v_add_f32_dpp v132, v119, v119 row_shr:8 row_mask:0xf bank_mask:0xf bound_ctrl:1
	v_add_f32_dpp v119, v127, v132 row_shl:8 row_mask:0xf bank_mask:0xf bound_ctrl:1
	v_add_f32_dpp v127, v127, v127 row_shr:8 row_mask:0xf bank_mask:0xf bound_ctrl:1
	v_add_f32_dpp v132, v120, v120 row_shr:8 row_mask:0xf bank_mask:0xf bound_ctrl:1
	v_add_f32_dpp v120, v128, v132 row_shl:8 row_mask:0xf bank_mask:0xf bound_ctrl:1
	v_add_f32_dpp v128, v128, v128 row_shr:8 row_mask:0xf bank_mask:0xf bound_ctrl:1
	v_add_f32_dpp v132, v121, v121 row_shr:8 row_mask:0xf bank_mask:0xf bound_ctrl:1
	v_add_f32_dpp v121, v129, v132 row_shl:8 row_mask:0xf bank_mask:0xf bound_ctrl:1
	v_add_f32_dpp v129, v129, v129 row_shr:8 row_mask:0xf bank_mask:0xf bound_ctrl:1
	v_add_f32_dpp v132, v122, v122 row_shr:8 row_mask:0xf bank_mask:0xf bound_ctrl:1
	v_add_f32_dpp v122, v130, v132 row_shl:8 row_mask:0xf bank_mask:0xf bound_ctrl:1
	v_add_f32_dpp v130, v130, v130 row_shr:8 row_mask:0xf bank_mask:0xf bound_ctrl:1
	v_add_f32_dpp v132, v123, v123 row_shr:8 row_mask:0xf bank_mask:0xf bound_ctrl:1
	v_add_f32_dpp v123, v131, v132 row_shl:8 row_mask:0xf bank_mask:0xf bound_ctrl:1
	v_add_f32_dpp v131, v131, v131 row_shr:8 row_mask:0xf bank_mask:0xf bound_ctrl:1
	v_fma_f32 v116, v116, v138, -v108
	v_fma_f32 v117, v117, v138, -v109
	v_fma_f32 v118, v118, v138, -v110
	v_fma_f32 v119, v119, v138, -v111
	v_fma_f32 v120, v120, v138, -v112
	v_fma_f32 v121, v121, v138, -v113
	v_fma_f32 v122, v122, v138, -v114
	v_fma_f32 v123, v123, v138, -v115
	v_cvt_pk_bf16_f32 v134, v116, v117
	v_cvt_pk_bf16_f32 v135, v118, v119
	v_cvt_pk_bf16_f32 v136, v120, v121
	v_cvt_pk_bf16_f32 v137, v122, v123
	s_waitcnt lgkmcnt(0)
	s_nop 0
	v_mfma_f32_16x16x32_bf16 v[76:79], v[44:47], v[134:137], v[76:79]
	v_mfma_f32_16x16x32_bf16 v[80:83], v[48:51], v[134:137], v[80:83]
	v_mfma_f32_16x16x32_bf16 v[84:87], v[52:55], v[134:137], v[84:87]
	v_mfma_f32_16x16x32_bf16 v[88:91], v[56:59], v[134:137], v[88:91]
	v_mfma_f32_16x16x32_bf16 v[92:95], v[60:63], v[134:137], v[92:95]
	v_mfma_f32_16x16x32_bf16 v[96:99], v[64:67], v[134:137], v[96:99]
	v_mfma_f32_16x16x32_bf16 v[100:103], v[68:71], v[134:137], v[100:103]
	v_mfma_f32_16x16x32_bf16 v[104:107], v[72:75], v[134:137], v[104:107]
	v_add_u32_e32 v147, 98304, v145
	ds_read_b128 v[44:47], v147
	ds_read_b128 v[48:51], v147 offset:4096
	ds_read_b128 v[52:55], v147 offset:8192
	ds_read_b128 v[56:59], v147 offset:12288
	ds_read_b128 v[60:63], v147 offset:16384
	ds_read_b128 v[64:67], v147 offset:20480
	ds_read_b128 v[68:71], v147 offset:24576
	ds_read_b128 v[72:75], v147 offset:28672
	s_waitcnt vmcnt(10)
; #define GAS __attribute__((address_space(1)))
; __device__ __forceinline__ void unpack8(const v4u w, float (&f)[8]) { f[0] = bf_lo(w.x); f[1] = bf_hi(w.x); f[2] = bf_lo(w.y); f[3] = bf_hi(w.y); f[4] = bf_lo(w.z); f[5] = bf_hi(w.z); f[6] = bf_lo(w.w); f[7] = bf_hi(w.w); }
; template <int W> __device__ __forceinline__ void pool_group(const bf16* zrow  , const bf16* pw  , bf16* orow  , int pos, bool prev_ok) {
;     ...
;             for (int dt = 0; dt < 8; ++dt) aw[(kk + 1) & 1][dt] = *(const GAS v4u*)(pw + (size_t)16 * dt * 128 + 32 * (kk + 1)); }
;         float own[8], c[8], p[8];
;         unpack8(cw[kk], own); unpack8(pv[kk], p);
; #pragma unroll
;         for (int j = 0; j < 8; ++j) c[j] = own[j];
;         win_step<1>(c, p);
;         if (W >= 4) win_step<2>(c, p);
;         if (W >= 8) win_step<4>(c, p);
;         if (W >= 16) win_step<8>(c, p);
	v_lshlrev_b32_e32 v108, 16, v28
	v_and_b32_e32 v109, 0xffff0000, v28
	v_lshlrev_b32_e32 v110, 16, v29
	v_and_b32_e32 v111, 0xffff0000, v29
	v_lshlrev_b32_e32 v112, 16, v30
	v_and_b32_e32 v113, 0xffff0000, v30
	v_lshlrev_b32_e32 v114, 16, v31
	v_and_b32_e32 v115, 0xffff0000, v31
	v_lshlrev_b32_e32 v124, 16, v32
	v_and_b32_e32 v125, 0xffff0000, v32
	v_lshlrev_b32_e32 v126, 16, v33
	v_and_b32_e32 v127, 0xffff0000, v33
	v_lshlrev_b32_e32 v128, 16, v34
	v_and_b32_e32 v129, 0xffff0000, v34
	v_lshlrev_b32_e32 v130, 16, v35
	v_and_b32_e32 v131, 0xffff0000, v35
	v_cndmask_b32_e64 v124, 0, v124, s[40:41]
	v_cndmask_b32_e64 v125, 0, v125, s[40:41]
	v_cndmask_b32_e64 v126, 0, v126, s[40:41]
	v_cndmask_b32_e64 v127, 0, v127, s[40:41]
	v_cndmask_b32_e64 v128, 0, v128, s[40:41]
	v_cndmask_b32_e64 v129, 0, v129, s[40:41]
	v_cndmask_b32_e64 v130, 0, v130, s[40:41]
	v_cndmask_b32_e64 v131, 0, v131, s[40:41]
	v_mov_b32_e32 v116, v108
	v_mov_b32_e32 v117, v109
	v_mov_b32_e32 v118, v110
	v_mov_b32_e32 v119, v111
	v_mov_b32_e32 v120, v112
	v_mov_b32_e32 v121, v113
	v_mov_b32_e32 v122, v114
	v_mov_b32_e32 v123, v115
	v_add_f32_dpp v132, v116, v116 row_shr:1 row_mask:0xf bank_mask:0xf bound_ctrl:1
	v_add_f32_dpp v116, v124, v132 row_shl:15 row_mask:0xf bank_mask:0xf bound_ctrl:1
	v_add_f32_dpp v124, v124, v124 row_shr:1 row_mask:0xf bank_mask:0xf bound_ctrl:1
	v_add_f32_dpp v132, v117, v117 row_shr:1 row_mask:0xf bank_mask:0xf bound_ctrl:1
	v_add_f32_dpp v117, v125, v132 row_shl:15 row_mask:0xf bank_mask:0xf bound_ctrl:1
	v_add_f32_dpp v125, v125, v125 row_shr:1 row_mask:0xf bank_mask:0xf bound_ctrl:1
	v_add_f32_dpp v132, v118, v118 row_shr:1 row_mask:0xf bank_mask:0xf bound_ctrl:1
	v_add_f32_dpp v118, v126, v132 row_shl:15 row_mask:0xf bank_mask:0xf bound_ctrl:1
	v_add_f32_dpp v126, v126, v126 row_shr:1 row_mask:0xf bank_mask:0xf bound_ctrl:1
	v_add_f32_dpp v132, v119, v119 row_shr:1 row_mask:0xf bank_mask:0xf bound_ctrl:1
	v_add_f32_dpp v119, v127, v132 row_shl:15 row_mask:0xf bank_mask:0xf bound_ctrl:1
	v_add_f32_dpp v127, v127, v127 row_shr:1 row_mask:0xf bank_mask:0xf bound_ctrl:1
	v_add_f32_dpp v132, v120, v120 row_shr:1 row_mask:0xf bank_mask:0xf bound_ctrl:1
	v_add_f32_dpp v120, v128, v132 row_shl:15 row_mask:0xf bank_mask:0xf bound_ctrl:1
	v_add_f32_dpp v128, v128, v128 row_shr:1 row_mask:0xf bank_mask:0xf bound_ctrl:1
	v_add_f32_dpp v132, v121, v121 row_shr:1 row_mask:0xf bank_mask:0xf bound_ctrl:1
	v_add_f32_dpp v121, v129, v132 row_shl:15 row_mask:0xf bank_mask:0xf bound_ctrl:1
	v_add_f32_dpp v129, v129, v129 row_shr:1 row_mask:0xf bank_mask:0xf bound_ctrl:1
	v_add_f32_dpp v132, v122, v122 row_shr:1 row_mask:0xf bank_mask:0xf bound_ctrl:1
	v_add_f32_dpp v122, v130, v132 row_shl:15 row_mask:0xf bank_mask:0xf bound_ctrl:1
	v_add_f32_dpp v130, v130, v130 row_shr:1 row_mask:0xf bank_mask:0xf bound_ctrl:1
	v_add_f32_dpp v132, v123, v123 row_shr:1 row_mask:0xf bank_mask:0xf bound_ctrl:1
	v_add_f32_dpp v123, v131, v132 row_shl:15 row_mask:0xf bank_mask:0xf bound_ctrl:1
	v_add_f32_dpp v131, v131, v131 row_shr:1 row_mask:0xf bank_mask:0xf bound_ctrl:1
	v_add_f32_dpp v132, v116, v116 row_shr:2 row_mask:0xf bank_mask:0xf bound_ctrl:1
	v_add_f32_dpp v116, v124, v132 row_shl:14 row_mask:0xf bank_mask:0xf bound_ctrl:1
	v_add_f32_dpp v124, v124, v124 row_shr:2 row_mask:0xf bank_mask:0xf bound_ctrl:1
	v_add_f32_dpp v132, v117, v117 row_shr:2 row_mask:0xf bank_mask:0xf bound_ctrl:1
	v_add_f32_dpp v117, v125, v132 row_shl:14 row_mask:0xf bank_mask:0xf bound_ctrl:1
	v_add_f32_dpp v125, v125, v125 row_shr:2 row_mask:0xf bank_mask:0xf bound_ctrl:1
	v_add_f32_dpp v132, v118, v118 row_shr:2 row_mask:0xf bank_mask:0xf bound_ctrl:1
	v_add_f32_dpp v118, v126, v132 row_shl:14 row_mask:0xf bank_mask:0xf bound_ctrl:1
	v_add_f32_dpp v126, v126, v126 row_shr:2 row_mask:0xf bank_mask:0xf bound_ctrl:1
	v_add_f32_dpp v132, v119, v119 row_shr:2 row_mask:0xf bank_mask:0xf bound_ctrl:1
	v_add_f32_dpp v119, v127, v132 row_shl:14 row_mask:0xf bank_mask:0xf bound_ctrl:1
	v_add_f32_dpp v127, v127, v127 row_shr:2 row_mask:0xf bank_mask:0xf bound_ctrl:1
	v_add_f32_dpp v132, v120, v120 row_shr:2 row_mask:0xf bank_mask:0xf bound_ctrl:1
	v_add_f32_dpp v120, v128, v132 row_shl:14 row_mask:0xf bank_mask:0xf bound_ctrl:1
	v_add_f32_dpp v128, v128, v128 row_shr:2 row_mask:0xf bank_mask:0xf bound_ctrl:1
	v_add_f32_dpp v132, v121, v121 row_shr:2 row_mask:0xf bank_mask:0xf bound_ctrl:1
	v_add_f32_dpp v121, v129, v132 row_shl:14 row_mask:0xf bank_mask:0xf bound_ctrl:1
	v_add_f32_dpp v129, v129, v129 row_shr:2 row_mask:0xf bank_mask:0xf bound_ctrl:1
	v_add_f32_dpp v132, v122, v122 row_shr:2 row_mask:0xf bank_mask:0xf bound_ctrl:1
	v_add_f32_dpp v122, v130, v132 row_shl:14 row_mask:0xf bank_mask:0xf bound_ctrl:1
	v_add_f32_dpp v130, v130, v130 row_shr:2 row_mask:0xf bank_mask:0xf bound_ctrl:1
	v_add_f32_dpp v132, v123, v123 row_shr:2 row_mask:0xf bank_mask:0xf bound_ctrl:1
	v_add_f32_dpp v123, v131, v132 row_shl:14 row_mask:0xf bank_mask:0xf bound_ctrl:1
	v_add_f32_dpp v131, v131, v131 row_shr:2 row_mask:0xf bank_mask:0xf bound_ctrl:1
	v_add_f32_dpp v132, v116, v116 row_shr:4 row_mask:0xf bank_mask:0xf bound_ctrl:1
	v_add_f32_dpp v116, v124, v132 row_shl:12 row_mask:0xf bank_mask:0xf bound_ctrl:1
	v_add_f32_dpp v124, v124, v124 row_shr:4 row_mask:0xf bank_mask:0xf bound_ctrl:1
	v_add_f32_dpp v132, v117, v117 row_shr:4 row_mask:0xf bank_mask:0xf bound_ctrl:1
	v_add_f32_dpp v117, v125, v132 row_shl:12 row_mask:0xf bank_mask:0xf bound_ctrl:1
	v_add_f32_dpp v125, v125, v125 row_shr:4 row_mask:0xf bank_mask:0xf bound_ctrl:1
	v_add_f32_dpp v132, v118, v118 row_shr:4 row_mask:0xf bank_mask:0xf bound_ctrl:1
; __device__ __forceinline__ v4u pack8(const float (&f)[8]) { v4u w; w.x = cvt_pk_bf16(f[0], f[1]); w.y = cvt_pk_bf16(f[2], f[3]); w.z = cvt_pk_bf16(f[4], f[5]); w.w = cvt_pk_bf16(f[6], f[7]); return w; }
; template <int W> __device__ __forceinline__ void pool_group(const bf16* zrow  , const bf16* pw  , bf16* orow  , int pos, bool prev_ok) {
;     ...
;         win_step<1>(c, p);
;         if (W >= 4) win_step<2>(c, p);
;         if (W >= 8) win_step<4>(c, p);
;         if (W >= 16) win_step<8>(c, p);
;         float pl[8];
; #pragma unroll
;         for (int j = 0; j < 8; ++j) pl[j] = c[j] * inv - own[j];
;         const v4u pwk = pack8(pl); const bf16x8 pf = __builtin_bit_cast(bf16x8, pwk);
; #pragma unroll
;         for (int dt = 0; dt < 8; ++dt) acc[dt] = __builtin_amdgcn_mfma_f32_16x16x32_bf16(__builtin_bit_cast(bf16x8, aw[kk & 1][dt]), pf, acc[dt], 0, 0, 0);
;     }
	v_add_f32_dpp v118, v126, v132 row_shl:12 row_mask:0xf bank_mask:0xf bound_ctrl:1
	v_add_f32_dpp v126, v126, v126 row_shr:4 row_mask:0xf bank_mask:0xf bound_ctrl:1
	v_add_f32_dpp v132, v119, v119 row_shr:4 row_mask:0xf bank_mask:0xf bound_ctrl:1
	v_add_f32_dpp v119, v127, v132 row_shl:12 row_mask:0xf bank_mask:0xf bound_ctrl:1
	v_add_f32_dpp v127, v127, v127 row_shr:4 row_mask:0xf bank_mask:0xf bound_ctrl:1
	v_add_f32_dpp v132, v120, v120 row_shr:4 row_mask:0xf bank_mask:0xf bound_ctrl:1
	v_add_f32_dpp v120, v128, v132 row_shl:12 row_mask:0xf bank_mask:0xf bound_ctrl:1
	v_add_f32_dpp v128, v128, v128 row_shr:4 row_mask:0xf bank_mask:0xf bound_ctrl:1
	v_add_f32_dpp v132, v121, v121 row_shr:4 row_mask:0xf bank_mask:0xf bound_ctrl:1
	v_add_f32_dpp v121, v129, v132 row_shl:12 row_mask:0xf bank_mask:0xf bound_ctrl:1
	v_add_f32_dpp v129, v129, v129 row_shr:4 row_mask:0xf bank_mask:0xf bound_ctrl:1
	v_add_f32_dpp v132, v122, v122 row_shr:4 row_mask:0xf bank_mask:0xf bound_ctrl:1
	v_add_f32_dpp v122, v130, v132 row_shl:12 row_mask:0xf bank_mask:0xf bound_ctrl:1
	v_add_f32_dpp v130, v130, v130 row_shr:4 row_mask:0xf bank_mask:0xf bound_ctrl:1
	v_add_f32_dpp v132, v123, v123 row_shr:4 row_mask:0xf bank_mask:0xf bound_ctrl:1
	v_add_f32_dpp v123, v131, v132 row_shl:12 row_mask:0xf bank_mask:0xf bound_ctrl:1
	v_add_f32_dpp v131, v131, v131 row_shr:4 row_mask:0xf bank_mask:0xf bound_ctrl:1
	v_add_f32_dpp v132, v116, v116 row_shr:8 row_mask:0xf bank_mask:0xf bound_ctrl:1
	v_add_f32_dpp v116, v124, v132 row_shl:8 row_mask:0xf bank_mask:0xf bound_ctrl:1
	v_add_f32_dpp v124, v124, v124 row_shr:8 row_mask:0xf bank_mask:0xf bound_ctrl:1
	v_add_f32_dpp v132, v117, v117 row_shr:8 row_mask:0xf bank_mask:0xf bound_ctrl:1
	v_add_f32_dpp v117, v125, v132 row_shl:8 row_mask:0xf bank_mask:0xf bound_ctrl:1
	v_add_f32_dpp v125, v125, v125 row_shr:8 row_mask:0xf bank_mask:0xf bound_ctrl:1
	v_add_f32_dpp v132, v118, v118 row_shr:8 row_mask:0xf bank_mask:0xf bound_ctrl:1
	v_add_f32_dpp v118, v126, v132 row_shl:8 row_mask:0xf bank_mask:0xf bound_ctrl:1
	v_add_f32_dpp v126, v126, v126 row_shr:8 row_mask:0xf bank_mask:0xf bound_ctrl:1
	v_add_f32_dpp v132, v119, v119 row_shr:8 row_mask:0xf bank_mask:0xf bound_ctrl:1
	v_add_f32_dpp v119, v127, v132 row_shl:8 row_mask:0xf bank_mask:0xf bound_ctrl:1
	v_add_f32_dpp v127, v127, v127 row_shr:8 row_mask:0xf bank_mask:0xf bound_ctrl:1
	v_add_f32_dpp v132, v120, v120 row_shr:8 row_mask:0xf bank_mask:0xf bound_ctrl:1
	v_add_f32_dpp v120, v128, v132 row_shl:8 row_mask:0xf bank_mask:0xf bound_ctrl:1
	v_add_f32_dpp v128, v128, v128 row_shr:8 row_mask:0xf bank_mask:0xf bound_ctrl:1
	v_add_f32_dpp v132, v121, v121 row_shr:8 row_mask:0xf bank_mask:0xf bound_ctrl:1
	v_add_f32_dpp v121, v129, v132 row_shl:8 row_mask:0xf bank_mask:0xf bound_ctrl:1
	v_add_f32_dpp v129, v129, v129 row_shr:8 row_mask:0xf bank_mask:0xf bound_ctrl:1
	v_add_f32_dpp v132, v122, v122 row_shr:8 row_mask:0xf bank_mask:0xf bound_ctrl:1
	v_add_f32_dpp v122, v130, v132 row_shl:8 row_mask:0xf bank_mask:0xf bound_ctrl:1
	v_add_f32_dpp v130, v130, v130 row_shr:8 row_mask:0xf bank_mask:0xf bound_ctrl:1
	v_add_f32_dpp v132, v123, v123 row_shr:8 row_mask:0xf bank_mask:0xf bound_ctrl:1
	v_add_f32_dpp v123, v131, v132 row_shl:8 row_mask:0xf bank_mask:0xf bound_ctrl:1
	v_add_f32_dpp v131, v131, v131 row_shr:8 row_mask:0xf bank_mask:0xf bound_ctrl:1
	v_fma_f32 v116, v116, v138, -v108
	v_fma_f32 v117, v117, v138, -v109
	v_fma_f32 v118, v118, v138, -v110
	v_fma_f32 v119, v119, v138, -v111
	v_fma_f32 v120, v120, v138, -v112
	v_fma_f32 v121, v121, v138, -v113
	v_fma_f32 v122, v122, v138, -v114
	v_fma_f32 v123, v123, v138, -v115
	v_cvt_pk_bf16_f32 v134, v116, v117
	v_cvt_pk_bf16_f32 v135, v118, v119
	v_cvt_pk_bf16_f32 v136, v120, v121
	v_cvt_pk_bf16_f32 v137, v122, v123
	s_waitcnt lgkmcnt(0)
	s_nop 0
	v_mfma_f32_16x16x32_bf16 v[76:79], v[44:47], v[134:137], v[76:79]
	v_mfma_f32_16x16x32_bf16 v[80:83], v[48:51], v[134:137], v[80:83]
	v_mfma_f32_16x16x32_bf16 v[84:87], v[52:55], v[134:137], v[84:87]
	v_mfma_f32_16x16x32_bf16 v[88:91], v[56:59], v[134:137], v[88:91]
	v_mfma_f32_16x16x32_bf16 v[92:95], v[60:63], v[134:137], v[92:95]
	v_mfma_f32_16x16x32_bf16 v[96:99], v[64:67], v[134:137], v[96:99]
	v_mfma_f32_16x16x32_bf16 v[100:103], v[68:71], v[134:137], v[100:103]
	v_mfma_f32_16x16x32_bf16 v[104:107], v[72:75], v[134:137], v[104:107]
	v_add_u32_e32 v147, 98304, v146
	ds_read_b128 v[44:47], v147
	ds_read_b128 v[48:51], v147 offset:4096
	ds_read_b128 v[52:55], v147 offset:8192
	ds_read_b128 v[56:59], v147 offset:12288
	ds_read_b128 v[60:63], v147 offset:16384
	ds_read_b128 v[64:67], v147 offset:20480
	ds_read_b128 v[68:71], v147 offset:24576
	ds_read_b128 v[72:75], v147 offset:28672
	s_waitcnt vmcnt(8)
; #define GAS __attribute__((address_space(1)))
; __device__ __forceinline__ void unpack8(const v4u w, float (&f)[8]) { f[0] = bf_lo(w.x); f[1] = bf_hi(w.x); f[2] = bf_lo(w.y); f[3] = bf_hi(w.y); f[4] = bf_lo(w.z); f[5] = bf_hi(w.z); f[6] = bf_lo(w.w); f[7] = bf_hi(w.w); }
; template <int W> __device__ __forceinline__ void pool_group(const bf16* zrow  , const bf16* pw  , bf16* orow  , int pos, bool prev_ok) {
;     ...
;             for (int dt = 0; dt < 8; ++dt) aw[(kk + 1) & 1][dt] = *(const GAS v4u*)(pw + (size_t)16 * dt * 128 + 32 * (kk + 1)); }
;         float own[8], c[8], p[8];
;         unpack8(cw[kk], own); unpack8(pv[kk], p);
; #pragma unroll
;         for (int j = 0; j < 8; ++j) c[j] = own[j];
;         win_step<1>(c, p);
;         if (W >= 4) win_step<2>(c, p);
;         if (W >= 8) win_step<4>(c, p);
;         if (W >= 16) win_step<8>(c, p);
	v_lshlrev_b32_e32 v108, 16, v36
	v_and_b32_e32 v109, 0xffff0000, v36
	v_lshlrev_b32_e32 v110, 16, v37
	v_and_b32_e32 v111, 0xffff0000, v37
	v_lshlrev_b32_e32 v112, 16, v38
	v_and_b32_e32 v113, 0xffff0000, v38
	v_lshlrev_b32_e32 v114, 16, v39
	v_and_b32_e32 v115, 0xffff0000, v39
	v_lshlrev_b32_e32 v124, 16, v40
	v_and_b32_e32 v125, 0xffff0000, v40
	v_lshlrev_b32_e32 v126, 16, v41
	v_and_b32_e32 v127, 0xffff0000, v41
	v_lshlrev_b32_e32 v128, 16, v42
	v_and_b32_e32 v129, 0xffff0000, v42
	v_lshlrev_b32_e32 v130, 16, v43
	v_and_b32_e32 v131, 0xffff0000, v43
	v_cndmask_b32_e64 v124, 0, v124, s[40:41]
	v_cndmask_b32_e64 v125, 0, v125, s[40:41]
	v_cndmask_b32_e64 v126, 0, v126, s[40:41]
	v_cndmask_b32_e64 v127, 0, v127, s[40:41]
	v_cndmask_b32_e64 v128, 0, v128, s[40:41]
	v_cndmask_b32_e64 v129, 0, v129, s[40:41]
	v_cndmask_b32_e64 v130, 0, v130, s[40:41]
	v_cndmask_b32_e64 v131, 0, v131, s[40:41]
	v_mov_b32_e32 v116, v108
	v_mov_b32_e32 v117, v109
	v_mov_b32_e32 v118, v110
	v_mov_b32_e32 v119, v111
	v_mov_b32_e32 v120, v112
	v_mov_b32_e32 v121, v113
	v_mov_b32_e32 v122, v114
	v_mov_b32_e32 v123, v115
	v_add_f32_dpp v132, v116, v116 row_shr:1 row_mask:0xf bank_mask:0xf bound_ctrl:1
	v_add_f32_dpp v116, v124, v132 row_shl:15 row_mask:0xf bank_mask:0xf bound_ctrl:1
	v_add_f32_dpp v124, v124, v124 row_shr:1 row_mask:0xf bank_mask:0xf bound_ctrl:1
	v_add_f32_dpp v132, v117, v117 row_shr:1 row_mask:0xf bank_mask:0xf bound_ctrl:1
	v_add_f32_dpp v117, v125, v132 row_shl:15 row_mask:0xf bank_mask:0xf bound_ctrl:1
	v_add_f32_dpp v125, v125, v125 row_shr:1 row_mask:0xf bank_mask:0xf bound_ctrl:1
	v_add_f32_dpp v132, v118, v118 row_shr:1 row_mask:0xf bank_mask:0xf bound_ctrl:1
	v_add_f32_dpp v118, v126, v132 row_shl:15 row_mask:0xf bank_mask:0xf bound_ctrl:1
	v_add_f32_dpp v126, v126, v126 row_shr:1 row_mask:0xf bank_mask:0xf bound_ctrl:1
	v_add_f32_dpp v132, v119, v119 row_shr:1 row_mask:0xf bank_mask:0xf bound_ctrl:1
	v_add_f32_dpp v119, v127, v132 row_shl:15 row_mask:0xf bank_mask:0xf bound_ctrl:1
	v_add_f32_dpp v127, v127, v127 row_shr:1 row_mask:0xf bank_mask:0xf bound_ctrl:1
	v_add_f32_dpp v132, v120, v120 row_shr:1 row_mask:0xf bank_mask:0xf bound_ctrl:1
	v_add_f32_dpp v120, v128, v132 row_shl:15 row_mask:0xf bank_mask:0xf bound_ctrl:1
	v_add_f32_dpp v128, v128, v128 row_shr:1 row_mask:0xf bank_mask:0xf bound_ctrl:1
	v_add_f32_dpp v132, v121, v121 row_shr:1 row_mask:0xf bank_mask:0xf bound_ctrl:1
	v_add_f32_dpp v121, v129, v132 row_shl:15 row_mask:0xf bank_mask:0xf bound_ctrl:1
	v_add_f32_dpp v129, v129, v129 row_shr:1 row_mask:0xf bank_mask:0xf bound_ctrl:1
	v_add_f32_dpp v132, v122, v122 row_shr:1 row_mask:0xf bank_mask:0xf bound_ctrl:1
	v_add_f32_dpp v122, v130, v132 row_shl:15 row_mask:0xf bank_mask:0xf bound_ctrl:1
	v_add_f32_dpp v130, v130, v130 row_shr:1 row_mask:0xf bank_mask:0xf bound_ctrl:1
	v_add_f32_dpp v132, v123, v123 row_shr:1 row_mask:0xf bank_mask:0xf bound_ctrl:1
	v_add_f32_dpp v123, v131, v132 row_shl:15 row_mask:0xf bank_mask:0xf bound_ctrl:1
	v_add_f32_dpp v131, v131, v131 row_shr:1 row_mask:0xf bank_mask:0xf bound_ctrl:1
	v_add_f32_dpp v132, v116, v116 row_shr:2 row_mask:0xf bank_mask:0xf bound_ctrl:1
	v_add_f32_dpp v116, v124, v132 row_shl:14 row_mask:0xf bank_mask:0xf bound_ctrl:1
	v_add_f32_dpp v124, v124, v124 row_shr:2 row_mask:0xf bank_mask:0xf bound_ctrl:1
	v_add_f32_dpp v132, v117, v117 row_shr:2 row_mask:0xf bank_mask:0xf bound_ctrl:1
	v_add_f32_dpp v117, v125, v132 row_shl:14 row_mask:0xf bank_mask:0xf bound_ctrl:1
	v_add_f32_dpp v125, v125, v125 row_shr:2 row_mask:0xf bank_mask:0xf bound_ctrl:1
	v_add_f32_dpp v132, v118, v118 row_shr:2 row_mask:0xf bank_mask:0xf bound_ctrl:1
	v_add_f32_dpp v118, v126, v132 row_shl:14 row_mask:0xf bank_mask:0xf bound_ctrl:1
	v_add_f32_dpp v126, v126, v126 row_shr:2 row_mask:0xf bank_mask:0xf bound_ctrl:1
	v_add_f32_dpp v132, v119, v119 row_shr:2 row_mask:0xf bank_mask:0xf bound_ctrl:1
	v_add_f32_dpp v119, v127, v132 row_shl:14 row_mask:0xf bank_mask:0xf bound_ctrl:1
	v_add_f32_dpp v127, v127, v127 row_shr:2 row_mask:0xf bank_mask:0xf bound_ctrl:1
	v_add_f32_dpp v132, v120, v120 row_shr:2 row_mask:0xf bank_mask:0xf bound_ctrl:1
	v_add_f32_dpp v120, v128, v132 row_shl:14 row_mask:0xf bank_mask:0xf bound_ctrl:1
	v_add_f32_dpp v128, v128, v128 row_shr:2 row_mask:0xf bank_mask:0xf bound_ctrl:1
	v_add_f32_dpp v132, v121, v121 row_shr:2 row_mask:0xf bank_mask:0xf bound_ctrl:1
	v_add_f32_dpp v121, v129, v132 row_shl:14 row_mask:0xf bank_mask:0xf bound_ctrl:1
	v_add_f32_dpp v129, v129, v129 row_shr:2 row_mask:0xf bank_mask:0xf bound_ctrl:1
	v_add_f32_dpp v132, v122, v122 row_shr:2 row_mask:0xf bank_mask:0xf bound_ctrl:1
	v_add_f32_dpp v122, v130, v132 row_shl:14 row_mask:0xf bank_mask:0xf bound_ctrl:1
	v_add_f32_dpp v130, v130, v130 row_shr:2 row_mask:0xf bank_mask:0xf bound_ctrl:1
	v_add_f32_dpp v132, v123, v123 row_shr:2 row_mask:0xf bank_mask:0xf bound_ctrl:1
	v_add_f32_dpp v123, v131, v132 row_shl:14 row_mask:0xf bank_mask:0xf bound_ctrl:1
	v_add_f32_dpp v131, v131, v131 row_shr:2 row_mask:0xf bank_mask:0xf bound_ctrl:1
	v_add_f32_dpp v132, v116, v116 row_shr:4 row_mask:0xf bank_mask:0xf bound_ctrl:1
	v_add_f32_dpp v116, v124, v132 row_shl:12 row_mask:0xf bank_mask:0xf bound_ctrl:1
	v_add_f32_dpp v124, v124, v124 row_shr:4 row_mask:0xf bank_mask:0xf bound_ctrl:1
	v_add_f32_dpp v132, v117, v117 row_shr:4 row_mask:0xf bank_mask:0xf bound_ctrl:1
	v_add_f32_dpp v117, v125, v132 row_shl:12 row_mask:0xf bank_mask:0xf bound_ctrl:1
	v_add_f32_dpp v125, v125, v125 row_shr:4 row_mask:0xf bank_mask:0xf bound_ctrl:1
	v_add_f32_dpp v132, v118, v118 row_shr:4 row_mask:0xf bank_mask:0xf bound_ctrl:1
; __device__ __forceinline__ unsigned cvt_pk_bf16(float lo, float hi) { return __builtin_bit_cast(unsigned, __builtin_convertvector((f32x2_t){lo, hi}, bf16x2_t)); }
; #define GAS __attribute__((address_space(1)))
; __device__ __forceinline__ v4u pack8(const float (&f)[8]) { v4u w; w.x = cvt_pk_bf16(f[0], f[1]); w.y = cvt_pk_bf16(f[2], f[3]); w.z = cvt_pk_bf16(f[4], f[5]); w.w = cvt_pk_bf16(f[6], f[7]); return w; }
; template <int W> __device__ __forceinline__ void pool_group(const bf16* zrow  , const bf16* pw  , bf16* orow  , int pos, bool prev_ok) {
;     ...
;         win_step<1>(c, p);
;         if (W >= 4) win_step<2>(c, p);
;         if (W >= 8) win_step<4>(c, p);
;         if (W >= 16) win_step<8>(c, p);
;         float pl[8];
; #pragma unroll
;         for (int j = 0; j < 8; ++j) pl[j] = c[j] * inv - own[j];
;         const v4u pwk = pack8(pl); const bf16x8 pf = __builtin_bit_cast(bf16x8, pwk);
; #pragma unroll
;         for (int dt = 0; dt < 8; ++dt) acc[dt] = __builtin_amdgcn_mfma_f32_16x16x32_bf16(__builtin_bit_cast(bf16x8, aw[kk & 1][dt]), pf, acc[dt], 0, 0, 0);
;     }
; #pragma unroll
;     for (int dt = 0; dt < 8; ++dt) { v2u w; w.x = cvt_pk_bf16(acc[dt][0], acc[dt][1]); w.y = cvt_pk_bf16(acc[dt][2], acc[dt][3]); *(GAS v2u*)(orow + 16 * dt) = w; }
	v_add_f32_dpp v118, v126, v132 row_shl:12 row_mask:0xf bank_mask:0xf bound_ctrl:1
	v_add_f32_dpp v126, v126, v126 row_shr:4 row_mask:0xf bank_mask:0xf bound_ctrl:1
	v_add_f32_dpp v132, v119, v119 row_shr:4 row_mask:0xf bank_mask:0xf bound_ctrl:1
	v_add_f32_dpp v119, v127, v132 row_shl:12 row_mask:0xf bank_mask:0xf bound_ctrl:1
	v_add_f32_dpp v127, v127, v127 row_shr:4 row_mask:0xf bank_mask:0xf bound_ctrl:1
	v_add_f32_dpp v132, v120, v120 row_shr:4 row_mask:0xf bank_mask:0xf bound_ctrl:1
	v_add_f32_dpp v120, v128, v132 row_shl:12 row_mask:0xf bank_mask:0xf bound_ctrl:1
	v_add_f32_dpp v128, v128, v128 row_shr:4 row_mask:0xf bank_mask:0xf bound_ctrl:1
	v_add_f32_dpp v132, v121, v121 row_shr:4 row_mask:0xf bank_mask:0xf bound_ctrl:1
	v_add_f32_dpp v121, v129, v132 row_shl:12 row_mask:0xf bank_mask:0xf bound_ctrl:1
	v_add_f32_dpp v129, v129, v129 row_shr:4 row_mask:0xf bank_mask:0xf bound_ctrl:1
	v_add_f32_dpp v132, v122, v122 row_shr:4 row_mask:0xf bank_mask:0xf bound_ctrl:1
	v_add_f32_dpp v122, v130, v132 row_shl:12 row_mask:0xf bank_mask:0xf bound_ctrl:1
	v_add_f32_dpp v130, v130, v130 row_shr:4 row_mask:0xf bank_mask:0xf bound_ctrl:1
	v_add_f32_dpp v132, v123, v123 row_shr:4 row_mask:0xf bank_mask:0xf bound_ctrl:1
	v_add_f32_dpp v123, v131, v132 row_shl:12 row_mask:0xf bank_mask:0xf bound_ctrl:1
	v_add_f32_dpp v131, v131, v131 row_shr:4 row_mask:0xf bank_mask:0xf bound_ctrl:1
	v_add_f32_dpp v132, v116, v116 row_shr:8 row_mask:0xf bank_mask:0xf bound_ctrl:1
	v_add_f32_dpp v116, v124, v132 row_shl:8 row_mask:0xf bank_mask:0xf bound_ctrl:1
	v_add_f32_dpp v124, v124, v124 row_shr:8 row_mask:0xf bank_mask:0xf bound_ctrl:1
	v_add_f32_dpp v132, v117, v117 row_shr:8 row_mask:0xf bank_mask:0xf bound_ctrl:1
	v_add_f32_dpp v117, v125, v132 row_shl:8 row_mask:0xf bank_mask:0xf bound_ctrl:1
	v_add_f32_dpp v125, v125, v125 row_shr:8 row_mask:0xf bank_mask:0xf bound_ctrl:1
	v_add_f32_dpp v132, v118, v118 row_shr:8 row_mask:0xf bank_mask:0xf bound_ctrl:1
	v_add_f32_dpp v118, v126, v132 row_shl:8 row_mask:0xf bank_mask:0xf bound_ctrl:1
	v_add_f32_dpp v126, v126, v126 row_shr:8 row_mask:0xf bank_mask:0xf bound_ctrl:1
	v_add_f32_dpp v132, v119, v119 row_shr:8 row_mask:0xf bank_mask:0xf bound_ctrl:1
	v_add_f32_dpp v119, v127, v132 row_shl:8 row_mask:0xf bank_mask:0xf bound_ctrl:1
	v_add_f32_dpp v127, v127, v127 row_shr:8 row_mask:0xf bank_mask:0xf bound_ctrl:1
	v_add_f32_dpp v132, v120, v120 row_shr:8 row_mask:0xf bank_mask:0xf bound_ctrl:1
	v_add_f32_dpp v120, v128, v132 row_shl:8 row_mask:0xf bank_mask:0xf bound_ctrl:1
	v_add_f32_dpp v128, v128, v128 row_shr:8 row_mask:0xf bank_mask:0xf bound_ctrl:1
	v_add_f32_dpp v132, v121, v121 row_shr:8 row_mask:0xf bank_mask:0xf bound_ctrl:1
	v_add_f32_dpp v121, v129, v132 row_shl:8 row_mask:0xf bank_mask:0xf bound_ctrl:1
	v_add_f32_dpp v129, v129, v129 row_shr:8 row_mask:0xf bank_mask:0xf bound_ctrl:1
	v_add_f32_dpp v132, v122, v122 row_shr:8 row_mask:0xf bank_mask:0xf bound_ctrl:1
	v_add_f32_dpp v122, v130, v132 row_shl:8 row_mask:0xf bank_mask:0xf bound_ctrl:1
	v_add_f32_dpp v130, v130, v130 row_shr:8 row_mask:0xf bank_mask:0xf bound_ctrl:1
	v_add_f32_dpp v132, v123, v123 row_shr:8 row_mask:0xf bank_mask:0xf bound_ctrl:1
	v_add_f32_dpp v123, v131, v132 row_shl:8 row_mask:0xf bank_mask:0xf bound_ctrl:1
	v_add_f32_dpp v131, v131, v131 row_shr:8 row_mask:0xf bank_mask:0xf bound_ctrl:1
	v_fma_f32 v116, v116, v138, -v108
	v_fma_f32 v117, v117, v138, -v109
	v_fma_f32 v118, v118, v138, -v110
	v_fma_f32 v119, v119, v138, -v111
	v_fma_f32 v120, v120, v138, -v112
	v_fma_f32 v121, v121, v138, -v113
	v_fma_f32 v122, v122, v138, -v114
	v_fma_f32 v123, v123, v138, -v115
	v_cvt_pk_bf16_f32 v134, v116, v117
	v_cvt_pk_bf16_f32 v135, v118, v119
	v_cvt_pk_bf16_f32 v136, v120, v121
	v_cvt_pk_bf16_f32 v137, v122, v123
	s_waitcnt lgkmcnt(0)
	s_nop 0
	v_mfma_f32_16x16x32_bf16 v[76:79], v[44:47], v[134:137], v[76:79]
	v_mfma_f32_16x16x32_bf16 v[80:83], v[48:51], v[134:137], v[80:83]
	v_mfma_f32_16x16x32_bf16 v[84:87], v[52:55], v[134:137], v[84:87]
	v_mfma_f32_16x16x32_bf16 v[88:91], v[56:59], v[134:137], v[88:91]
	v_mfma_f32_16x16x32_bf16 v[92:95], v[60:63], v[134:137], v[92:95]
	v_mfma_f32_16x16x32_bf16 v[96:99], v[64:67], v[134:137], v[96:99]
	v_mfma_f32_16x16x32_bf16 v[100:103], v[68:71], v[134:137], v[100:103]
	v_mfma_f32_16x16x32_bf16 v[104:107], v[72:75], v[134:137], v[104:107]
	s_nop 7
	s_nop 1
	v_cvt_pk_bf16_f32 v132, v76, v77
	v_cvt_pk_bf16_f32 v133, v78, v79
	global_store_dwordx2 v142, v[132:133], s[46:47] offset:768
	s_nop 0
	v_cvt_pk_bf16_f32 v132, v80, v81
	v_cvt_pk_bf16_f32 v133, v82, v83
	global_store_dwordx2 v142, v[132:133], s[46:47] offset:800
	s_nop 0
	v_cvt_pk_bf16_f32 v132, v84, v85
	v_cvt_pk_bf16_f32 v133, v86, v87
	global_store_dwordx2 v142, v[132:133], s[46:47] offset:832
	s_nop 0
	v_cvt_pk_bf16_f32 v132, v88, v89
	v_cvt_pk_bf16_f32 v133, v90, v91
	global_store_dwordx2 v142, v[132:133], s[46:47] offset:864
	s_nop 0
	v_cvt_pk_bf16_f32 v132, v92, v93
	v_cvt_pk_bf16_f32 v133, v94, v95
	global_store_dwordx2 v142, v[132:133], s[46:47] offset:896
	s_nop 0
	v_cvt_pk_bf16_f32 v132, v96, v97
	v_cvt_pk_bf16_f32 v133, v98, v99
	global_store_dwordx2 v142, v[132:133], s[46:47] offset:928
	s_nop 0
	v_cvt_pk_bf16_f32 v132, v100, v101
	v_cvt_pk_bf16_f32 v133, v102, v103
	global_store_dwordx2 v142, v[132:133], s[46:47] offset:960
	s_nop 0
	v_cvt_pk_bf16_f32 v132, v104, v105
	v_cvt_pk_bf16_f32 v133, v106, v107
	global_store_dwordx2 v142, v[132:133], s[46:47] offset:992
	s_nop 0
	s_waitcnt lgkmcnt(0)
	s_barrier
; #define GAS __attribute__((address_space(1)))
; __device__ __forceinline__ int lane_opaque() { int l; asm volatile("v_mbcnt_lo_u32_b32 %0, -1, 0\n\tv_mbcnt_hi_u32_b32 %0, -1, %0" : "=v"(l)); return l; }
; __device__ __forceinline__ void mixer_sgu(const Frame& F, const Args& A, int l, int chunk, const bf16* Z, bf16* MIX) {
;     const int lane = lane_opaque(), tid = F.wave * 64 + lane;
;     const int row0 = chunk * 128;
;     const bf16* wsb = (const bf16*)(F.ws + WS_WSB) + (size_t)l * 4 * 128 * 128;
;     const int t1 = tid >> 2, q = tid & 3, i = lane & 15, g4 = lane >> 4, w = F.wave, t2 = 16 * w + i, kkmax = w >> 1;
;     const bf16* zv = Z + (size_t)(row0 + t1) * ZC + 512 + 32 * q;
;     const bf16* zu = Z + (size_t)(row0 + t2) * ZC + 4 * g4;
;     bf16* mo = MIX + (size_t)(row0 + t2) * D + 4 * g4;
;     v4u vr[4];
; #pragma unroll
;     for (int j = 0; j < 4; ++j) vr[j] = *(const GAS v4u*)(zv + 8 * j);
	s_mov_b32 s52, 0
	s_mov_b64 s[44:45], 0
	s_mov_b64 s[46:47], 0
	v_mbcnt_lo_u32_b32 v1, -1, 0
	v_mbcnt_hi_u32_b32 v1, -1, v1
	v_mov_b32_e32 v7, v0
	v_add_u32_e32 v2, s77, v1
	v_ashrrev_i32_e32 v76, 2, v2
	v_lshlrev_b32_e32 v6, 5, v1
	v_add_u32_e32 v4, s21, v76
	v_mov_b64_e32 v[2:3], s[82:83]
	v_and_b32_e32 v26, 0x60, v6
	v_mad_i64_i32 v[4:5], s[36:37], v4, s33, v[2:3]
	v_lshlrev_b32_e32 v6, 1, v26
	v_lshl_add_u64 v[16:17], v[4:5], 0, v[6:7]
	global_load_dwordx4 v[4:7], v[16:17], off offset:1072
	global_load_dwordx4 v[8:11], v[16:17], off offset:1056
	global_load_dwordx4 v[12:15], v[16:17], off offset:1040
	s_nop 0
	global_load_dwordx4 v[16:19], v[16:17], off offset:1024
	v_and_b32_e32 v27, 15, v1
	v_ashrrev_i32_e32 v28, 4, v1
	v_or_b32_e32 v60, s56, v27
	v_add_u32_e32 v20, s21, v60
	v_lshlrev_b32_e32 v22, 2, v28
	v_ashrrev_i32_e32 v21, 31, v20
	v_ashrrev_i32_e32 v23, 31, v22
	v_lshlrev_b64 v[24:25], 12, v[20:21]
	v_mad_i64_i32 v[2:3], s[36:37], v20, s33, v[2:3]
	v_lshlrev_b64 v[20:21], 1, v[22:23]
	v_lshl_add_u64 v[62:63], v[2:3], 0, v[20:21]
	v_lshlrev_b32_e32 v2, 3, v28
	v_ashrrev_i32_e32 v3, 31, v2
	v_lshl_add_u64 v[66:67], v[2:3], 1, s[8:9]
	v_mad_i64_i32 v[2:3], s[36:37], v76, s33, 0
	v_lshl_add_u64 v[24:25], s[2:3], 0, v[24:25]
	v_and_b32_e32 v77, -16, v1
	v_mad_u64_u32 v[2:3], s[36:37], s5, v225, v[2:3]
	v_and_b32_e32 v1, 3, v1
	v_lshl_add_u64 v[64:65], v[24:25], 0, v[20:21]
	v_lshl_or_b32 v2, v1, 6, v2
	v_add_u32_e32 v20, s56, v27
	v_lshl_add_u64 v[68:69], s[96:97], 0, v[2:3]
	v_lshlrev_b32_e32 v2, 7, v1
	v_mov_b32_e32 v3, v0
	v_ashrrev_i32_e32 v21, 31, v20
	v_ashrrev_i32_e32 v61, 31, v60
	v_mul_u32_u24_e32 v78, 0x110, v26
	v_mul_u32_u24_e32 v79, 0x110, v27
	v_lshl_add_u64 v[70:71], s[60:61], 0, v[2:3]
	v_lshl_add_u64 v[72:73], v[20:21], 2, s[66:67]
	v_lshl_add_u64 v[74:75], s[62:63], 0, v[2:3]
	s_branch .LBB0_338
